# v35 minus the pre-barrier s_waitcnt lgkmcnt(8) in GEMM phases 1 and 5 (post-barrier lgkmcnt(0) covers the reads)
# baseline (speedup 1.0000x reference)
.LBB0_38:
	ds_read_b128 v[150:153], v147
	ds_read_b128 v[156:159], v147 offset:1024
	ds_read_b128 v[160:163], v147 offset:2048
	ds_read_b128 v[164:167], v147 offset:3072
	s_add_u32 s83, s88, 0xfffc0080
	s_addc_u32 s90, s89, -1
	s_cmp_eq_u32 s82, 12
	s_cselect_b32 s93, s13, s90
	s_cselect_b32 s92, s78, s83
	s_cselect_b32 s91, s11, s81
	s_cselect_b32 s90, s79, s80
	v_lshl_add_u64 v[200:201], s[88:89], 0, v[136:137]
	s_add_i32 m0, s9, 0xc000
	ds_read_b128 v[168:171], v148
	ds_read_b128 v[172:175], v148 offset:1024
	ds_read_b128 v[176:179], v148 offset:2048
	ds_read_b128 v[180:183], v148 offset:3072
	ds_read_b128 v[184:187], v148 offset:4096
	ds_read_b128 v[188:191], v148 offset:5120
	ds_read_b128 v[192:195], v148 offset:6144
	ds_read_b128 v[196:199], v148 offset:7168
	global_load_lds_dwordx4 v[200:201], off
	s_add_i32 m0, s9, 0xe000
	v_lshl_add_u64 v[200:201], s[88:89], 0, v[138:139]
	global_load_lds_dwordx4 v[200:201], off
	s_barrier
	s_waitcnt lgkmcnt(0)
	v_mfma_f32_16x16x32_bf16 v[124:127], v[150:153], v[168:171], v[124:127]
	v_mfma_f32_16x16x32_bf16 v[120:123], v[160:163], v[168:171], v[120:123]
	v_mfma_f32_16x16x32_bf16 v[116:119], v[150:153], v[176:179], v[116:119]
	v_mfma_f32_16x16x32_bf16 v[112:115], v[160:163], v[176:179], v[112:115]
	v_mfma_f32_16x16x32_bf16 v[100:103], v[150:153], v[184:187], v[100:103]
	v_mfma_f32_16x16x32_bf16 v[96:99], v[160:163], v[184:187], v[96:99]
	v_mfma_f32_16x16x32_bf16 v[84:87], v[150:153], v[192:195], v[84:87]
	v_mfma_f32_16x16x32_bf16 v[80:83], v[160:163], v[192:195], v[80:83]
	v_mfma_f32_16x16x32_bf16 v[124:127], v[156:159], v[172:175], v[124:127]
	v_mfma_f32_16x16x32_bf16 v[120:123], v[164:167], v[172:175], v[120:123]
	v_mfma_f32_16x16x32_bf16 v[116:119], v[156:159], v[180:183], v[116:119]
	v_mfma_f32_16x16x32_bf16 v[112:115], v[164:167], v[180:183], v[112:115]
	v_mfma_f32_16x16x32_bf16 v[100:103], v[156:159], v[188:191], v[100:103]
	v_mfma_f32_16x16x32_bf16 v[96:99], v[164:167], v[188:191], v[96:99]
	v_mfma_f32_16x16x32_bf16 v[84:87], v[156:159], v[196:199], v[84:87]
	v_mfma_f32_16x16x32_bf16 v[80:83], v[164:167], v[196:199], v[80:83]
	s_barrier
	s_add_i32 s83, s74, s1
	v_lshl_add_u64 v[216:217], s[90:91], 0, v[132:133]
	s_mov_b32 m0, s83
	ds_read_b128 v[200:203], v149
	ds_read_b128 v[204:207], v149 offset:1024
	ds_read_b128 v[208:211], v149 offset:2048
	ds_read_b128 v[212:215], v149 offset:3072
	global_load_lds_dwordx4 v[216:217], off
	s_add_i32 m0, s83, 0x2000
	v_lshl_add_u64 v[218:219], s[90:91], 0, v[128:129]
	global_load_lds_dwordx4 v[218:219], off
	s_barrier
	s_waitcnt lgkmcnt(0)
	v_mfma_f32_16x16x32_bf16 v[108:111], v[200:203], v[168:171], v[108:111]
	v_mfma_f32_16x16x32_bf16 v[104:107], v[208:211], v[168:171], v[104:107]
	v_mfma_f32_16x16x32_bf16 v[92:95], v[200:203], v[176:179], v[92:95]
	v_mfma_f32_16x16x32_bf16 v[88:91], v[208:211], v[176:179], v[88:91]
	v_mfma_f32_16x16x32_bf16 v[76:79], v[200:203], v[184:187], v[76:79]
	v_mfma_f32_16x16x32_bf16 v[72:75], v[208:211], v[184:187], v[72:75]
	v_mfma_f32_16x16x32_bf16 v[68:71], v[200:203], v[192:195], v[68:71]
	v_mfma_f32_16x16x32_bf16 v[64:67], v[208:211], v[192:195], v[64:67]
	v_mfma_f32_16x16x32_bf16 v[108:111], v[204:207], v[172:175], v[108:111]
	v_mfma_f32_16x16x32_bf16 v[104:107], v[212:215], v[172:175], v[104:107]
	v_mfma_f32_16x16x32_bf16 v[92:95], v[204:207], v[180:183], v[92:95]
	v_mfma_f32_16x16x32_bf16 v[88:91], v[212:215], v[180:183], v[88:91]
	v_mfma_f32_16x16x32_bf16 v[76:79], v[204:207], v[188:191], v[76:79]
	v_mfma_f32_16x16x32_bf16 v[72:75], v[212:215], v[188:191], v[72:75]
	v_mfma_f32_16x16x32_bf16 v[68:71], v[204:207], v[196:199], v[68:71]
	v_mfma_f32_16x16x32_bf16 v[64:67], v[212:215], v[196:199], v[64:67]
	s_mov_b32 m0, s9
	v_lshl_add_u64 v[220:221], s[92:93], 0, v[134:135]
	s_barrier
	ds_read_b128 v[168:171], v148 offset:16384
	ds_read_b128 v[172:175], v148 offset:17408
	ds_read_b128 v[176:179], v148 offset:18432
	ds_read_b128 v[180:183], v148 offset:19456
	ds_read_b128 v[184:187], v148 offset:20480
	ds_read_b128 v[188:191], v148 offset:21504
	ds_read_b128 v[192:195], v148 offset:22528
	ds_read_b128 v[196:199], v148 offset:23552
	global_load_lds_dwordx4 v[220:221], off
	s_mov_b32 m0, s35
	v_lshl_add_u64 v[222:223], s[92:93], 0, v[130:131]
	global_load_lds_dwordx4 v[222:223], off
	s_barrier
	s_waitcnt lgkmcnt(0)
	v_mfma_f32_16x16x32_bf16 v[60:63], v[150:153], v[168:171], v[60:63]
	v_mfma_f32_16x16x32_bf16 v[56:59], v[160:163], v[168:171], v[56:59]
	v_mfma_f32_16x16x32_bf16 v[52:55], v[150:153], v[176:179], v[52:55]
	v_mfma_f32_16x16x32_bf16 v[48:51], v[160:163], v[176:179], v[48:51]
	v_mfma_f32_16x16x32_bf16 v[36:39], v[150:153], v[184:187], v[36:39]
	v_mfma_f32_16x16x32_bf16 v[32:35], v[160:163], v[184:187], v[32:35]
	v_mfma_f32_16x16x32_bf16 v[20:23], v[150:153], v[192:195], v[20:23]
	v_mfma_f32_16x16x32_bf16 v[16:19], v[160:163], v[192:195], v[16:19]
	v_mfma_f32_16x16x32_bf16 v[60:63], v[156:159], v[172:175], v[60:63]
	v_mfma_f32_16x16x32_bf16 v[56:59], v[164:167], v[172:175], v[56:59]
	v_mfma_f32_16x16x32_bf16 v[52:55], v[156:159], v[180:183], v[52:55]
	v_mfma_f32_16x16x32_bf16 v[48:51], v[164:167], v[180:183], v[48:51]
	v_mfma_f32_16x16x32_bf16 v[36:39], v[156:159], v[188:191], v[36:39]
	v_mfma_f32_16x16x32_bf16 v[32:35], v[164:167], v[188:191], v[32:35]
	v_mfma_f32_16x16x32_bf16 v[20:23], v[156:159], v[196:199], v[20:23]
	v_mfma_f32_16x16x32_bf16 v[16:19], v[164:167], v[196:199], v[16:19]
	s_barrier
	s_add_u32 s94, s90, 0x40000
	s_addc_u32 s95, s91, 0
	s_add_i32 s83, s75, s1
	s_mov_b32 m0, s83
	v_lshl_add_u64 v[150:151], s[94:95], 0, v[132:133]
	global_load_lds_dwordx4 v[150:151], off
	s_add_i32 m0, s83, 0x2000
	v_lshl_add_u64 v[150:151], s[94:95], 0, v[128:129]
	global_load_lds_dwordx4 v[150:151], off
	s_waitcnt vmcnt(6)
	s_barrier
	v_mfma_f32_16x16x32_bf16 v[44:47], v[200:203], v[168:171], v[44:47]
	v_mfma_f32_16x16x32_bf16 v[40:43], v[208:211], v[168:171], v[40:43]
	v_mfma_f32_16x16x32_bf16 v[28:31], v[200:203], v[176:179], v[28:31]
	v_mfma_f32_16x16x32_bf16 v[24:27], v[208:211], v[176:179], v[24:27]
	v_mfma_f32_16x16x32_bf16 v[12:15], v[200:203], v[184:187], v[12:15]
	v_mfma_f32_16x16x32_bf16 v[8:11], v[208:211], v[184:187], v[8:11]
	v_mfma_f32_16x16x32_bf16 v[4:7], v[200:203], v[192:195], v[4:7]
	v_mfma_f32_16x16x32_bf16 v[0:3], v[208:211], v[192:195], v[0:3]
	v_mfma_f32_16x16x32_bf16 v[44:47], v[204:207], v[172:175], v[44:47]
	v_mfma_f32_16x16x32_bf16 v[40:43], v[212:215], v[172:175], v[40:43]
	v_mfma_f32_16x16x32_bf16 v[28:31], v[204:207], v[180:183], v[28:31]
	v_mfma_f32_16x16x32_bf16 v[24:27], v[212:215], v[180:183], v[24:27]
	v_mfma_f32_16x16x32_bf16 v[12:15], v[204:207], v[188:191], v[12:15]
	v_mfma_f32_16x16x32_bf16 v[8:11], v[212:215], v[188:191], v[8:11]
	v_mfma_f32_16x16x32_bf16 v[4:7], v[204:207], v[196:199], v[4:7]
	v_mfma_f32_16x16x32_bf16 v[0:3], v[212:215], v[196:199], v[0:3]
	s_add_i32 s83, 0, 0x18000
	v_add_u32_e32 v164, s83, v145
	s_barrier
	ds_read_b128 v[150:153], v164
	ds_read_b128 v[156:159], v164 offset:1024
	ds_read_b128 v[160:163], v164 offset:2048
	ds_read_b128 v[164:167], v164 offset:3072
	s_add_u32 s92, s92, 0x40000
	s_addc_u32 s93, s93, 0
	s_mov_b32 m0, s68
	v_lshl_add_u64 v[200:201], s[92:93], 0, v[134:135]
	ds_read_b128 v[168:171], v148 offset:32768
	ds_read_b128 v[172:175], v148 offset:33792
	ds_read_b128 v[176:179], v148 offset:34816
	ds_read_b128 v[180:183], v148 offset:35840
	ds_read_b128 v[184:187], v148 offset:36864
	ds_read_b128 v[188:191], v148 offset:37888
	ds_read_b128 v[192:195], v148 offset:38912
	ds_read_b128 v[196:199], v148 offset:39936
	global_load_lds_dwordx4 v[200:201], off
	s_mov_b32 m0, s69
	v_lshl_add_u64 v[200:201], s[92:93], 0, v[130:131]
	global_load_lds_dwordx4 v[200:201], off
	s_barrier
	s_waitcnt lgkmcnt(0)
	v_mfma_f32_16x16x32_bf16 v[124:127], v[150:153], v[168:171], v[124:127]
	v_mfma_f32_16x16x32_bf16 v[120:123], v[160:163], v[168:171], v[120:123]
	v_mfma_f32_16x16x32_bf16 v[116:119], v[150:153], v[176:179], v[116:119]
	v_mfma_f32_16x16x32_bf16 v[112:115], v[160:163], v[176:179], v[112:115]
	v_mfma_f32_16x16x32_bf16 v[100:103], v[150:153], v[184:187], v[100:103]
	v_mfma_f32_16x16x32_bf16 v[96:99], v[160:163], v[184:187], v[96:99]
	v_mfma_f32_16x16x32_bf16 v[84:87], v[150:153], v[192:195], v[84:87]
	v_mfma_f32_16x16x32_bf16 v[80:83], v[160:163], v[192:195], v[80:83]
	v_mfma_f32_16x16x32_bf16 v[124:127], v[156:159], v[172:175], v[124:127]
	v_mfma_f32_16x16x32_bf16 v[120:123], v[164:167], v[172:175], v[120:123]
	v_mfma_f32_16x16x32_bf16 v[116:119], v[156:159], v[180:183], v[116:119]
	v_mfma_f32_16x16x32_bf16 v[112:115], v[164:167], v[180:183], v[112:115]
	v_mfma_f32_16x16x32_bf16 v[100:103], v[156:159], v[188:191], v[100:103]
	v_mfma_f32_16x16x32_bf16 v[96:99], v[164:167], v[188:191], v[96:99]
	v_mfma_f32_16x16x32_bf16 v[84:87], v[156:159], v[196:199], v[84:87]
	v_mfma_f32_16x16x32_bf16 v[80:83], v[164:167], v[196:199], v[80:83]
	s_barrier
	s_add_i32 s92, 0, 0x1c000
	s_add_i32 s83, s83, s1
	v_add_u32_e32 v212, s92, v145
	v_lshl_add_u64 v[216:217], v[216:217], 0, s[6:7]
	s_mov_b32 m0, s83
	ds_read_b128 v[200:203], v212
	ds_read_b128 v[204:207], v212 offset:1024
	ds_read_b128 v[208:211], v212 offset:2048
	ds_read_b128 v[212:215], v212 offset:3072
	global_load_lds_dwordx4 v[216:217], off
	s_add_i32 m0, s83, 0x2000
	v_lshl_add_u64 v[216:217], v[218:219], 0, s[6:7]
	global_load_lds_dwordx4 v[216:217], off
	s_barrier
	s_waitcnt lgkmcnt(0)
	v_mfma_f32_16x16x32_bf16 v[108:111], v[200:203], v[168:171], v[108:111]
	v_mfma_f32_16x16x32_bf16 v[104:107], v[208:211], v[168:171], v[104:107]
	v_mfma_f32_16x16x32_bf16 v[92:95], v[200:203], v[176:179], v[92:95]
	v_mfma_f32_16x16x32_bf16 v[88:91], v[208:211], v[176:179], v[88:91]
	v_mfma_f32_16x16x32_bf16 v[76:79], v[200:203], v[184:187], v[76:79]
	v_mfma_f32_16x16x32_bf16 v[72:75], v[208:211], v[184:187], v[72:75]
	v_mfma_f32_16x16x32_bf16 v[68:71], v[200:203], v[192:195], v[68:71]
	v_mfma_f32_16x16x32_bf16 v[64:67], v[208:211], v[192:195], v[64:67]
	v_mfma_f32_16x16x32_bf16 v[108:111], v[204:207], v[172:175], v[108:111]
	v_mfma_f32_16x16x32_bf16 v[104:107], v[212:215], v[172:175], v[104:107]
	v_mfma_f32_16x16x32_bf16 v[92:95], v[204:207], v[180:183], v[92:95]
	v_mfma_f32_16x16x32_bf16 v[88:91], v[212:215], v[180:183], v[88:91]
	v_mfma_f32_16x16x32_bf16 v[76:79], v[204:207], v[188:191], v[76:79]
	v_mfma_f32_16x16x32_bf16 v[72:75], v[212:215], v[188:191], v[72:75]
	v_mfma_f32_16x16x32_bf16 v[68:71], v[204:207], v[196:199], v[68:71]
	v_mfma_f32_16x16x32_bf16 v[64:67], v[212:215], v[196:199], v[64:67]
	s_mov_b32 m0, s71
	v_lshl_add_u64 v[216:217], v[220:221], 0, s[6:7]
	s_barrier
	ds_read_b128 v[168:171], v148 offset:49152
	ds_read_b128 v[172:175], v148 offset:50176
	ds_read_b128 v[176:179], v148 offset:51200
	ds_read_b128 v[180:183], v148 offset:52224
	ds_read_b128 v[184:187], v148 offset:53248
	ds_read_b128 v[188:191], v148 offset:54272
	ds_read_b128 v[192:195], v148 offset:55296
	ds_read_b128 v[196:199], v148 offset:56320
	global_load_lds_dwordx4 v[216:217], off
	s_mov_b32 m0, s72
	v_lshl_add_u64 v[216:217], v[222:223], 0, s[6:7]
	global_load_lds_dwordx4 v[216:217], off
	s_barrier
	s_waitcnt lgkmcnt(0)
	v_mfma_f32_16x16x32_bf16 v[60:63], v[150:153], v[168:171], v[60:63]
	v_mfma_f32_16x16x32_bf16 v[56:59], v[160:163], v[168:171], v[56:59]
	v_mfma_f32_16x16x32_bf16 v[52:55], v[150:153], v[176:179], v[52:55]
	v_mfma_f32_16x16x32_bf16 v[48:51], v[160:163], v[176:179], v[48:51]
	v_mfma_f32_16x16x32_bf16 v[36:39], v[150:153], v[184:187], v[36:39]
	v_mfma_f32_16x16x32_bf16 v[32:35], v[160:163], v[184:187], v[32:35]
	v_mfma_f32_16x16x32_bf16 v[20:23], v[150:153], v[192:195], v[20:23]
	v_mfma_f32_16x16x32_bf16 v[16:19], v[160:163], v[192:195], v[16:19]
	v_mfma_f32_16x16x32_bf16 v[60:63], v[156:159], v[172:175], v[60:63]
	v_mfma_f32_16x16x32_bf16 v[56:59], v[164:167], v[172:175], v[56:59]
	v_mfma_f32_16x16x32_bf16 v[52:55], v[156:159], v[180:183], v[52:55]
	v_mfma_f32_16x16x32_bf16 v[48:51], v[164:167], v[180:183], v[48:51]
	v_mfma_f32_16x16x32_bf16 v[36:39], v[156:159], v[188:191], v[36:39]
	v_mfma_f32_16x16x32_bf16 v[32:35], v[164:167], v[188:191], v[32:35]
	v_mfma_f32_16x16x32_bf16 v[20:23], v[156:159], v[196:199], v[20:23]
	v_mfma_f32_16x16x32_bf16 v[16:19], v[164:167], v[196:199], v[16:19]
	s_barrier
	s_add_u32 s90, s90, 0x40080
	s_addc_u32 s91, s91, 0
	s_add_i32 s83, s92, s1
	s_mov_b32 m0, s83
	v_lshl_add_u64 v[150:151], s[90:91], 0, v[132:133]
	global_load_lds_dwordx4 v[150:151], off
	s_add_i32 m0, s83, 0x2000
	v_lshl_add_u64 v[150:151], s[90:91], 0, v[128:129]
	global_load_lds_dwordx4 v[150:151], off
	s_waitcnt vmcnt(6)
	s_barrier
	v_mfma_f32_16x16x32_bf16 v[44:47], v[200:203], v[168:171], v[44:47]
	v_mfma_f32_16x16x32_bf16 v[40:43], v[208:211], v[168:171], v[40:43]
	v_mfma_f32_16x16x32_bf16 v[28:31], v[200:203], v[176:179], v[28:31]
	v_mfma_f32_16x16x32_bf16 v[24:27], v[208:211], v[176:179], v[24:27]
	v_mfma_f32_16x16x32_bf16 v[12:15], v[200:203], v[184:187], v[12:15]
	v_mfma_f32_16x16x32_bf16 v[8:11], v[208:211], v[184:187], v[8:11]
	v_mfma_f32_16x16x32_bf16 v[4:7], v[200:203], v[192:195], v[4:7]
	v_mfma_f32_16x16x32_bf16 v[0:3], v[208:211], v[192:195], v[0:3]
	v_mfma_f32_16x16x32_bf16 v[44:47], v[204:207], v[172:175], v[44:47]
	v_mfma_f32_16x16x32_bf16 v[40:43], v[212:215], v[172:175], v[40:43]
	v_mfma_f32_16x16x32_bf16 v[28:31], v[204:207], v[180:183], v[28:31]
	v_mfma_f32_16x16x32_bf16 v[24:27], v[212:215], v[180:183], v[24:27]
	v_mfma_f32_16x16x32_bf16 v[12:15], v[204:207], v[188:191], v[12:15]
	v_mfma_f32_16x16x32_bf16 v[8:11], v[212:215], v[188:191], v[8:11]
	v_mfma_f32_16x16x32_bf16 v[4:7], v[204:207], v[196:199], v[4:7]
	v_mfma_f32_16x16x32_bf16 v[0:3], v[212:215], v[196:199], v[0:3]
	s_add_i32 s82, s82, 2
	s_add_u32 s88, s88, 0x100
	s_addc_u32 s89, s89, 0
	s_add_u32 s80, s80, 0x100
	s_addc_u32 s81, s81, 0
	s_cmp_gt_u32 s82, 13
	s_barrier
	s_cbranch_scc0 .LBB0_38
	v_lshl_add_u32 v152, s8, 8, v144
	v_lshl_or_b32 v150, s77, 8, v146
	v_cvt_pk_bf16_f32 v124, v124, v125
	v_cvt_pk_bf16_f32 v125, v126, v127
	v_cvt_pk_bf16_f32 v126, v120, v121
	v_mov_b64_e32 v[120:121], s[42:43]
	v_ashrrev_i32_e32 v151, 31, v150
	v_cvt_pk_bf16_f32 v68, v68, v69
	v_cvt_pk_bf16_f32 v69, v70, v71
	v_cvt_pk_bf16_f32 v70, v64, v65
	v_add_u32_e32 v64, 0x80, v152
	v_cvt_pk_bf16_f32 v127, v122, v123
	v_mad_i64_i32 v[122:123], s[78:79], v152, s76, v[120:121]
	v_lshlrev_b64 v[150:151], 1, v[150:151]
	v_cvt_pk_bf16_f32 v60, v60, v61
	v_cvt_pk_bf16_f32 v61, v62, v63
	v_cvt_pk_bf16_f32 v62, v56, v57
	v_mad_i64_i32 v[56:57], s[78:79], v64, s76, v[120:121]
	v_lshl_add_u64 v[122:123], v[122:123], 0, v[150:151]
	v_cvt_pk_bf16_f32 v108, v108, v109
	v_cvt_pk_bf16_f32 v109, v110, v111
	v_cvt_pk_bf16_f32 v110, v104, v105
	v_cvt_pk_bf16_f32 v111, v106, v107
	v_lshl_add_u64 v[56:57], v[56:57], 0, v[150:151]
	v_cvt_pk_bf16_f32 v44, v44, v45
	v_cvt_pk_bf16_f32 v45, v46, v47
	v_cvt_pk_bf16_f32 v46, v40, v41
	v_cvt_pk_bf16_f32 v47, v42, v43
	global_store_dwordx4 v[122:123], v[108:111], off offset:256
	global_store_dwordx4 v[56:57], v[44:47], off offset:256
	v_cvt_pk_bf16_f32 v92, v92, v93
	v_or_b32_e32 v108, 16, v152
	v_add_u32_e32 v44, 0x90, v152
	v_mad_i64_i32 v[108:109], s[78:79], v108, s76, v[120:121]
	v_mad_i64_i32 v[44:45], s[78:79], v44, s76, v[120:121]
	v_lshl_add_u64 v[108:109], v[108:109], 0, v[150:151]
	v_cvt_pk_bf16_f32 v93, v94, v95
	v_cvt_pk_bf16_f32 v94, v88, v89
	v_cvt_pk_bf16_f32 v95, v90, v91
	v_lshl_add_u64 v[44:45], v[44:45], 0, v[150:151]
	v_cvt_pk_bf16_f32 v28, v28, v29
	v_cvt_pk_bf16_f32 v29, v30, v31
	v_cvt_pk_bf16_f32 v30, v24, v25
	v_cvt_pk_bf16_f32 v31, v26, v27
	global_store_dwordx4 v[108:109], v[92:95], off offset:256
	global_store_dwordx4 v[44:45], v[28:31], off offset:256
	v_cvt_pk_bf16_f32 v76, v76, v77
	v_or_b32_e32 v92, 32, v152
	v_add_u32_e32 v28, 0xa0, v152
	v_mad_i64_i32 v[92:93], s[78:79], v92, s76, v[120:121]
	v_mad_i64_i32 v[28:29], s[78:79], v28, s76, v[120:121]
	v_lshl_add_u64 v[92:93], v[92:93], 0, v[150:151]
	v_cvt_pk_bf16_f32 v77, v78, v79
	v_cvt_pk_bf16_f32 v78, v72, v73
	v_cvt_pk_bf16_f32 v79, v74, v75
	v_lshl_add_u64 v[28:29], v[28:29], 0, v[150:151]
	v_cvt_pk_bf16_f32 v12, v12, v13
	v_cvt_pk_bf16_f32 v13, v14, v15
	v_cvt_pk_bf16_f32 v14, v8, v9
	v_cvt_pk_bf16_f32 v15, v10, v11
	global_store_dwordx4 v[92:93], v[76:79], off offset:256
	global_store_dwordx4 v[28:29], v[12:15], off offset:256
	v_cvt_pk_bf16_f32 v104, v116, v117
	v_or_b32_e32 v76, 48, v152
	v_add_u32_e32 v12, 0xb0, v152
	v_mad_i64_i32 v[76:77], s[78:79], v76, s76, v[120:121]
	v_mad_i64_i32 v[12:13], s[78:79], v12, s76, v[120:121]
	v_cvt_pk_bf16_f32 v105, v118, v119
	v_cvt_pk_bf16_f32 v106, v112, v113
	v_cvt_pk_bf16_f32 v107, v114, v115
	v_cvt_pk_bf16_f32 v88, v100, v101
	v_cvt_pk_bf16_f32 v89, v102, v103
	v_cvt_pk_bf16_f32 v90, v96, v97
	v_cvt_pk_bf16_f32 v91, v98, v99
	v_cvt_pk_bf16_f32 v72, v84, v85
	v_cvt_pk_bf16_f32 v73, v86, v87
	v_cvt_pk_bf16_f32 v74, v80, v81
	v_cvt_pk_bf16_f32 v75, v82, v83
	v_lshl_add_u64 v[76:77], v[76:77], 0, v[150:151]
	v_cvt_pk_bf16_f32 v71, v66, v67
	v_cvt_pk_bf16_f32 v63, v58, v59
	v_cvt_pk_bf16_f32 v40, v52, v53
	v_cvt_pk_bf16_f32 v41, v54, v55
	v_cvt_pk_bf16_f32 v42, v48, v49
	v_cvt_pk_bf16_f32 v43, v50, v51
	v_cvt_pk_bf16_f32 v24, v36, v37
	v_cvt_pk_bf16_f32 v25, v38, v39
	v_cvt_pk_bf16_f32 v26, v32, v33
	v_cvt_pk_bf16_f32 v27, v34, v35
	v_cvt_pk_bf16_f32 v8, v20, v21
	v_cvt_pk_bf16_f32 v9, v22, v23
	v_cvt_pk_bf16_f32 v10, v16, v17
	v_cvt_pk_bf16_f32 v11, v18, v19
	v_lshl_add_u64 v[12:13], v[12:13], 0, v[150:151]
	v_cvt_pk_bf16_f32 v4, v4, v5
	v_cvt_pk_bf16_f32 v5, v6, v7
	v_cvt_pk_bf16_f32 v6, v0, v1
	v_cvt_pk_bf16_f32 v7, v2, v3
	s_and_b64 vcc, exec, s[4:5]
	s_mov_b32 s77, s10
	s_mov_b32 s8, s12
	s_mov_b64 s[90:91], s[86:87]
	s_mov_b64 s[88:89], s[14:15]
	global_store_dwordx4 v[122:123], v[124:127], off
	global_store_dwordx4 v[108:109], v[104:107], off
	global_store_dwordx4 v[92:93], v[88:91], off
	global_store_dwordx4 v[76:77], v[72:75], off
	global_store_dwordx4 v[76:77], v[68:71], off offset:256
	global_store_dwordx4 v[56:57], v[60:63], off
	global_store_dwordx4 v[44:45], v[40:43], off
	global_store_dwordx4 v[28:29], v[24:27], off
	global_store_dwordx4 v[12:13], v[8:11], off
	global_store_dwordx4 v[12:13], v[4:7], off offset:256
	s_cbranch_vccz .LBB0_35
	s_waitcnt vmcnt(0)
	s_cmpk_gt_u32 s0, 0xff
	v_readlane_b32 s33, v228, 32
	v_readlane_b32 s56, v228, 35
	s_cbranch_scc1 .LBB0_42
	s_barrier

.LBB0_547:
	s_add_u32 s68, s54, s60
	s_addc_u32 s69, s55, s61
	s_add_u32 s64, s68, 0x100
	s_addc_u32 s65, s69, 0
	s_and_b64 s[62:63], s[58:59], exec
	s_cselect_b32 s65, s41, s65
	s_cselect_b32 s64, s82, s64
	s_add_u32 s60, s52, s60
	s_addc_u32 s61, s53, s61
	s_add_u32 s60, s60, 0x100
	s_addc_u32 s61, s61, 0
	s_and_b64 s[58:59], s[58:59], exec
	s_cselect_b32 s67, s25, s61
	s_cselect_b32 s66, s83, s60
	s_add_u32 s68, s68, 0x10080
	s_addc_u32 s69, s69, 0
	s_add_i32 s94, s79, s1
	s_add_i32 m0, s51, 0xc000
	s_add_i32 s95, s51, 0xe000
	s_add_i32 s93, s94, 0x2000
	s_add_u32 s62, s66, 0x10000
	s_addc_u32 s63, s67, 0
	s_add_i32 s92, s72, s1
	ds_read_b128 v[140:143], v149
	ds_read_b128 v[156:159], v149 offset:1024
	ds_read_b128 v[160:163], v149 offset:2048
	ds_read_b128 v[164:167], v149 offset:3072
	s_add_i32 s91, s92, 0x2000
	s_add_i32 s90, 0, 0x18000
	s_add_u32 s60, s64, 0x10000
	s_addc_u32 s61, s65, 0
	s_add_i32 s89, s90, s1
	s_add_i32 s88, s89, 0x2000
	s_add_u32 s58, s66, 0x10080
	s_addc_u32 s59, s67, 0
	s_add_i32 s87, s97, s1
	s_add_i32 s86, s87, 0x2000
	v_lshl_add_u64 v[144:145], s[68:69], 0, v[134:135]
	ds_read_b128 v[168:171], v150
	ds_read_b128 v[172:175], v150 offset:1024
	ds_read_b128 v[176:179], v150 offset:2048
	ds_read_b128 v[180:183], v150 offset:3072
	ds_read_b128 v[184:187], v150 offset:4096
	ds_read_b128 v[188:191], v150 offset:5120
	ds_read_b128 v[192:195], v150 offset:6144
	ds_read_b128 v[196:199], v150 offset:7168
	global_load_lds_dwordx4 v[144:145], off
	s_mov_b32 m0, s95
	v_lshl_add_u64 v[144:145], s[68:69], 0, v[130:131]
	global_load_lds_dwordx4 v[144:145], off
	s_barrier
	s_waitcnt lgkmcnt(0)
	v_mfma_f32_16x16x32_bf16 v[124:127], v[140:143], v[168:171], v[124:127]
	v_mfma_f32_16x16x32_bf16 v[120:123], v[160:163], v[168:171], v[120:123]
	v_mfma_f32_16x16x32_bf16 v[112:115], v[140:143], v[176:179], v[112:115]
	v_mfma_f32_16x16x32_bf16 v[104:107], v[160:163], v[176:179], v[104:107]
	v_mfma_f32_16x16x32_bf16 v[92:95], v[140:143], v[184:187], v[92:95]
	v_mfma_f32_16x16x32_bf16 v[88:91], v[160:163], v[184:187], v[88:91]
	v_mfma_f32_16x16x32_bf16 v[80:83], v[140:143], v[192:195], v[80:83]
	v_mfma_f32_16x16x32_bf16 v[72:75], v[160:163], v[192:195], v[72:75]
	v_mfma_f32_16x16x32_bf16 v[124:127], v[156:159], v[172:175], v[124:127]
	v_mfma_f32_16x16x32_bf16 v[120:123], v[164:167], v[172:175], v[120:123]
	v_mfma_f32_16x16x32_bf16 v[112:115], v[156:159], v[180:183], v[112:115]
	v_mfma_f32_16x16x32_bf16 v[104:107], v[164:167], v[180:183], v[104:107]
	v_mfma_f32_16x16x32_bf16 v[92:95], v[156:159], v[188:191], v[92:95]
	v_mfma_f32_16x16x32_bf16 v[88:91], v[164:167], v[188:191], v[88:91]
	v_mfma_f32_16x16x32_bf16 v[80:83], v[156:159], v[196:199], v[80:83]
	v_mfma_f32_16x16x32_bf16 v[72:75], v[164:167], v[196:199], v[72:75]
	s_barrier
	s_mov_b32 m0, s94
	v_lshl_add_u64 v[144:145], s[66:67], 0, v[132:133]
	ds_read_b128 v[200:203], v151
	ds_read_b128 v[204:207], v151 offset:1024
	ds_read_b128 v[208:211], v151 offset:2048
	ds_read_b128 v[212:215], v151 offset:3072
	global_load_lds_dwordx4 v[144:145], off
	s_mov_b32 m0, s93
	v_lshl_add_u64 v[152:153], s[66:67], 0, v[128:129]
	global_load_lds_dwordx4 v[152:153], off
	s_barrier
	s_waitcnt lgkmcnt(0)
	v_mfma_f32_16x16x32_bf16 v[116:119], v[200:203], v[168:171], v[116:119]
	v_mfma_f32_16x16x32_bf16 v[108:111], v[208:211], v[168:171], v[108:111]
	v_mfma_f32_16x16x32_bf16 v[100:103], v[200:203], v[176:179], v[100:103]
	v_mfma_f32_16x16x32_bf16 v[96:99], v[208:211], v[176:179], v[96:99]
	v_mfma_f32_16x16x32_bf16 v[84:87], v[200:203], v[184:187], v[84:87]
	v_mfma_f32_16x16x32_bf16 v[76:79], v[208:211], v[184:187], v[76:79]
	v_mfma_f32_16x16x32_bf16 v[68:71], v[200:203], v[192:195], v[68:71]
	v_mfma_f32_16x16x32_bf16 v[64:67], v[208:211], v[192:195], v[64:67]
	v_mfma_f32_16x16x32_bf16 v[116:119], v[204:207], v[172:175], v[116:119]
	v_mfma_f32_16x16x32_bf16 v[108:111], v[212:215], v[172:175], v[108:111]
	v_mfma_f32_16x16x32_bf16 v[100:103], v[204:207], v[180:183], v[100:103]
	v_mfma_f32_16x16x32_bf16 v[96:99], v[212:215], v[180:183], v[96:99]
	v_mfma_f32_16x16x32_bf16 v[84:87], v[204:207], v[188:191], v[84:87]
	v_mfma_f32_16x16x32_bf16 v[76:79], v[212:215], v[188:191], v[76:79]
	v_mfma_f32_16x16x32_bf16 v[68:71], v[204:207], v[196:199], v[68:71]
	v_mfma_f32_16x16x32_bf16 v[64:67], v[212:215], v[196:199], v[64:67]
	s_mov_b32 m0, s51
	v_lshl_add_u64 v[216:217], s[64:65], 0, v[134:135]
	s_barrier
	ds_read_b128 v[168:171], v150 offset:16384
	ds_read_b128 v[172:175], v150 offset:17408
	ds_read_b128 v[176:179], v150 offset:18432
	ds_read_b128 v[180:183], v150 offset:19456
	ds_read_b128 v[184:187], v150 offset:20480
	ds_read_b128 v[188:191], v150 offset:21504
	ds_read_b128 v[192:195], v150 offset:22528
	ds_read_b128 v[196:199], v150 offset:23552
	global_load_lds_dwordx4 v[216:217], off
	s_mov_b32 m0, s71
	v_lshl_add_u64 v[218:219], s[64:65], 0, v[130:131]
	global_load_lds_dwordx4 v[218:219], off
	s_barrier
	s_waitcnt lgkmcnt(0)
	v_mfma_f32_16x16x32_bf16 v[60:63], v[140:143], v[168:171], v[60:63]
	v_mfma_f32_16x16x32_bf16 v[56:59], v[160:163], v[168:171], v[56:59]
	v_mfma_f32_16x16x32_bf16 v[52:55], v[140:143], v[176:179], v[52:55]
	v_mfma_f32_16x16x32_bf16 v[48:51], v[160:163], v[176:179], v[48:51]
	v_mfma_f32_16x16x32_bf16 v[28:31], v[140:143], v[184:187], v[28:31]
	v_mfma_f32_16x16x32_bf16 v[20:23], v[160:163], v[184:187], v[20:23]
	v_mfma_f32_16x16x32_bf16 v[24:27], v[140:143], v[192:195], v[24:27]
	v_mfma_f32_16x16x32_bf16 v[16:19], v[160:163], v[192:195], v[16:19]
	v_mfma_f32_16x16x32_bf16 v[60:63], v[156:159], v[172:175], v[60:63]
	v_mfma_f32_16x16x32_bf16 v[56:59], v[164:167], v[172:175], v[56:59]
	v_mfma_f32_16x16x32_bf16 v[52:55], v[156:159], v[180:183], v[52:55]
	v_mfma_f32_16x16x32_bf16 v[48:51], v[164:167], v[180:183], v[48:51]
	v_mfma_f32_16x16x32_bf16 v[28:31], v[156:159], v[188:191], v[28:31]
	v_mfma_f32_16x16x32_bf16 v[20:23], v[164:167], v[188:191], v[20:23]
	v_mfma_f32_16x16x32_bf16 v[24:27], v[156:159], v[196:199], v[24:27]
	v_mfma_f32_16x16x32_bf16 v[16:19], v[164:167], v[196:199], v[16:19]
	s_barrier
	s_mov_b32 m0, s92
	v_lshl_add_u64 v[140:141], s[62:63], 0, v[132:133]
	global_load_lds_dwordx4 v[140:141], off
	s_mov_b32 m0, s91
	v_lshl_add_u64 v[140:141], s[62:63], 0, v[128:129]
	global_load_lds_dwordx4 v[140:141], off
	s_waitcnt vmcnt(6)
	s_barrier
	v_mfma_f32_16x16x32_bf16 v[44:47], v[200:203], v[168:171], v[44:47]
	v_mfma_f32_16x16x32_bf16 v[40:43], v[208:211], v[168:171], v[40:43]
	v_mfma_f32_16x16x32_bf16 v[36:39], v[200:203], v[176:179], v[36:39]
	v_mfma_f32_16x16x32_bf16 v[32:35], v[208:211], v[176:179], v[32:35]
	v_mfma_f32_16x16x32_bf16 v[12:15], v[200:203], v[184:187], v[12:15]
	v_mfma_f32_16x16x32_bf16 v[4:7], v[208:211], v[184:187], v[4:7]
	v_mfma_f32_16x16x32_bf16 v[8:11], v[200:203], v[192:195], v[8:11]
	v_mfma_f32_16x16x32_bf16 v[0:3], v[208:211], v[192:195], v[0:3]
	v_mfma_f32_16x16x32_bf16 v[44:47], v[204:207], v[172:175], v[44:47]
	v_mfma_f32_16x16x32_bf16 v[40:43], v[212:215], v[172:175], v[40:43]
	v_mfma_f32_16x16x32_bf16 v[36:39], v[204:207], v[180:183], v[36:39]
	v_mfma_f32_16x16x32_bf16 v[32:35], v[212:215], v[180:183], v[32:35]
	v_mfma_f32_16x16x32_bf16 v[12:15], v[204:207], v[188:191], v[12:15]
	v_mfma_f32_16x16x32_bf16 v[4:7], v[212:215], v[188:191], v[4:7]
	v_mfma_f32_16x16x32_bf16 v[8:11], v[204:207], v[196:199], v[8:11]
	v_mfma_f32_16x16x32_bf16 v[0:3], v[212:215], v[196:199], v[0:3]
	v_add_u32_e32 v164, s90, v147
	s_barrier
	ds_read_b128 v[140:143], v164
	ds_read_b128 v[156:159], v164 offset:1024
	ds_read_b128 v[160:163], v164 offset:2048
	ds_read_b128 v[164:167], v164 offset:3072
	s_mov_b32 m0, s73
	v_lshl_add_u64 v[200:201], s[60:61], 0, v[134:135]
	ds_read_b128 v[168:171], v150 offset:32768
	ds_read_b128 v[172:175], v150 offset:33792
	ds_read_b128 v[176:179], v150 offset:34816
	ds_read_b128 v[180:183], v150 offset:35840
	ds_read_b128 v[184:187], v150 offset:36864
	ds_read_b128 v[188:191], v150 offset:37888
	ds_read_b128 v[192:195], v150 offset:38912
	ds_read_b128 v[196:199], v150 offset:39936
	global_load_lds_dwordx4 v[200:201], off
	s_mov_b32 m0, s74
	v_lshl_add_u64 v[200:201], s[60:61], 0, v[130:131]
	global_load_lds_dwordx4 v[200:201], off
	s_barrier
	s_waitcnt lgkmcnt(0)
	v_mfma_f32_16x16x32_bf16 v[124:127], v[140:143], v[168:171], v[124:127]
	v_mfma_f32_16x16x32_bf16 v[120:123], v[160:163], v[168:171], v[120:123]
	v_mfma_f32_16x16x32_bf16 v[112:115], v[140:143], v[176:179], v[112:115]
	v_mfma_f32_16x16x32_bf16 v[104:107], v[160:163], v[176:179], v[104:107]
	v_mfma_f32_16x16x32_bf16 v[92:95], v[140:143], v[184:187], v[92:95]
	v_mfma_f32_16x16x32_bf16 v[88:91], v[160:163], v[184:187], v[88:91]
	v_mfma_f32_16x16x32_bf16 v[80:83], v[140:143], v[192:195], v[80:83]
	v_mfma_f32_16x16x32_bf16 v[72:75], v[160:163], v[192:195], v[72:75]
	v_mfma_f32_16x16x32_bf16 v[124:127], v[156:159], v[172:175], v[124:127]
	v_mfma_f32_16x16x32_bf16 v[120:123], v[164:167], v[172:175], v[120:123]
	v_mfma_f32_16x16x32_bf16 v[112:115], v[156:159], v[180:183], v[112:115]
	v_mfma_f32_16x16x32_bf16 v[104:107], v[164:167], v[180:183], v[104:107]
	v_mfma_f32_16x16x32_bf16 v[92:95], v[156:159], v[188:191], v[92:95]
	v_mfma_f32_16x16x32_bf16 v[88:91], v[164:167], v[188:191], v[88:91]
	v_mfma_f32_16x16x32_bf16 v[80:83], v[156:159], v[196:199], v[80:83]
	v_mfma_f32_16x16x32_bf16 v[72:75], v[164:167], v[196:199], v[72:75]
	s_barrier
	s_mov_b32 m0, s89
	v_add_u32_e32 v212, s97, v147
	v_lshl_add_u64 v[144:145], v[144:145], 0, s[6:7]
	ds_read_b128 v[200:203], v212
	ds_read_b128 v[204:207], v212 offset:1024
	ds_read_b128 v[208:211], v212 offset:2048
	ds_read_b128 v[212:215], v212 offset:3072
	global_load_lds_dwordx4 v[144:145], off
	s_mov_b32 m0, s88
	v_lshl_add_u64 v[144:145], v[152:153], 0, s[6:7]
	global_load_lds_dwordx4 v[144:145], off
	s_barrier
	s_waitcnt lgkmcnt(0)
	v_mfma_f32_16x16x32_bf16 v[116:119], v[200:203], v[168:171], v[116:119]
	v_mfma_f32_16x16x32_bf16 v[108:111], v[208:211], v[168:171], v[108:111]
	v_mfma_f32_16x16x32_bf16 v[100:103], v[200:203], v[176:179], v[100:103]
	v_mfma_f32_16x16x32_bf16 v[96:99], v[208:211], v[176:179], v[96:99]
	v_mfma_f32_16x16x32_bf16 v[84:87], v[200:203], v[184:187], v[84:87]
	v_mfma_f32_16x16x32_bf16 v[76:79], v[208:211], v[184:187], v[76:79]
	v_mfma_f32_16x16x32_bf16 v[68:71], v[200:203], v[192:195], v[68:71]
	v_mfma_f32_16x16x32_bf16 v[64:67], v[208:211], v[192:195], v[64:67]
	v_mfma_f32_16x16x32_bf16 v[116:119], v[204:207], v[172:175], v[116:119]
	v_mfma_f32_16x16x32_bf16 v[108:111], v[212:215], v[172:175], v[108:111]
	v_mfma_f32_16x16x32_bf16 v[100:103], v[204:207], v[180:183], v[100:103]
	v_mfma_f32_16x16x32_bf16 v[96:99], v[212:215], v[180:183], v[96:99]
	v_mfma_f32_16x16x32_bf16 v[84:87], v[204:207], v[188:191], v[84:87]
	v_mfma_f32_16x16x32_bf16 v[76:79], v[212:215], v[188:191], v[76:79]
	v_mfma_f32_16x16x32_bf16 v[68:71], v[204:207], v[196:199], v[68:71]
	v_mfma_f32_16x16x32_bf16 v[64:67], v[212:215], v[196:199], v[64:67]
	s_mov_b32 m0, s76
	v_lshl_add_u64 v[144:145], v[216:217], 0, s[6:7]
	s_barrier
	ds_read_b128 v[168:171], v150 offset:49152
	ds_read_b128 v[172:175], v150 offset:50176
	ds_read_b128 v[176:179], v150 offset:51200
	ds_read_b128 v[180:183], v150 offset:52224
	ds_read_b128 v[184:187], v150 offset:53248
	ds_read_b128 v[188:191], v150 offset:54272
	ds_read_b128 v[192:195], v150 offset:55296
	ds_read_b128 v[196:199], v150 offset:56320
	global_load_lds_dwordx4 v[144:145], off
	s_mov_b32 m0, s77
	v_lshl_add_u64 v[144:145], v[218:219], 0, s[6:7]
	global_load_lds_dwordx4 v[144:145], off
	s_barrier
	s_waitcnt lgkmcnt(0)
	v_mfma_f32_16x16x32_bf16 v[60:63], v[140:143], v[168:171], v[60:63]
	v_mfma_f32_16x16x32_bf16 v[56:59], v[160:163], v[168:171], v[56:59]
	v_mfma_f32_16x16x32_bf16 v[52:55], v[140:143], v[176:179], v[52:55]
	v_mfma_f32_16x16x32_bf16 v[48:51], v[160:163], v[176:179], v[48:51]
	v_mfma_f32_16x16x32_bf16 v[28:31], v[140:143], v[184:187], v[28:31]
	v_mfma_f32_16x16x32_bf16 v[20:23], v[160:163], v[184:187], v[20:23]
	v_mfma_f32_16x16x32_bf16 v[24:27], v[140:143], v[192:195], v[24:27]
	v_mfma_f32_16x16x32_bf16 v[16:19], v[160:163], v[192:195], v[16:19]
	v_mfma_f32_16x16x32_bf16 v[60:63], v[156:159], v[172:175], v[60:63]
	v_mfma_f32_16x16x32_bf16 v[56:59], v[164:167], v[172:175], v[56:59]
	v_mfma_f32_16x16x32_bf16 v[52:55], v[156:159], v[180:183], v[52:55]
	v_mfma_f32_16x16x32_bf16 v[48:51], v[164:167], v[180:183], v[48:51]
	v_mfma_f32_16x16x32_bf16 v[28:31], v[156:159], v[188:191], v[28:31]
	v_mfma_f32_16x16x32_bf16 v[20:23], v[164:167], v[188:191], v[20:23]
	v_mfma_f32_16x16x32_bf16 v[24:27], v[156:159], v[196:199], v[24:27]
	v_mfma_f32_16x16x32_bf16 v[16:19], v[164:167], v[196:199], v[16:19]
	s_barrier
	s_mov_b32 m0, s87
	v_lshl_add_u64 v[140:141], s[58:59], 0, v[132:133]
	global_load_lds_dwordx4 v[140:141], off
	s_mov_b32 m0, s86
	v_lshl_add_u64 v[140:141], s[58:59], 0, v[128:129]
	global_load_lds_dwordx4 v[140:141], off
	s_waitcnt vmcnt(6)
	s_barrier
	v_mfma_f32_16x16x32_bf16 v[44:47], v[200:203], v[168:171], v[44:47]
	v_mfma_f32_16x16x32_bf16 v[40:43], v[208:211], v[168:171], v[40:43]
	v_mfma_f32_16x16x32_bf16 v[36:39], v[200:203], v[176:179], v[36:39]
	v_mfma_f32_16x16x32_bf16 v[32:35], v[208:211], v[176:179], v[32:35]
	v_mfma_f32_16x16x32_bf16 v[12:15], v[200:203], v[184:187], v[12:15]
	v_mfma_f32_16x16x32_bf16 v[4:7], v[208:211], v[184:187], v[4:7]
	v_mfma_f32_16x16x32_bf16 v[8:11], v[200:203], v[192:195], v[8:11]
	v_mfma_f32_16x16x32_bf16 v[0:3], v[208:211], v[192:195], v[0:3]
	v_mfma_f32_16x16x32_bf16 v[44:47], v[204:207], v[172:175], v[44:47]
	v_mfma_f32_16x16x32_bf16 v[40:43], v[212:215], v[172:175], v[40:43]
	v_mfma_f32_16x16x32_bf16 v[36:39], v[204:207], v[180:183], v[36:39]
	v_mfma_f32_16x16x32_bf16 v[32:35], v[212:215], v[180:183], v[32:35]
	v_mfma_f32_16x16x32_bf16 v[12:15], v[204:207], v[188:191], v[12:15]
	v_mfma_f32_16x16x32_bf16 v[4:7], v[212:215], v[188:191], v[4:7]
	v_mfma_f32_16x16x32_bf16 v[8:11], v[204:207], v[196:199], v[8:11]
	v_mfma_f32_16x16x32_bf16 v[0:3], v[212:215], v[196:199], v[0:3]
	s_andn2_b64 vcc, exec, s[56:57]
	s_mov_b64 s[58:59], -1
	s_mov_b64 s[56:57], 0
	s_mov_b64 s[60:61], 0x100
	s_barrier
	s_cbranch_vccz .LBB0_547
	v_lshl_add_u32 v142, s50, 8, v146
	v_lshl_or_b32 v140, s81, 8, v148
	v_ashrrev_i32_e32 v143, 31, v142
	v_lshlrev_b64 v[144:145], 11, v[142:143]
	v_ashrrev_i32_e32 v141, 31, v140
	v_lshl_add_u64 v[152:153], s[28:29], 0, v[144:145]
	v_lshlrev_b64 v[144:145], 1, v[140:141]
	v_lshl_add_u64 v[140:141], v[152:153], 0, v[144:145]
	v_or_b32_e32 v152, 16, v142
	v_ashrrev_i32_e32 v153, 31, v152
	v_lshlrev_b64 v[152:153], 11, v[152:153]
	global_load_dwordx4 v[156:159], v[140:141], off
	global_load_dwordx4 v[160:163], v[140:141], off offset:256
	v_lshl_add_u64 v[152:153], s[28:29], 0, v[152:153]
	v_lshl_add_u64 v[152:153], v[152:153], 0, v[144:145]
	global_load_dwordx4 v[164:167], v[152:153], off
	global_load_dwordx4 v[168:171], v[152:153], off offset:256
	s_waitcnt vmcnt(0)
	v_lshlrev_b32_e32 v172, 16, v156
	v_and_b32_e32 v173, 0xffff0000, v156
	v_lshlrev_b32_e32 v156, 16, v157
	v_and_b32_e32 v157, 0xffff0000, v157
	v_lshlrev_b32_e32 v176, 16, v160
	v_and_b32_e32 v177, 0xffff0000, v160
	v_lshlrev_b32_e32 v160, 16, v161
	v_and_b32_e32 v161, 0xffff0000, v161
	v_lshlrev_b32_e32 v178, 16, v162
	v_and_b32_e32 v179, 0xffff0000, v162
	v_lshlrev_b32_e32 v162, 16, v163
	v_and_b32_e32 v163, 0xffff0000, v163
	v_lshlrev_b32_e32 v174, 16, v158
	v_and_b32_e32 v175, 0xffff0000, v158
	v_lshlrev_b32_e32 v158, 16, v159
	v_and_b32_e32 v159, 0xffff0000, v159
	v_pk_mul_f32 v[126:127], v[126:127], v[156:157]
	v_pk_mul_f32 v[118:119], v[118:119], v[160:161]
	v_pk_mul_f32 v[156:157], v[110:111], v[162:163]
	v_lshlrev_b32_e32 v160, 16, v164
	v_and_b32_e32 v161, 0xffff0000, v164
	v_lshlrev_b32_e32 v162, 16, v165
	v_and_b32_e32 v163, 0xffff0000, v165
	v_lshlrev_b32_e32 v164, 16, v166
	v_and_b32_e32 v165, 0xffff0000, v166
	v_lshlrev_b32_e32 v166, 16, v167
	v_and_b32_e32 v167, 0xffff0000, v167
	v_pk_mul_f32 v[124:125], v[124:125], v[172:173]
	v_pk_mul_f32 v[122:123], v[122:123], v[158:159]
	v_pk_mul_f32 v[120:121], v[120:121], v[174:175]
	v_lshlrev_b32_e32 v172, 16, v168
	v_and_b32_e32 v173, 0xffff0000, v168
	v_lshlrev_b32_e32 v168, 16, v169
	v_and_b32_e32 v169, 0xffff0000, v169
	v_lshlrev_b32_e32 v174, 16, v170
	v_and_b32_e32 v175, 0xffff0000, v170
	v_lshlrev_b32_e32 v170, 16, v171
	v_and_b32_e32 v171, 0xffff0000, v171
	v_pk_mul_f32 v[114:115], v[114:115], v[162:163]
	v_pk_mul_f32 v[112:113], v[112:113], v[160:161]
	v_pk_mul_f32 v[106:107], v[106:107], v[166:167]
	v_pk_mul_f32 v[104:105], v[104:105], v[164:165]
	v_pk_mul_f32 v[116:117], v[116:117], v[176:177]
	v_pk_mul_f32 v[158:159], v[108:109], v[178:179]
	v_cvt_pk_bf16_f32 v108, v124, v125
	v_cvt_pk_bf16_f32 v109, v126, v127
	v_cvt_pk_bf16_f32 v110, v120, v121
	v_cvt_pk_bf16_f32 v111, v122, v123
	v_pk_mul_f32 v[102:103], v[102:103], v[168:169]
	v_pk_mul_f32 v[100:101], v[100:101], v[172:173]
	v_pk_mul_f32 v[120:121], v[98:99], v[170:171]
	v_pk_mul_f32 v[122:123], v[96:97], v[174:175]
	v_cvt_pk_bf16_f32 v96, v112, v113
	v_cvt_pk_bf16_f32 v97, v114, v115
	v_cvt_pk_bf16_f32 v98, v104, v105
	v_cvt_pk_bf16_f32 v99, v106, v107
	v_cvt_pk_bf16_f32 v116, v116, v117
	v_cvt_pk_bf16_f32 v117, v118, v119
	v_cvt_pk_bf16_f32 v118, v158, v159
	v_cvt_pk_bf16_f32 v119, v156, v157
	global_store_dwordx4 v[140:141], v[108:111], off
	global_store_dwordx4 v[140:141], v[116:119], off offset:256
	v_cvt_pk_bf16_f32 v100, v100, v101
	v_cvt_pk_bf16_f32 v101, v102, v103
	v_cvt_pk_bf16_f32 v102, v122, v123
	v_cvt_pk_bf16_f32 v103, v120, v121
	global_store_dwordx4 v[152:153], v[96:99], off
	global_store_dwordx4 v[152:153], v[100:103], off offset:256
	s_nop 0
	v_or_b32_e32 v96, 32, v142
	v_ashrrev_i32_e32 v97, 31, v96
	v_lshlrev_b64 v[96:97], 11, v[96:97]
	v_or_b32_e32 v104, 48, v142
	v_lshl_add_u64 v[96:97], s[28:29], 0, v[96:97]
	v_ashrrev_i32_e32 v105, 31, v104
	v_lshl_add_u64 v[112:113], v[96:97], 0, v[144:145]
	v_lshlrev_b64 v[104:105], 11, v[104:105]
	global_load_dwordx4 v[96:99], v[112:113], off
	global_load_dwordx4 v[100:103], v[112:113], off offset:256
	v_lshl_add_u64 v[104:105], s[28:29], 0, v[104:105]
	v_lshl_add_u64 v[114:115], v[104:105], 0, v[144:145]
	global_load_dwordx4 v[104:107], v[114:115], off
	global_load_dwordx4 v[108:111], v[114:115], off offset:256
	s_waitcnt vmcnt(0)
	v_lshlrev_b32_e32 v116, 16, v96
	v_and_b32_e32 v117, 0xffff0000, v96
	v_lshlrev_b32_e32 v96, 16, v97
	v_and_b32_e32 v97, 0xffff0000, v97
	v_lshlrev_b32_e32 v120, 16, v100
	v_and_b32_e32 v121, 0xffff0000, v100
	v_lshlrev_b32_e32 v100, 16, v101
	v_and_b32_e32 v101, 0xffff0000, v101
	v_lshlrev_b32_e32 v122, 16, v102
	v_and_b32_e32 v123, 0xffff0000, v102
	v_lshlrev_b32_e32 v102, 16, v103
	v_and_b32_e32 v103, 0xffff0000, v103
	v_lshlrev_b32_e32 v118, 16, v98
	v_and_b32_e32 v119, 0xffff0000, v98
	v_lshlrev_b32_e32 v98, 16, v99
	v_and_b32_e32 v99, 0xffff0000, v99
	v_pk_mul_f32 v[94:95], v[94:95], v[96:97]
	v_pk_mul_f32 v[86:87], v[86:87], v[100:101]
	v_pk_mul_f32 v[96:97], v[78:79], v[102:103]
	v_lshlrev_b32_e32 v100, 16, v104
	v_and_b32_e32 v101, 0xffff0000, v104
	v_lshlrev_b32_e32 v102, 16, v105
	v_and_b32_e32 v103, 0xffff0000, v105
	v_lshlrev_b32_e32 v104, 16, v106
	v_and_b32_e32 v105, 0xffff0000, v106
	v_lshlrev_b32_e32 v106, 16, v107
	v_and_b32_e32 v107, 0xffff0000, v107
	v_pk_mul_f32 v[92:93], v[92:93], v[116:117]
	v_pk_mul_f32 v[90:91], v[90:91], v[98:99]
	v_pk_mul_f32 v[88:89], v[88:89], v[118:119]
	v_lshlrev_b32_e32 v116, 16, v108
	v_and_b32_e32 v117, 0xffff0000, v108
	v_lshlrev_b32_e32 v108, 16, v109
	v_and_b32_e32 v109, 0xffff0000, v109
	v_lshlrev_b32_e32 v118, 16, v110
	v_and_b32_e32 v119, 0xffff0000, v110
	v_lshlrev_b32_e32 v110, 16, v111
	v_and_b32_e32 v111, 0xffff0000, v111
	v_pk_mul_f32 v[82:83], v[82:83], v[102:103]
	v_pk_mul_f32 v[80:81], v[80:81], v[100:101]
	v_pk_mul_f32 v[74:75], v[74:75], v[106:107]
	v_pk_mul_f32 v[72:73], v[72:73], v[104:105]
	v_pk_mul_f32 v[84:85], v[84:85], v[120:121]
	v_pk_mul_f32 v[98:99], v[76:77], v[122:123]
	v_cvt_pk_bf16_f32 v76, v92, v93
	v_cvt_pk_bf16_f32 v77, v94, v95
	v_cvt_pk_bf16_f32 v78, v88, v89
	v_cvt_pk_bf16_f32 v79, v90, v91
	v_pk_mul_f32 v[70:71], v[70:71], v[108:109]
	v_pk_mul_f32 v[68:69], v[68:69], v[116:117]
	v_pk_mul_f32 v[88:89], v[66:67], v[110:111]
	v_pk_mul_f32 v[90:91], v[64:65], v[118:119]
	v_cvt_pk_bf16_f32 v64, v80, v81
	v_cvt_pk_bf16_f32 v65, v82, v83
	v_cvt_pk_bf16_f32 v66, v72, v73
	v_cvt_pk_bf16_f32 v67, v74, v75
	v_cvt_pk_bf16_f32 v84, v84, v85
	v_cvt_pk_bf16_f32 v85, v86, v87
	v_cvt_pk_bf16_f32 v86, v98, v99
	v_cvt_pk_bf16_f32 v87, v96, v97
	global_store_dwordx4 v[112:113], v[76:79], off
	global_store_dwordx4 v[112:113], v[84:87], off offset:256
	v_cvt_pk_bf16_f32 v68, v68, v69
	v_cvt_pk_bf16_f32 v69, v70, v71
	v_cvt_pk_bf16_f32 v70, v90, v91
	v_cvt_pk_bf16_f32 v71, v88, v89
	global_store_dwordx4 v[114:115], v[64:67], off
	global_store_dwordx4 v[114:115], v[68:71], off offset:256
	s_mov_b32 s25, 0x40000
	v_add_co_u32_e32 v80, vcc, s25, v140
	s_mov_b64 s[52:53], 0x40000
	s_nop 0
	v_addc_co_u32_e32 v81, vcc, 0, v141, vcc
	s_mov_b32 s25, 0x48000
	v_lshl_add_u64 v[82:83], v[140:141], 0, s[52:53]
	v_add_co_u32_e32 v84, vcc, s25, v140
	s_mov_b64 s[52:53], 0x48000
	global_load_dwordx4 v[64:67], v[80:81], off
	global_load_dwordx4 v[68:71], v[82:83], off offset:256
	v_addc_co_u32_e32 v85, vcc, 0, v141, vcc
	v_lshl_add_u64 v[86:87], v[140:141], 0, s[52:53]
	global_load_dwordx4 v[72:75], v[84:85], off
	global_load_dwordx4 v[76:79], v[86:87], off offset:256
	s_waitcnt vmcnt(0)
	v_lshlrev_b32_e32 v88, 16, v64
	v_and_b32_e32 v89, 0xffff0000, v64
	v_lshlrev_b32_e32 v64, 16, v65
	v_and_b32_e32 v65, 0xffff0000, v65
	v_lshlrev_b32_e32 v90, 16, v66
	v_and_b32_e32 v91, 0xffff0000, v66
	v_lshlrev_b32_e32 v66, 16, v67
	v_and_b32_e32 v67, 0xffff0000, v67
	v_lshlrev_b32_e32 v92, 16, v68
	v_and_b32_e32 v93, 0xffff0000, v68
	v_lshlrev_b32_e32 v68, 16, v69
	v_and_b32_e32 v69, 0xffff0000, v69
	v_lshlrev_b32_e32 v94, 16, v70
	v_and_b32_e32 v95, 0xffff0000, v70
	v_lshlrev_b32_e32 v70, 16, v71
	v_and_b32_e32 v71, 0xffff0000, v71
	v_lshlrev_b32_e32 v96, 16, v72
	v_and_b32_e32 v97, 0xffff0000, v72
	v_lshlrev_b32_e32 v72, 16, v73
	v_and_b32_e32 v73, 0xffff0000, v73
	v_lshlrev_b32_e32 v98, 16, v74
	v_and_b32_e32 v99, 0xffff0000, v74
	v_lshlrev_b32_e32 v74, 16, v75
	v_and_b32_e32 v75, 0xffff0000, v75
	v_lshlrev_b32_e32 v100, 16, v76
	v_and_b32_e32 v101, 0xffff0000, v76
	v_lshlrev_b32_e32 v76, 16, v77
	v_and_b32_e32 v77, 0xffff0000, v77
	v_lshlrev_b32_e32 v102, 16, v78
	v_and_b32_e32 v103, 0xffff0000, v78
	v_lshlrev_b32_e32 v78, 16, v79
	v_and_b32_e32 v79, 0xffff0000, v79
	v_pk_mul_f32 v[62:63], v[62:63], v[64:65]
	v_pk_mul_f32 v[60:61], v[60:61], v[88:89]
	v_pk_mul_f32 v[58:59], v[58:59], v[66:67]
	v_pk_mul_f32 v[56:57], v[56:57], v[90:91]
	v_pk_mul_f32 v[46:47], v[46:47], v[68:69]
	v_pk_mul_f32 v[44:45], v[44:45], v[92:93]
	v_pk_mul_f32 v[42:43], v[42:43], v[70:71]
	v_pk_mul_f32 v[40:41], v[40:41], v[94:95]
	v_pk_mul_f32 v[54:55], v[54:55], v[72:73]
	v_pk_mul_f32 v[52:53], v[52:53], v[96:97]
	v_pk_mul_f32 v[50:51], v[50:51], v[74:75]
	v_pk_mul_f32 v[48:49], v[48:49], v[98:99]
	v_pk_mul_f32 v[64:65], v[38:39], v[76:77]
	v_pk_mul_f32 v[66:67], v[36:37], v[100:101]
	v_pk_mul_f32 v[68:69], v[34:35], v[78:79]
	v_pk_mul_f32 v[70:71], v[32:33], v[102:103]
	v_cvt_pk_bf16_f32 v32, v60, v61
	v_cvt_pk_bf16_f32 v33, v62, v63
	v_cvt_pk_bf16_f32 v34, v56, v57
	v_cvt_pk_bf16_f32 v35, v58, v59
	v_cvt_pk_bf16_f32 v36, v44, v45
	v_cvt_pk_bf16_f32 v37, v46, v47
	v_cvt_pk_bf16_f32 v38, v40, v41
	v_cvt_pk_bf16_f32 v39, v42, v43
	v_cvt_pk_bf16_f32 v40, v52, v53
	v_cvt_pk_bf16_f32 v41, v54, v55
	v_cvt_pk_bf16_f32 v42, v48, v49
	v_cvt_pk_bf16_f32 v43, v50, v51
	v_cvt_pk_bf16_f32 v44, v66, v67
	v_cvt_pk_bf16_f32 v45, v64, v65
	v_cvt_pk_bf16_f32 v46, v70, v71
	v_cvt_pk_bf16_f32 v47, v68, v69
	global_store_dwordx4 v[80:81], v[32:35], off
	global_store_dwordx4 v[82:83], v[36:39], off offset:256
	global_store_dwordx4 v[84:85], v[40:43], off
	global_store_dwordx4 v[86:87], v[44:47], off offset:256
	v_add_co_u32_e32 v48, vcc, s80, v140
	s_mov_b32 s25, 0x50000
	s_nop 0
	v_addc_co_u32_e32 v49, vcc, 0, v141, vcc
	v_add_co_u32_e32 v52, vcc, s25, v140
	v_lshl_add_u64 v[50:51], v[140:141], 0, s[14:15]
	s_nop 0
	v_addc_co_u32_e32 v53, vcc, 0, v141, vcc
	s_mov_b64 s[52:53], 0x50000
	global_load_dwordx4 v[32:35], v[48:49], off
	global_load_dwordx4 v[36:39], v[50:51], off offset:256
	global_load_dwordx4 v[40:43], v[52:53], off
	v_lshl_add_u64 v[54:55], v[140:141], 0, s[52:53]
	global_load_dwordx4 v[44:47], v[54:55], off offset:256
	s_and_b64 vcc, exec, s[4:5]
	s_mov_b32 s81, s24
	s_mov_b32 s50, s40
	s_mov_b64 s[52:53], s[48:49]
	s_mov_b64 s[54:55], s[46:47]
	s_waitcnt vmcnt(0)
	v_lshlrev_b32_e32 v56, 16, v32
	v_lshlrev_b32_e32 v60, 16, v36
	v_and_b32_e32 v61, 0xffff0000, v36
	v_lshlrev_b32_e32 v36, 16, v37
	v_and_b32_e32 v37, 0xffff0000, v37
	v_lshlrev_b32_e32 v64, 16, v40
	v_and_b32_e32 v65, 0xffff0000, v40
	v_lshlrev_b32_e32 v40, 16, v41
	v_and_b32_e32 v41, 0xffff0000, v41
	v_lshlrev_b32_e32 v66, 16, v42
	v_and_b32_e32 v67, 0xffff0000, v42
	v_lshlrev_b32_e32 v42, 16, v43
	v_and_b32_e32 v43, 0xffff0000, v43
	v_and_b32_e32 v57, 0xffff0000, v32
	v_lshlrev_b32_e32 v32, 16, v33
	v_and_b32_e32 v33, 0xffff0000, v33
	v_lshlrev_b32_e32 v58, 16, v34
	v_and_b32_e32 v59, 0xffff0000, v34
	v_lshlrev_b32_e32 v34, 16, v35
	v_and_b32_e32 v35, 0xffff0000, v35
	v_lshlrev_b32_e32 v62, 16, v38
	v_and_b32_e32 v63, 0xffff0000, v38
	v_lshlrev_b32_e32 v38, 16, v39
	v_and_b32_e32 v39, 0xffff0000, v39
	v_lshlrev_b32_e32 v68, 16, v44
	v_and_b32_e32 v69, 0xffff0000, v44
	v_lshlrev_b32_e32 v44, 16, v45
	v_and_b32_e32 v45, 0xffff0000, v45
	v_lshlrev_b32_e32 v70, 16, v46
	v_and_b32_e32 v71, 0xffff0000, v46
	v_lshlrev_b32_e32 v46, 16, v47
	v_and_b32_e32 v47, 0xffff0000, v47
	v_pk_mul_f32 v[10:11], v[10:11], v[36:37]
	v_pk_mul_f32 v[8:9], v[8:9], v[60:61]
	v_pk_mul_f32 v[30:31], v[30:31], v[40:41]
	v_pk_mul_f32 v[28:29], v[28:29], v[64:65]
	v_pk_mul_f32 v[22:23], v[22:23], v[42:43]
	v_pk_mul_f32 v[20:21], v[20:21], v[66:67]
	v_pk_mul_f32 v[26:27], v[26:27], v[32:33]
	v_pk_mul_f32 v[24:25], v[24:25], v[56:57]
	v_pk_mul_f32 v[18:19], v[18:19], v[34:35]
	v_pk_mul_f32 v[16:17], v[16:17], v[58:59]
	v_pk_mul_f32 v[32:33], v[2:3], v[38:39]
	v_pk_mul_f32 v[34:35], v[0:1], v[62:63]
	v_pk_mul_f32 v[14:15], v[14:15], v[44:45]
	v_pk_mul_f32 v[12:13], v[12:13], v[68:69]
	v_pk_mul_f32 v[36:37], v[6:7], v[46:47]
	v_pk_mul_f32 v[38:39], v[4:5], v[70:71]
	v_cvt_pk_bf16_f32 v4, v8, v9
	v_cvt_pk_bf16_f32 v5, v10, v11
	v_cvt_pk_bf16_f32 v8, v28, v29
	v_cvt_pk_bf16_f32 v9, v30, v31
	v_cvt_pk_bf16_f32 v10, v20, v21
	v_cvt_pk_bf16_f32 v11, v22, v23
	v_cvt_pk_bf16_f32 v0, v24, v25
	v_cvt_pk_bf16_f32 v1, v26, v27
	v_cvt_pk_bf16_f32 v2, v16, v17
	v_cvt_pk_bf16_f32 v3, v18, v19
	v_cvt_pk_bf16_f32 v6, v34, v35
	v_cvt_pk_bf16_f32 v7, v32, v33
	v_cvt_pk_bf16_f32 v12, v12, v13
	v_cvt_pk_bf16_f32 v13, v14, v15
	v_cvt_pk_bf16_f32 v14, v38, v39
	v_cvt_pk_bf16_f32 v15, v36, v37
	global_store_dwordx4 v[52:53], v[8:11], off
	global_store_dwordx4 v[54:55], v[12:15], off offset:256
	global_store_dwordx4 v[48:49], v[0:3], off
	global_store_dwordx4 v[50:51], v[4:7], off offset:256
	s_cbranch_vccz .LBB0_544
	s_waitcnt vmcnt(0)
	v_readlane_b32 s78, v228, 33
	v_readlane_b32 s80, v228, 36
	s_cmpk_gt_u32 s0, 0xff
	v_readlane_b32 s76, v228, 32
	v_readlane_b32 s79, v228, 34
	v_readlane_b32 s77, v228, 35
	v_readlane_b32 s81, v228, 37
	s_cbranch_scc1 .LBB0_551
	s_barrier

.LBB0_569:
	ds_read_b128 v[144:147], v157
	ds_read_b128 v[148:151], v157 offset:1024
	ds_read_b128 v[160:163], v157 offset:2048
	ds_read_b128 v[164:167], v157 offset:3072
	s_add_u32 s60, s58, 0xfffc0080
	s_addc_u32 s61, s59, -1
	s_cmp_eq_u32 s83, 12
	s_cselect_b32 s63, s51, s61
	s_cselect_b32 s62, s79, s60
	s_cselect_b32 s61, s49, s82
	s_cselect_b32 s60, s80, s81
	v_lshl_add_u64 v[200:201], s[58:59], 0, v[136:137]
	s_add_i32 m0, s57, 0xc000
	ds_read_b128 v[168:171], v158
	ds_read_b128 v[172:175], v158 offset:1024
	ds_read_b128 v[176:179], v158 offset:2048
	ds_read_b128 v[180:183], v158 offset:3072
	ds_read_b128 v[184:187], v158 offset:4096
	ds_read_b128 v[188:191], v158 offset:5120
	ds_read_b128 v[192:195], v158 offset:6144
	ds_read_b128 v[196:199], v158 offset:7168
	global_load_lds_dwordx4 v[200:201], off
	s_add_i32 m0, s57, 0xe000
	v_lshl_add_u64 v[200:201], s[58:59], 0, v[138:139]
	global_load_lds_dwordx4 v[200:201], off
	s_barrier
	s_waitcnt lgkmcnt(0)
	v_mfma_f32_16x16x32_bf16 v[124:127], v[144:147], v[168:171], v[124:127]
	v_mfma_f32_16x16x32_bf16 v[120:123], v[160:163], v[168:171], v[120:123]
	v_mfma_f32_16x16x32_bf16 v[108:111], v[144:147], v[176:179], v[108:111]
	v_mfma_f32_16x16x32_bf16 v[104:107], v[160:163], v[176:179], v[104:107]
	v_mfma_f32_16x16x32_bf16 v[92:95], v[144:147], v[184:187], v[92:95]
	v_mfma_f32_16x16x32_bf16 v[88:91], v[160:163], v[184:187], v[88:91]
	v_mfma_f32_16x16x32_bf16 v[76:79], v[144:147], v[192:195], v[76:79]
	v_mfma_f32_16x16x32_bf16 v[72:75], v[160:163], v[192:195], v[72:75]
	v_mfma_f32_16x16x32_bf16 v[124:127], v[148:151], v[172:175], v[124:127]
	v_mfma_f32_16x16x32_bf16 v[120:123], v[164:167], v[172:175], v[120:123]
	v_mfma_f32_16x16x32_bf16 v[108:111], v[148:151], v[180:183], v[108:111]
	v_mfma_f32_16x16x32_bf16 v[104:107], v[164:167], v[180:183], v[104:107]
	v_mfma_f32_16x16x32_bf16 v[92:95], v[148:151], v[188:191], v[92:95]
	v_mfma_f32_16x16x32_bf16 v[88:91], v[164:167], v[188:191], v[88:91]
	v_mfma_f32_16x16x32_bf16 v[76:79], v[148:151], v[196:199], v[76:79]
	v_mfma_f32_16x16x32_bf16 v[72:75], v[164:167], v[196:199], v[72:75]
	s_barrier
	s_add_i32 s86, s73, s34
	v_lshl_add_u64 v[216:217], s[60:61], 0, v[132:133]
	s_mov_b32 m0, s86
	ds_read_b128 v[200:203], v159
	ds_read_b128 v[204:207], v159 offset:1024
	ds_read_b128 v[208:211], v159 offset:2048
	ds_read_b128 v[212:215], v159 offset:3072
	global_load_lds_dwordx4 v[216:217], off
	s_add_i32 m0, s86, 0x2000
	v_lshl_add_u64 v[218:219], s[60:61], 0, v[128:129]
	global_load_lds_dwordx4 v[218:219], off
	s_barrier
	s_waitcnt lgkmcnt(0)
	v_mfma_f32_16x16x32_bf16 v[116:119], v[200:203], v[168:171], v[116:119]
	v_mfma_f32_16x16x32_bf16 v[112:115], v[208:211], v[168:171], v[112:115]
	v_mfma_f32_16x16x32_bf16 v[100:103], v[200:203], v[176:179], v[100:103]
	v_mfma_f32_16x16x32_bf16 v[96:99], v[208:211], v[176:179], v[96:99]
	v_mfma_f32_16x16x32_bf16 v[84:87], v[200:203], v[184:187], v[84:87]
	v_mfma_f32_16x16x32_bf16 v[80:83], v[208:211], v[184:187], v[80:83]
	v_mfma_f32_16x16x32_bf16 v[68:71], v[200:203], v[192:195], v[68:71]
	v_mfma_f32_16x16x32_bf16 v[64:67], v[208:211], v[192:195], v[64:67]
	v_mfma_f32_16x16x32_bf16 v[116:119], v[204:207], v[172:175], v[116:119]
	v_mfma_f32_16x16x32_bf16 v[112:115], v[212:215], v[172:175], v[112:115]
	v_mfma_f32_16x16x32_bf16 v[100:103], v[204:207], v[180:183], v[100:103]
	v_mfma_f32_16x16x32_bf16 v[96:99], v[212:215], v[180:183], v[96:99]
	v_mfma_f32_16x16x32_bf16 v[84:87], v[204:207], v[188:191], v[84:87]
	v_mfma_f32_16x16x32_bf16 v[80:83], v[212:215], v[188:191], v[80:83]
	v_mfma_f32_16x16x32_bf16 v[68:71], v[204:207], v[196:199], v[68:71]
	v_mfma_f32_16x16x32_bf16 v[64:67], v[212:215], v[196:199], v[64:67]
	s_mov_b32 m0, s57
	v_lshl_add_u64 v[220:221], s[62:63], 0, v[134:135]
	s_barrier
	ds_read_b128 v[168:171], v158 offset:16384
	ds_read_b128 v[172:175], v158 offset:17408
	ds_read_b128 v[176:179], v158 offset:18432
	ds_read_b128 v[180:183], v158 offset:19456
	ds_read_b128 v[184:187], v158 offset:20480
	ds_read_b128 v[188:191], v158 offset:21504
	ds_read_b128 v[192:195], v158 offset:22528
	ds_read_b128 v[196:199], v158 offset:23552
	global_load_lds_dwordx4 v[220:221], off
	s_mov_b32 m0, s65
	v_lshl_add_u64 v[222:223], s[62:63], 0, v[130:131]
	global_load_lds_dwordx4 v[222:223], off
	s_barrier
	s_waitcnt lgkmcnt(0)
	v_mfma_f32_16x16x32_bf16 v[60:63], v[144:147], v[168:171], v[60:63]
	v_mfma_f32_16x16x32_bf16 v[56:59], v[160:163], v[168:171], v[56:59]
	v_mfma_f32_16x16x32_bf16 v[44:47], v[144:147], v[176:179], v[44:47]
	v_mfma_f32_16x16x32_bf16 v[40:43], v[160:163], v[176:179], v[40:43]
	v_mfma_f32_16x16x32_bf16 v[28:31], v[144:147], v[184:187], v[28:31]
	v_mfma_f32_16x16x32_bf16 v[24:27], v[160:163], v[184:187], v[24:27]
	v_mfma_f32_16x16x32_bf16 v[12:15], v[144:147], v[192:195], v[12:15]
	v_mfma_f32_16x16x32_bf16 v[8:11], v[160:163], v[192:195], v[8:11]
	v_mfma_f32_16x16x32_bf16 v[60:63], v[148:151], v[172:175], v[60:63]
	v_mfma_f32_16x16x32_bf16 v[56:59], v[164:167], v[172:175], v[56:59]
	v_mfma_f32_16x16x32_bf16 v[44:47], v[148:151], v[180:183], v[44:47]
	v_mfma_f32_16x16x32_bf16 v[40:43], v[164:167], v[180:183], v[40:43]
	v_mfma_f32_16x16x32_bf16 v[28:31], v[148:151], v[188:191], v[28:31]
	v_mfma_f32_16x16x32_bf16 v[24:27], v[164:167], v[188:191], v[24:27]
	v_mfma_f32_16x16x32_bf16 v[12:15], v[148:151], v[196:199], v[12:15]
	v_mfma_f32_16x16x32_bf16 v[8:11], v[164:167], v[196:199], v[8:11]
	s_barrier
	s_add_u32 s86, s60, 0x40000
	s_addc_u32 s87, s61, 0
	s_add_i32 s88, s72, s34
	s_mov_b32 m0, s88
	v_lshl_add_u64 v[144:145], s[86:87], 0, v[132:133]
	global_load_lds_dwordx4 v[144:145], off
	s_add_i32 m0, s88, 0x2000
	v_lshl_add_u64 v[144:145], s[86:87], 0, v[128:129]
	global_load_lds_dwordx4 v[144:145], off
	s_waitcnt vmcnt(6)
	s_barrier
	v_mfma_f32_16x16x32_bf16 v[52:55], v[200:203], v[168:171], v[52:55]
	v_mfma_f32_16x16x32_bf16 v[48:51], v[208:211], v[168:171], v[48:51]
	v_mfma_f32_16x16x32_bf16 v[36:39], v[200:203], v[176:179], v[36:39]
	v_mfma_f32_16x16x32_bf16 v[32:35], v[208:211], v[176:179], v[32:35]
	v_mfma_f32_16x16x32_bf16 v[20:23], v[200:203], v[184:187], v[20:23]
	v_mfma_f32_16x16x32_bf16 v[16:19], v[208:211], v[184:187], v[16:19]
	v_mfma_f32_16x16x32_bf16 v[4:7], v[200:203], v[192:195], v[4:7]
	v_mfma_f32_16x16x32_bf16 v[0:3], v[208:211], v[192:195], v[0:3]
	v_mfma_f32_16x16x32_bf16 v[52:55], v[204:207], v[172:175], v[52:55]
	v_mfma_f32_16x16x32_bf16 v[48:51], v[212:215], v[172:175], v[48:51]
	v_mfma_f32_16x16x32_bf16 v[36:39], v[204:207], v[180:183], v[36:39]
	v_mfma_f32_16x16x32_bf16 v[32:35], v[212:215], v[180:183], v[32:35]
	v_mfma_f32_16x16x32_bf16 v[20:23], v[204:207], v[188:191], v[20:23]
	v_mfma_f32_16x16x32_bf16 v[16:19], v[212:215], v[188:191], v[16:19]
	v_mfma_f32_16x16x32_bf16 v[4:7], v[204:207], v[196:199], v[4:7]
	v_mfma_f32_16x16x32_bf16 v[0:3], v[212:215], v[196:199], v[0:3]
	s_add_i32 s86, 0, 0x18000
	v_add_u32_e32 v164, s86, v153
	s_barrier
	ds_read_b128 v[144:147], v164
	ds_read_b128 v[148:151], v164 offset:1024
	ds_read_b128 v[160:163], v164 offset:2048
	ds_read_b128 v[164:167], v164 offset:3072
	s_add_u32 s62, s62, 0x40000
	s_addc_u32 s63, s63, 0
	s_mov_b32 m0, s66
	v_lshl_add_u64 v[200:201], s[62:63], 0, v[134:135]
	ds_read_b128 v[168:171], v158 offset:32768
	ds_read_b128 v[172:175], v158 offset:33792
	ds_read_b128 v[176:179], v158 offset:34816
	ds_read_b128 v[180:183], v158 offset:35840
	ds_read_b128 v[184:187], v158 offset:36864
	ds_read_b128 v[188:191], v158 offset:37888
	ds_read_b128 v[192:195], v158 offset:38912
	ds_read_b128 v[196:199], v158 offset:39936
	global_load_lds_dwordx4 v[200:201], off
	s_mov_b32 m0, s67
	v_lshl_add_u64 v[200:201], s[62:63], 0, v[130:131]
	global_load_lds_dwordx4 v[200:201], off
	s_barrier
	s_waitcnt lgkmcnt(0)
	v_mfma_f32_16x16x32_bf16 v[124:127], v[144:147], v[168:171], v[124:127]
	v_mfma_f32_16x16x32_bf16 v[120:123], v[160:163], v[168:171], v[120:123]
	v_mfma_f32_16x16x32_bf16 v[108:111], v[144:147], v[176:179], v[108:111]
	v_mfma_f32_16x16x32_bf16 v[104:107], v[160:163], v[176:179], v[104:107]
	v_mfma_f32_16x16x32_bf16 v[92:95], v[144:147], v[184:187], v[92:95]
	v_mfma_f32_16x16x32_bf16 v[88:91], v[160:163], v[184:187], v[88:91]
	v_mfma_f32_16x16x32_bf16 v[76:79], v[144:147], v[192:195], v[76:79]
	v_mfma_f32_16x16x32_bf16 v[72:75], v[160:163], v[192:195], v[72:75]
	v_mfma_f32_16x16x32_bf16 v[124:127], v[148:151], v[172:175], v[124:127]
	v_mfma_f32_16x16x32_bf16 v[120:123], v[164:167], v[172:175], v[120:123]
	v_mfma_f32_16x16x32_bf16 v[108:111], v[148:151], v[180:183], v[108:111]
	v_mfma_f32_16x16x32_bf16 v[104:107], v[164:167], v[180:183], v[104:107]
	v_mfma_f32_16x16x32_bf16 v[92:95], v[148:151], v[188:191], v[92:95]
	v_mfma_f32_16x16x32_bf16 v[88:91], v[164:167], v[188:191], v[88:91]
	v_mfma_f32_16x16x32_bf16 v[76:79], v[148:151], v[196:199], v[76:79]
	v_mfma_f32_16x16x32_bf16 v[72:75], v[164:167], v[196:199], v[72:75]
	s_barrier
	s_add_i32 s62, s86, s34
	v_add_u32_e32 v212, s97, v153
	v_lshl_add_u64 v[216:217], v[216:217], 0, s[8:9]
	s_mov_b32 m0, s62
	ds_read_b128 v[200:203], v212
	ds_read_b128 v[204:207], v212 offset:1024
	ds_read_b128 v[208:211], v212 offset:2048
	ds_read_b128 v[212:215], v212 offset:3072
	global_load_lds_dwordx4 v[216:217], off
	s_add_i32 m0, s62, 0x2000
	v_lshl_add_u64 v[216:217], v[218:219], 0, s[8:9]
	global_load_lds_dwordx4 v[216:217], off
	s_barrier
	s_waitcnt lgkmcnt(0)
	v_mfma_f32_16x16x32_bf16 v[116:119], v[200:203], v[168:171], v[116:119]
	v_mfma_f32_16x16x32_bf16 v[112:115], v[208:211], v[168:171], v[112:115]
	v_mfma_f32_16x16x32_bf16 v[100:103], v[200:203], v[176:179], v[100:103]
	v_mfma_f32_16x16x32_bf16 v[96:99], v[208:211], v[176:179], v[96:99]
	v_mfma_f32_16x16x32_bf16 v[84:87], v[200:203], v[184:187], v[84:87]
	v_mfma_f32_16x16x32_bf16 v[80:83], v[208:211], v[184:187], v[80:83]
	v_mfma_f32_16x16x32_bf16 v[68:71], v[200:203], v[192:195], v[68:71]
	v_mfma_f32_16x16x32_bf16 v[64:67], v[208:211], v[192:195], v[64:67]
	v_mfma_f32_16x16x32_bf16 v[116:119], v[204:207], v[172:175], v[116:119]
	v_mfma_f32_16x16x32_bf16 v[112:115], v[212:215], v[172:175], v[112:115]
	v_mfma_f32_16x16x32_bf16 v[100:103], v[204:207], v[180:183], v[100:103]
	v_mfma_f32_16x16x32_bf16 v[96:99], v[212:215], v[180:183], v[96:99]
	v_mfma_f32_16x16x32_bf16 v[84:87], v[204:207], v[188:191], v[84:87]
	v_mfma_f32_16x16x32_bf16 v[80:83], v[212:215], v[188:191], v[80:83]
	v_mfma_f32_16x16x32_bf16 v[68:71], v[204:207], v[196:199], v[68:71]
	v_mfma_f32_16x16x32_bf16 v[64:67], v[212:215], v[196:199], v[64:67]
	s_mov_b32 m0, s69
	v_lshl_add_u64 v[216:217], v[220:221], 0, s[8:9]
	s_barrier
	ds_read_b128 v[168:171], v158 offset:49152
	ds_read_b128 v[172:175], v158 offset:50176
	ds_read_b128 v[176:179], v158 offset:51200
	ds_read_b128 v[180:183], v158 offset:52224
	ds_read_b128 v[184:187], v158 offset:53248
	ds_read_b128 v[188:191], v158 offset:54272
	ds_read_b128 v[192:195], v158 offset:55296
	ds_read_b128 v[196:199], v158 offset:56320
	global_load_lds_dwordx4 v[216:217], off
	s_mov_b32 m0, s70
	v_lshl_add_u64 v[216:217], v[222:223], 0, s[8:9]
	global_load_lds_dwordx4 v[216:217], off
	s_barrier
	s_waitcnt lgkmcnt(0)
	v_mfma_f32_16x16x32_bf16 v[60:63], v[144:147], v[168:171], v[60:63]
	v_mfma_f32_16x16x32_bf16 v[56:59], v[160:163], v[168:171], v[56:59]
	v_mfma_f32_16x16x32_bf16 v[44:47], v[144:147], v[176:179], v[44:47]
	v_mfma_f32_16x16x32_bf16 v[40:43], v[160:163], v[176:179], v[40:43]
	v_mfma_f32_16x16x32_bf16 v[28:31], v[144:147], v[184:187], v[28:31]
	v_mfma_f32_16x16x32_bf16 v[24:27], v[160:163], v[184:187], v[24:27]
	v_mfma_f32_16x16x32_bf16 v[12:15], v[144:147], v[192:195], v[12:15]
	v_mfma_f32_16x16x32_bf16 v[8:11], v[160:163], v[192:195], v[8:11]
	v_mfma_f32_16x16x32_bf16 v[60:63], v[148:151], v[172:175], v[60:63]
	v_mfma_f32_16x16x32_bf16 v[56:59], v[164:167], v[172:175], v[56:59]
	v_mfma_f32_16x16x32_bf16 v[44:47], v[148:151], v[180:183], v[44:47]
	v_mfma_f32_16x16x32_bf16 v[40:43], v[164:167], v[180:183], v[40:43]
	v_mfma_f32_16x16x32_bf16 v[28:31], v[148:151], v[188:191], v[28:31]
	v_mfma_f32_16x16x32_bf16 v[24:27], v[164:167], v[188:191], v[24:27]
	v_mfma_f32_16x16x32_bf16 v[12:15], v[148:151], v[196:199], v[12:15]
	v_mfma_f32_16x16x32_bf16 v[8:11], v[164:167], v[196:199], v[8:11]
	s_barrier
	s_add_u32 s60, s60, 0x40080
	s_addc_u32 s61, s61, 0
	s_add_i32 s62, s97, s34
	s_mov_b32 m0, s62
	v_lshl_add_u64 v[144:145], s[60:61], 0, v[132:133]
	global_load_lds_dwordx4 v[144:145], off
	s_add_i32 m0, s62, 0x2000
	v_lshl_add_u64 v[144:145], s[60:61], 0, v[128:129]
	global_load_lds_dwordx4 v[144:145], off
	s_waitcnt vmcnt(6)
	s_barrier
	v_mfma_f32_16x16x32_bf16 v[52:55], v[200:203], v[168:171], v[52:55]
	v_mfma_f32_16x16x32_bf16 v[48:51], v[208:211], v[168:171], v[48:51]
	v_mfma_f32_16x16x32_bf16 v[36:39], v[200:203], v[176:179], v[36:39]
	v_mfma_f32_16x16x32_bf16 v[32:35], v[208:211], v[176:179], v[32:35]
	v_mfma_f32_16x16x32_bf16 v[20:23], v[200:203], v[184:187], v[20:23]
	v_mfma_f32_16x16x32_bf16 v[16:19], v[208:211], v[184:187], v[16:19]
	v_mfma_f32_16x16x32_bf16 v[4:7], v[200:203], v[192:195], v[4:7]
	v_mfma_f32_16x16x32_bf16 v[0:3], v[208:211], v[192:195], v[0:3]
	v_mfma_f32_16x16x32_bf16 v[52:55], v[204:207], v[172:175], v[52:55]
	v_mfma_f32_16x16x32_bf16 v[48:51], v[212:215], v[172:175], v[48:51]
	v_mfma_f32_16x16x32_bf16 v[36:39], v[204:207], v[180:183], v[36:39]
	v_mfma_f32_16x16x32_bf16 v[32:35], v[212:215], v[180:183], v[32:35]
	v_mfma_f32_16x16x32_bf16 v[20:23], v[204:207], v[188:191], v[20:23]
	v_mfma_f32_16x16x32_bf16 v[16:19], v[212:215], v[188:191], v[16:19]
	v_mfma_f32_16x16x32_bf16 v[4:7], v[204:207], v[196:199], v[4:7]
	v_mfma_f32_16x16x32_bf16 v[0:3], v[212:215], v[196:199], v[0:3]
	s_add_i32 s83, s83, 2
	s_add_u32 s58, s58, 0x100
	s_addc_u32 s59, s59, 0
	s_add_u32 s81, s81, 0x100
	s_addc_u32 s82, s82, 0
	s_cmp_gt_u32 s83, 13
	s_barrier
	s_cbranch_scc0 .LBB0_569
	v_lshl_or_b32 v146, s78, 8, v156
	v_ashrrev_i32_e32 v147, 31, v146
	v_lshl_add_u64 v[144:145], v[146:147], 2, s[44:45]
	global_load_dwordx4 v[160:163], v[144:145], off
	global_load_dwordx4 v[164:167], v[144:145], off offset:16
	v_lshl_add_u32 v148, s56, 8, v152
	v_ashrrev_i32_e32 v149, 31, v148
	v_lshlrev_b64 v[168:169], 12, v[148:149]
	v_lshlrev_b64 v[150:151], 1, v[146:147]
	v_lshl_add_u64 v[146:147], s[6:7], 0, v[168:169]
	v_lshl_add_u64 v[146:147], v[146:147], 0, v[150:151]
	s_mov_b32 s78, s48
	s_mov_b32 s56, s50
	s_mov_b64 s[60:61], s[54:55]
	s_mov_b64 s[58:59], s[52:53]
	s_waitcnt vmcnt(0)
	v_add_f32_e32 v124, v124, v160
	v_add_f32_e32 v120, v120, v164
	v_add_f32_e32 v125, v125, v161
	v_add_f32_e32 v121, v121, v165
	v_add_f32_e32 v126, v126, v162
	v_add_f32_e32 v122, v122, v166
	v_add_f32_e32 v127, v127, v163
	v_add_f32_e32 v123, v123, v167
	v_mul_f32_e32 v124, 0xbfb8aa3b, v124
	v_mul_f32_e32 v120, 0xbfb8aa3b, v120
	v_mul_f32_e32 v125, 0xbfb8aa3b, v125
	v_mul_f32_e32 v121, 0xbfb8aa3b, v121
	v_mul_f32_e32 v126, 0xbfb8aa3b, v126
	v_mul_f32_e32 v122, 0xbfb8aa3b, v122
	v_mul_f32_e32 v127, 0xbfb8aa3b, v127
	v_mul_f32_e32 v123, 0xbfb8aa3b, v123
	v_exp_f32_e32 v124, v124
	v_exp_f32_e32 v120, v120
	v_exp_f32_e32 v125, v125
	v_exp_f32_e32 v121, v121
	v_exp_f32_e32 v126, v126
	v_exp_f32_e32 v122, v122
	v_exp_f32_e32 v127, v127
	v_exp_f32_e32 v123, v123
	v_add_f32_e32 v124, 1.0, v124
	v_add_f32_e32 v120, 1.0, v120
	v_add_f32_e32 v125, 1.0, v125
	v_add_f32_e32 v121, 1.0, v121
	v_add_f32_e32 v126, 1.0, v126
	v_add_f32_e32 v122, 1.0, v122
	v_add_f32_e32 v127, 1.0, v127
	v_add_f32_e32 v123, 1.0, v123
	v_rcp_f32_e32 v124, v124
	v_rcp_f32_e32 v149, v120
	v_rcp_f32_e32 v120, v125
	v_rcp_f32_e32 v125, v121
	v_rcp_f32_e32 v121, v126
	v_rcp_f32_e32 v126, v127
	v_rcp_f32_e32 v127, v122
	v_rcp_f32_e32 v123, v123
	v_cvt_pk_bf16_f32 v120, v124, v120
	v_cvt_pk_bf16_f32 v121, v121, v126
	v_cvt_pk_bf16_f32 v122, v149, v125
	v_cvt_pk_bf16_f32 v123, v127, v123
	global_store_dwordx4 v[146:147], v[120:123], off
	global_load_dwordx4 v[120:123], v[144:145], off offset:512
	s_nop 0
	global_load_dwordx4 v[124:127], v[144:145], off offset:528
	s_waitcnt vmcnt(0)
	v_add_f32_e32 v116, v116, v120
	v_add_f32_e32 v112, v112, v124
	v_add_f32_e32 v117, v117, v121
	v_add_f32_e32 v113, v113, v125
	v_add_f32_e32 v118, v118, v122
	v_add_f32_e32 v114, v114, v126
	v_add_f32_e32 v119, v119, v123
	v_add_f32_e32 v115, v115, v127
	v_mul_f32_e32 v116, 0xbfb8aa3b, v116
	v_mul_f32_e32 v112, 0xbfb8aa3b, v112
	v_mul_f32_e32 v117, 0xbfb8aa3b, v117
	v_mul_f32_e32 v113, 0xbfb8aa3b, v113
	v_mul_f32_e32 v118, 0xbfb8aa3b, v118
	v_mul_f32_e32 v114, 0xbfb8aa3b, v114
	v_mul_f32_e32 v119, 0xbfb8aa3b, v119
	v_mul_f32_e32 v115, 0xbfb8aa3b, v115
	v_exp_f32_e32 v116, v116
	v_exp_f32_e32 v112, v112
	v_exp_f32_e32 v117, v117
	v_exp_f32_e32 v113, v113
	v_exp_f32_e32 v118, v118
	v_exp_f32_e32 v114, v114
	v_exp_f32_e32 v119, v119
	v_exp_f32_e32 v115, v115
	v_add_f32_e32 v116, 1.0, v116
	v_add_f32_e32 v112, 1.0, v112
	v_add_f32_e32 v117, 1.0, v117
	v_add_f32_e32 v113, 1.0, v113
	v_add_f32_e32 v118, 1.0, v118
	v_add_f32_e32 v114, 1.0, v114
	v_add_f32_e32 v119, 1.0, v119
	v_add_f32_e32 v115, 1.0, v115
	v_rcp_f32_e32 v116, v116
	v_rcp_f32_e32 v120, v112
	v_rcp_f32_e32 v112, v117
	v_rcp_f32_e32 v117, v113
	v_rcp_f32_e32 v113, v118
	v_rcp_f32_e32 v118, v119
	v_rcp_f32_e32 v119, v114
	v_rcp_f32_e32 v115, v115
	v_cvt_pk_bf16_f32 v112, v116, v112
	v_cvt_pk_bf16_f32 v113, v113, v118
	v_cvt_pk_bf16_f32 v114, v120, v117
	v_cvt_pk_bf16_f32 v115, v119, v115
	global_store_dwordx4 v[146:147], v[112:115], off offset:256
	global_load_dwordx4 v[112:115], v[144:145], off
	s_nop 0
	global_load_dwordx4 v[116:119], v[144:145], off offset:16
	v_or_b32_e32 v120, 16, v148
	v_ashrrev_i32_e32 v121, 31, v120
	v_lshlrev_b64 v[120:121], 12, v[120:121]
	v_lshl_add_u64 v[120:121], s[6:7], 0, v[120:121]
	v_lshl_add_u64 v[120:121], v[120:121], 0, v[150:151]
	s_waitcnt vmcnt(0)
	v_add_f32_e32 v108, v108, v112
	v_add_f32_e32 v104, v104, v116
	v_add_f32_e32 v109, v109, v113
	v_add_f32_e32 v105, v105, v117
	v_add_f32_e32 v110, v110, v114
	v_add_f32_e32 v106, v106, v118
	v_add_f32_e32 v111, v111, v115
	v_add_f32_e32 v107, v107, v119
	v_mul_f32_e32 v108, 0xbfb8aa3b, v108
	v_mul_f32_e32 v104, 0xbfb8aa3b, v104
	v_mul_f32_e32 v109, 0xbfb8aa3b, v109
	v_mul_f32_e32 v105, 0xbfb8aa3b, v105
	v_mul_f32_e32 v110, 0xbfb8aa3b, v110
	v_mul_f32_e32 v106, 0xbfb8aa3b, v106
	v_mul_f32_e32 v111, 0xbfb8aa3b, v111
	v_mul_f32_e32 v107, 0xbfb8aa3b, v107
	v_exp_f32_e32 v108, v108
	v_exp_f32_e32 v104, v104
	v_exp_f32_e32 v109, v109
	v_exp_f32_e32 v105, v105
	v_exp_f32_e32 v110, v110
	v_exp_f32_e32 v106, v106
	v_exp_f32_e32 v111, v111
	v_exp_f32_e32 v107, v107
	v_add_f32_e32 v108, 1.0, v108
	v_add_f32_e32 v104, 1.0, v104
	v_add_f32_e32 v109, 1.0, v109
	v_add_f32_e32 v105, 1.0, v105
	v_add_f32_e32 v110, 1.0, v110
	v_add_f32_e32 v106, 1.0, v106
	v_add_f32_e32 v111, 1.0, v111
	v_add_f32_e32 v107, 1.0, v107
	v_rcp_f32_e32 v108, v108
	v_rcp_f32_e32 v112, v104
	v_rcp_f32_e32 v104, v109
	v_rcp_f32_e32 v109, v105
	v_rcp_f32_e32 v105, v110
	v_rcp_f32_e32 v110, v111
	v_rcp_f32_e32 v111, v106
	v_rcp_f32_e32 v107, v107
	v_cvt_pk_bf16_f32 v104, v108, v104
	v_cvt_pk_bf16_f32 v105, v105, v110
	v_cvt_pk_bf16_f32 v106, v112, v109
	v_cvt_pk_bf16_f32 v107, v111, v107
	global_store_dwordx4 v[120:121], v[104:107], off
	global_load_dwordx4 v[104:107], v[144:145], off offset:512
	s_nop 0
	global_load_dwordx4 v[108:111], v[144:145], off offset:528
	s_waitcnt vmcnt(0)
	v_add_f32_e32 v100, v100, v104
	v_add_f32_e32 v96, v96, v108
	v_add_f32_e32 v101, v101, v105
	v_add_f32_e32 v97, v97, v109
	v_add_f32_e32 v102, v102, v106
	v_add_f32_e32 v98, v98, v110
	v_add_f32_e32 v103, v103, v107
	v_add_f32_e32 v99, v99, v111
	v_mul_f32_e32 v100, 0xbfb8aa3b, v100
	v_mul_f32_e32 v96, 0xbfb8aa3b, v96
	v_mul_f32_e32 v101, 0xbfb8aa3b, v101
	v_mul_f32_e32 v97, 0xbfb8aa3b, v97
	v_mul_f32_e32 v102, 0xbfb8aa3b, v102
	v_mul_f32_e32 v98, 0xbfb8aa3b, v98
	v_mul_f32_e32 v103, 0xbfb8aa3b, v103
	v_mul_f32_e32 v99, 0xbfb8aa3b, v99
	v_exp_f32_e32 v100, v100
	v_exp_f32_e32 v96, v96
	v_exp_f32_e32 v101, v101
	v_exp_f32_e32 v97, v97
	v_exp_f32_e32 v102, v102
	v_exp_f32_e32 v98, v98
	v_exp_f32_e32 v103, v103
	v_exp_f32_e32 v99, v99
	v_add_f32_e32 v100, 1.0, v100
	v_add_f32_e32 v96, 1.0, v96
	v_add_f32_e32 v101, 1.0, v101
	v_add_f32_e32 v97, 1.0, v97
	v_add_f32_e32 v102, 1.0, v102
	v_add_f32_e32 v98, 1.0, v98
	v_add_f32_e32 v103, 1.0, v103
	v_add_f32_e32 v99, 1.0, v99
	v_rcp_f32_e32 v100, v100
	v_rcp_f32_e32 v104, v96
	v_rcp_f32_e32 v96, v101
	v_rcp_f32_e32 v101, v97
	v_rcp_f32_e32 v97, v102
	v_rcp_f32_e32 v102, v103
	v_rcp_f32_e32 v103, v98
	v_rcp_f32_e32 v99, v99
	v_cvt_pk_bf16_f32 v96, v100, v96
	v_cvt_pk_bf16_f32 v97, v97, v102
	v_cvt_pk_bf16_f32 v98, v104, v101
	v_cvt_pk_bf16_f32 v99, v103, v99
	global_store_dwordx4 v[120:121], v[96:99], off offset:256
	global_load_dwordx4 v[96:99], v[144:145], off
	s_nop 0
	global_load_dwordx4 v[100:103], v[144:145], off offset:16
	v_or_b32_e32 v104, 32, v148
	v_ashrrev_i32_e32 v105, 31, v104
	v_lshlrev_b64 v[104:105], 12, v[104:105]
	v_lshl_add_u64 v[104:105], s[6:7], 0, v[104:105]
	v_lshl_add_u64 v[104:105], v[104:105], 0, v[150:151]
	s_waitcnt vmcnt(0)
	v_add_f32_e32 v92, v92, v96
	v_add_f32_e32 v88, v88, v100
	v_add_f32_e32 v93, v93, v97
	v_add_f32_e32 v89, v89, v101
	v_add_f32_e32 v94, v94, v98
	v_add_f32_e32 v90, v90, v102
	v_add_f32_e32 v95, v95, v99
	v_add_f32_e32 v91, v91, v103
	v_mul_f32_e32 v92, 0xbfb8aa3b, v92
	v_mul_f32_e32 v88, 0xbfb8aa3b, v88
	v_mul_f32_e32 v93, 0xbfb8aa3b, v93
	v_mul_f32_e32 v89, 0xbfb8aa3b, v89
	v_mul_f32_e32 v94, 0xbfb8aa3b, v94
	v_mul_f32_e32 v90, 0xbfb8aa3b, v90
	v_mul_f32_e32 v95, 0xbfb8aa3b, v95
	v_mul_f32_e32 v91, 0xbfb8aa3b, v91
	v_exp_f32_e32 v92, v92
	v_exp_f32_e32 v88, v88
	v_exp_f32_e32 v93, v93
	v_exp_f32_e32 v89, v89
	v_exp_f32_e32 v94, v94
	v_exp_f32_e32 v90, v90
	v_exp_f32_e32 v95, v95
	v_exp_f32_e32 v91, v91
	v_add_f32_e32 v92, 1.0, v92
	v_add_f32_e32 v88, 1.0, v88
	v_add_f32_e32 v93, 1.0, v93
	v_add_f32_e32 v89, 1.0, v89
	v_add_f32_e32 v94, 1.0, v94
	v_add_f32_e32 v90, 1.0, v90
	v_add_f32_e32 v95, 1.0, v95
	v_add_f32_e32 v91, 1.0, v91
	v_rcp_f32_e32 v92, v92
	v_rcp_f32_e32 v96, v88
	v_rcp_f32_e32 v88, v93
	v_rcp_f32_e32 v93, v89
	v_rcp_f32_e32 v89, v94
	v_rcp_f32_e32 v94, v95
	v_rcp_f32_e32 v95, v90
	v_rcp_f32_e32 v91, v91
	v_cvt_pk_bf16_f32 v88, v92, v88
	v_cvt_pk_bf16_f32 v89, v89, v94
	v_cvt_pk_bf16_f32 v90, v96, v93
	v_cvt_pk_bf16_f32 v91, v95, v91
	global_store_dwordx4 v[104:105], v[88:91], off
	global_load_dwordx4 v[88:91], v[144:145], off offset:512
	s_nop 0
	global_load_dwordx4 v[92:95], v[144:145], off offset:528
	s_waitcnt vmcnt(0)
	v_add_f32_e32 v84, v84, v88
	v_add_f32_e32 v80, v80, v92
	v_add_f32_e32 v85, v85, v89
	v_add_f32_e32 v81, v81, v93
	v_add_f32_e32 v86, v86, v90
	v_add_f32_e32 v82, v82, v94
	v_add_f32_e32 v87, v87, v91
	v_add_f32_e32 v83, v83, v95
	v_mul_f32_e32 v84, 0xbfb8aa3b, v84
	v_mul_f32_e32 v80, 0xbfb8aa3b, v80
	v_mul_f32_e32 v85, 0xbfb8aa3b, v85
	v_mul_f32_e32 v81, 0xbfb8aa3b, v81
	v_mul_f32_e32 v86, 0xbfb8aa3b, v86
	v_mul_f32_e32 v82, 0xbfb8aa3b, v82
	v_mul_f32_e32 v87, 0xbfb8aa3b, v87
	v_mul_f32_e32 v83, 0xbfb8aa3b, v83
	v_exp_f32_e32 v84, v84
	v_exp_f32_e32 v80, v80
	v_exp_f32_e32 v85, v85
	v_exp_f32_e32 v81, v81
	v_exp_f32_e32 v86, v86
	v_exp_f32_e32 v82, v82
	v_exp_f32_e32 v87, v87
	v_exp_f32_e32 v83, v83
	v_add_f32_e32 v84, 1.0, v84
	v_add_f32_e32 v80, 1.0, v80
	v_add_f32_e32 v85, 1.0, v85
	v_add_f32_e32 v81, 1.0, v81
	v_add_f32_e32 v86, 1.0, v86
	v_add_f32_e32 v82, 1.0, v82
	v_add_f32_e32 v87, 1.0, v87
	v_add_f32_e32 v83, 1.0, v83
	v_rcp_f32_e32 v84, v84
	v_rcp_f32_e32 v88, v80
	v_rcp_f32_e32 v80, v85
	v_rcp_f32_e32 v85, v81
	v_rcp_f32_e32 v81, v86
	v_rcp_f32_e32 v86, v87
	v_rcp_f32_e32 v87, v82
	v_rcp_f32_e32 v83, v83
	v_cvt_pk_bf16_f32 v80, v84, v80
	v_cvt_pk_bf16_f32 v81, v81, v86
	v_cvt_pk_bf16_f32 v82, v88, v85
	v_cvt_pk_bf16_f32 v83, v87, v83
	global_store_dwordx4 v[104:105], v[80:83], off offset:256
	global_load_dwordx4 v[80:83], v[144:145], off
	s_nop 0
	global_load_dwordx4 v[84:87], v[144:145], off offset:16
	v_or_b32_e32 v88, 48, v148
	v_ashrrev_i32_e32 v89, 31, v88
	v_lshlrev_b64 v[88:89], 12, v[88:89]
	v_lshl_add_u64 v[88:89], s[6:7], 0, v[88:89]
	v_lshl_add_u64 v[88:89], v[88:89], 0, v[150:151]
	s_waitcnt vmcnt(0)
	v_add_f32_e32 v76, v76, v80
	v_add_f32_e32 v72, v72, v84
	v_add_f32_e32 v77, v77, v81
	v_add_f32_e32 v73, v73, v85
	v_add_f32_e32 v78, v78, v82
	v_add_f32_e32 v74, v74, v86
	v_add_f32_e32 v79, v79, v83
	v_add_f32_e32 v75, v75, v87
	v_mul_f32_e32 v76, 0xbfb8aa3b, v76
	v_mul_f32_e32 v72, 0xbfb8aa3b, v72
	v_mul_f32_e32 v77, 0xbfb8aa3b, v77
	v_mul_f32_e32 v73, 0xbfb8aa3b, v73
	v_mul_f32_e32 v78, 0xbfb8aa3b, v78
	v_mul_f32_e32 v74, 0xbfb8aa3b, v74
	v_mul_f32_e32 v79, 0xbfb8aa3b, v79
	v_mul_f32_e32 v75, 0xbfb8aa3b, v75
	v_exp_f32_e32 v76, v76
	v_exp_f32_e32 v72, v72
	v_exp_f32_e32 v77, v77
	v_exp_f32_e32 v73, v73
	v_exp_f32_e32 v78, v78
	v_exp_f32_e32 v74, v74
	v_exp_f32_e32 v79, v79
	v_exp_f32_e32 v75, v75
	v_add_f32_e32 v76, 1.0, v76
	v_add_f32_e32 v72, 1.0, v72
	v_add_f32_e32 v77, 1.0, v77
	v_add_f32_e32 v73, 1.0, v73
	v_add_f32_e32 v78, 1.0, v78
	v_add_f32_e32 v74, 1.0, v74
	v_add_f32_e32 v79, 1.0, v79
	v_add_f32_e32 v75, 1.0, v75
	v_rcp_f32_e32 v76, v76
	v_rcp_f32_e32 v80, v72
	v_rcp_f32_e32 v72, v77
	v_rcp_f32_e32 v77, v73
	v_rcp_f32_e32 v73, v78
	v_rcp_f32_e32 v78, v79
	v_rcp_f32_e32 v79, v74
	v_rcp_f32_e32 v75, v75
	v_cvt_pk_bf16_f32 v72, v76, v72
	v_cvt_pk_bf16_f32 v73, v73, v78
	v_cvt_pk_bf16_f32 v74, v80, v77
	v_cvt_pk_bf16_f32 v75, v79, v75
	global_store_dwordx4 v[88:89], v[72:75], off
	global_load_dwordx4 v[72:75], v[144:145], off offset:512
	s_nop 0
	global_load_dwordx4 v[76:79], v[144:145], off offset:528
	s_waitcnt vmcnt(0)
	v_add_f32_e32 v68, v68, v72
	v_add_f32_e32 v64, v64, v76
	v_add_f32_e32 v69, v69, v73
	v_add_f32_e32 v65, v65, v77
	v_add_f32_e32 v70, v70, v74
	v_add_f32_e32 v66, v66, v78
	v_add_f32_e32 v71, v71, v75
	v_add_f32_e32 v67, v67, v79
	v_mul_f32_e32 v68, 0xbfb8aa3b, v68
	v_mul_f32_e32 v64, 0xbfb8aa3b, v64
	v_mul_f32_e32 v69, 0xbfb8aa3b, v69
	v_mul_f32_e32 v65, 0xbfb8aa3b, v65
	v_mul_f32_e32 v70, 0xbfb8aa3b, v70
	v_mul_f32_e32 v66, 0xbfb8aa3b, v66
	v_mul_f32_e32 v71, 0xbfb8aa3b, v71
	v_mul_f32_e32 v67, 0xbfb8aa3b, v67
	v_exp_f32_e32 v68, v68
	v_exp_f32_e32 v64, v64
	v_exp_f32_e32 v69, v69
	v_exp_f32_e32 v65, v65
	v_exp_f32_e32 v70, v70
	v_exp_f32_e32 v66, v66
	v_exp_f32_e32 v71, v71
	v_exp_f32_e32 v67, v67
	v_add_f32_e32 v68, 1.0, v68
	v_add_f32_e32 v64, 1.0, v64
	v_add_f32_e32 v69, 1.0, v69
	v_add_f32_e32 v65, 1.0, v65
	v_add_f32_e32 v70, 1.0, v70
	v_add_f32_e32 v66, 1.0, v66
	v_add_f32_e32 v71, 1.0, v71
	v_add_f32_e32 v67, 1.0, v67
	v_rcp_f32_e32 v68, v68
	v_rcp_f32_e32 v72, v64
	v_rcp_f32_e32 v64, v69
	v_rcp_f32_e32 v69, v65
	v_rcp_f32_e32 v65, v70
	v_rcp_f32_e32 v70, v71
	v_rcp_f32_e32 v71, v66
	v_rcp_f32_e32 v67, v67
	v_cvt_pk_bf16_f32 v64, v68, v64
	v_cvt_pk_bf16_f32 v65, v65, v70
	v_cvt_pk_bf16_f32 v66, v72, v69
	v_cvt_pk_bf16_f32 v67, v71, v67
	global_store_dwordx4 v[88:89], v[64:67], off offset:256
	global_load_dwordx4 v[64:67], v[144:145], off
	s_nop 0
	global_load_dwordx4 v[68:71], v[144:145], off offset:16
	v_add_co_u32_e32 v72, vcc, s74, v146
	s_waitcnt vmcnt(0)
	v_add_f32_e32 v60, v60, v64
	v_add_f32_e32 v56, v56, v68
	v_add_f32_e32 v61, v61, v65
	v_add_f32_e32 v57, v57, v69
	v_add_f32_e32 v62, v62, v66
	v_add_f32_e32 v58, v58, v70
	v_add_f32_e32 v63, v63, v67
	v_add_f32_e32 v59, v59, v71
	v_mul_f32_e32 v60, 0xbfb8aa3b, v60
	v_mul_f32_e32 v56, 0xbfb8aa3b, v56
	v_mul_f32_e32 v61, 0xbfb8aa3b, v61
	v_mul_f32_e32 v57, 0xbfb8aa3b, v57
	v_mul_f32_e32 v62, 0xbfb8aa3b, v62
	v_mul_f32_e32 v58, 0xbfb8aa3b, v58
	v_mul_f32_e32 v63, 0xbfb8aa3b, v63
	v_mul_f32_e32 v59, 0xbfb8aa3b, v59
	v_exp_f32_e32 v60, v60
	v_exp_f32_e32 v56, v56
	v_exp_f32_e32 v61, v61
	v_exp_f32_e32 v57, v57
	v_exp_f32_e32 v62, v62
	v_exp_f32_e32 v58, v58
	v_exp_f32_e32 v63, v63
	v_exp_f32_e32 v59, v59
	v_add_f32_e32 v60, 1.0, v60
	v_add_f32_e32 v56, 1.0, v56
	v_add_f32_e32 v61, 1.0, v61
	v_add_f32_e32 v57, 1.0, v57
	v_add_f32_e32 v62, 1.0, v62
	v_add_f32_e32 v58, 1.0, v58
	v_add_f32_e32 v63, 1.0, v63
	v_add_f32_e32 v59, 1.0, v59
	v_rcp_f32_e32 v60, v60
	v_rcp_f32_e32 v64, v56
	v_rcp_f32_e32 v56, v61
	v_rcp_f32_e32 v61, v57
	v_rcp_f32_e32 v57, v62
	v_rcp_f32_e32 v62, v63
	v_rcp_f32_e32 v63, v58
	v_rcp_f32_e32 v59, v59
	v_addc_co_u32_e32 v73, vcc, 0, v147, vcc
	v_cvt_pk_bf16_f32 v56, v60, v56
	v_cvt_pk_bf16_f32 v57, v57, v62
	v_cvt_pk_bf16_f32 v58, v64, v61
	v_cvt_pk_bf16_f32 v59, v63, v59
	global_store_dwordx4 v[72:73], v[56:59], off
	global_load_dwordx4 v[56:59], v[144:145], off offset:512
	s_nop 0
	global_load_dwordx4 v[60:63], v[144:145], off offset:528
	v_lshl_add_u64 v[64:65], v[146:147], 0, s[14:15]
	s_waitcnt vmcnt(0)
	v_add_f32_e32 v52, v52, v56
	v_add_f32_e32 v48, v48, v60
	v_add_f32_e32 v53, v53, v57
	v_add_f32_e32 v49, v49, v61
	v_add_f32_e32 v54, v54, v58
	v_add_f32_e32 v50, v50, v62
	v_add_f32_e32 v55, v55, v59
	v_add_f32_e32 v51, v51, v63
	v_mul_f32_e32 v52, 0xbfb8aa3b, v52
	v_mul_f32_e32 v48, 0xbfb8aa3b, v48
	v_mul_f32_e32 v53, 0xbfb8aa3b, v53
	v_mul_f32_e32 v49, 0xbfb8aa3b, v49
	v_mul_f32_e32 v54, 0xbfb8aa3b, v54
	v_mul_f32_e32 v50, 0xbfb8aa3b, v50
	v_mul_f32_e32 v55, 0xbfb8aa3b, v55
	v_mul_f32_e32 v51, 0xbfb8aa3b, v51
	v_exp_f32_e32 v52, v52
	v_exp_f32_e32 v48, v48
	v_exp_f32_e32 v53, v53
	v_exp_f32_e32 v49, v49
	v_exp_f32_e32 v54, v54
	v_exp_f32_e32 v50, v50
	v_exp_f32_e32 v55, v55
	v_exp_f32_e32 v51, v51
	v_add_f32_e32 v52, 1.0, v52
	v_add_f32_e32 v48, 1.0, v48
	v_add_f32_e32 v53, 1.0, v53
	v_add_f32_e32 v49, 1.0, v49
	v_add_f32_e32 v54, 1.0, v54
	v_add_f32_e32 v50, 1.0, v50
	v_add_f32_e32 v55, 1.0, v55
	v_add_f32_e32 v51, 1.0, v51
	v_rcp_f32_e32 v52, v52
	v_rcp_f32_e32 v56, v48
	v_rcp_f32_e32 v48, v53
	v_rcp_f32_e32 v53, v49
	v_rcp_f32_e32 v49, v54
	v_rcp_f32_e32 v54, v55
	v_rcp_f32_e32 v55, v50
	v_rcp_f32_e32 v51, v51
	v_cvt_pk_bf16_f32 v48, v52, v48
	v_cvt_pk_bf16_f32 v49, v49, v54
	v_cvt_pk_bf16_f32 v50, v56, v53
	v_cvt_pk_bf16_f32 v51, v55, v51
	global_store_dwordx4 v[64:65], v[48:51], off offset:256
	global_load_dwordx4 v[48:51], v[144:145], off
	s_nop 0
	global_load_dwordx4 v[52:55], v[144:145], off offset:16
	v_add_co_u32_e32 v56, vcc, s75, v146
	s_waitcnt vmcnt(0)
	v_add_f32_e32 v44, v44, v48
	v_add_f32_e32 v40, v40, v52
	v_add_f32_e32 v45, v45, v49
	v_add_f32_e32 v41, v41, v53
	v_add_f32_e32 v46, v46, v50
	v_add_f32_e32 v42, v42, v54
	v_add_f32_e32 v47, v47, v51
	v_add_f32_e32 v43, v43, v55
	v_mul_f32_e32 v44, 0xbfb8aa3b, v44
	v_mul_f32_e32 v40, 0xbfb8aa3b, v40
	v_mul_f32_e32 v45, 0xbfb8aa3b, v45
	v_mul_f32_e32 v41, 0xbfb8aa3b, v41
	v_mul_f32_e32 v46, 0xbfb8aa3b, v46
	v_mul_f32_e32 v42, 0xbfb8aa3b, v42
	v_mul_f32_e32 v47, 0xbfb8aa3b, v47
	v_mul_f32_e32 v43, 0xbfb8aa3b, v43
	v_exp_f32_e32 v44, v44
	v_exp_f32_e32 v40, v40
	v_exp_f32_e32 v45, v45
	v_exp_f32_e32 v41, v41
	v_exp_f32_e32 v46, v46
	v_exp_f32_e32 v42, v42
	v_exp_f32_e32 v47, v47
	v_exp_f32_e32 v43, v43
	v_add_f32_e32 v44, 1.0, v44
	v_add_f32_e32 v40, 1.0, v40
	v_add_f32_e32 v45, 1.0, v45
	v_add_f32_e32 v41, 1.0, v41
	v_add_f32_e32 v46, 1.0, v46
	v_add_f32_e32 v42, 1.0, v42
	v_add_f32_e32 v47, 1.0, v47
	v_add_f32_e32 v43, 1.0, v43
	v_rcp_f32_e32 v44, v44
	v_rcp_f32_e32 v48, v40
	v_rcp_f32_e32 v40, v45
	v_rcp_f32_e32 v45, v41
	v_rcp_f32_e32 v41, v46
	v_rcp_f32_e32 v46, v47
	v_rcp_f32_e32 v47, v42
	v_rcp_f32_e32 v43, v43
	v_addc_co_u32_e32 v57, vcc, 0, v147, vcc
	v_cvt_pk_bf16_f32 v40, v44, v40
	v_cvt_pk_bf16_f32 v41, v41, v46
	v_cvt_pk_bf16_f32 v42, v48, v45
	v_cvt_pk_bf16_f32 v43, v47, v43
	global_store_dwordx4 v[56:57], v[40:43], off
	global_load_dwordx4 v[40:43], v[144:145], off offset:512
	s_nop 0
	global_load_dwordx4 v[44:47], v[144:145], off offset:528
	v_lshl_add_u64 v[48:49], v[146:147], 0, s[24:25]
	s_waitcnt vmcnt(0)
	v_add_f32_e32 v36, v36, v40
	v_add_f32_e32 v32, v32, v44
	v_add_f32_e32 v37, v37, v41
	v_add_f32_e32 v33, v33, v45
	v_add_f32_e32 v38, v38, v42
	v_add_f32_e32 v34, v34, v46
	v_add_f32_e32 v39, v39, v43
	v_add_f32_e32 v35, v35, v47
	v_mul_f32_e32 v36, 0xbfb8aa3b, v36
	v_mul_f32_e32 v32, 0xbfb8aa3b, v32
	v_mul_f32_e32 v37, 0xbfb8aa3b, v37
	v_mul_f32_e32 v33, 0xbfb8aa3b, v33
	v_mul_f32_e32 v38, 0xbfb8aa3b, v38
	v_mul_f32_e32 v34, 0xbfb8aa3b, v34
	v_mul_f32_e32 v39, 0xbfb8aa3b, v39
	v_mul_f32_e32 v35, 0xbfb8aa3b, v35
	v_exp_f32_e32 v36, v36
	v_exp_f32_e32 v32, v32
	v_exp_f32_e32 v37, v37
	v_exp_f32_e32 v33, v33
	v_exp_f32_e32 v38, v38
	v_exp_f32_e32 v34, v34
	v_exp_f32_e32 v39, v39
	v_exp_f32_e32 v35, v35
	v_add_f32_e32 v36, 1.0, v36
	v_add_f32_e32 v32, 1.0, v32
	v_add_f32_e32 v37, 1.0, v37
	v_add_f32_e32 v33, 1.0, v33
	v_add_f32_e32 v38, 1.0, v38
	v_add_f32_e32 v34, 1.0, v34
	v_add_f32_e32 v39, 1.0, v39
	v_add_f32_e32 v35, 1.0, v35
	v_rcp_f32_e32 v36, v36
	v_rcp_f32_e32 v40, v32
	v_rcp_f32_e32 v32, v37
	v_rcp_f32_e32 v37, v33
	v_rcp_f32_e32 v33, v38
	v_rcp_f32_e32 v38, v39
	v_rcp_f32_e32 v39, v34
	v_rcp_f32_e32 v35, v35
	v_cvt_pk_bf16_f32 v32, v36, v32
	v_cvt_pk_bf16_f32 v33, v33, v38
	v_cvt_pk_bf16_f32 v34, v40, v37
	v_cvt_pk_bf16_f32 v35, v39, v35
	global_store_dwordx4 v[48:49], v[32:35], off offset:256
	global_load_dwordx4 v[32:35], v[144:145], off
	s_nop 0
	global_load_dwordx4 v[36:39], v[144:145], off offset:16
	v_add_co_u32_e32 v40, vcc, s76, v146
	s_waitcnt vmcnt(0)
	v_add_f32_e32 v28, v28, v32
	v_add_f32_e32 v24, v24, v36
	v_add_f32_e32 v29, v29, v33
	v_add_f32_e32 v25, v25, v37
	v_add_f32_e32 v30, v30, v34
	v_add_f32_e32 v26, v26, v38
	v_add_f32_e32 v31, v31, v35
	v_add_f32_e32 v27, v27, v39
	v_mul_f32_e32 v28, 0xbfb8aa3b, v28
	v_mul_f32_e32 v24, 0xbfb8aa3b, v24
	v_mul_f32_e32 v29, 0xbfb8aa3b, v29
	v_mul_f32_e32 v25, 0xbfb8aa3b, v25
	v_mul_f32_e32 v30, 0xbfb8aa3b, v30
	v_mul_f32_e32 v26, 0xbfb8aa3b, v26
	v_mul_f32_e32 v31, 0xbfb8aa3b, v31
	v_mul_f32_e32 v27, 0xbfb8aa3b, v27
	v_exp_f32_e32 v28, v28
	v_exp_f32_e32 v24, v24
	v_exp_f32_e32 v29, v29
	v_exp_f32_e32 v25, v25
	v_exp_f32_e32 v30, v30
	v_exp_f32_e32 v26, v26
	v_exp_f32_e32 v31, v31
	v_exp_f32_e32 v27, v27
	v_add_f32_e32 v28, 1.0, v28
	v_add_f32_e32 v24, 1.0, v24
	v_add_f32_e32 v29, 1.0, v29
	v_add_f32_e32 v25, 1.0, v25
	v_add_f32_e32 v30, 1.0, v30
	v_add_f32_e32 v26, 1.0, v26
	v_add_f32_e32 v31, 1.0, v31
	v_add_f32_e32 v27, 1.0, v27
	v_rcp_f32_e32 v28, v28
	v_rcp_f32_e32 v32, v24
	v_rcp_f32_e32 v24, v29
	v_rcp_f32_e32 v29, v25
	v_rcp_f32_e32 v25, v30
	v_rcp_f32_e32 v30, v31
	v_rcp_f32_e32 v31, v26
	v_rcp_f32_e32 v27, v27
	v_addc_co_u32_e32 v41, vcc, 0, v147, vcc
	v_cvt_pk_bf16_f32 v24, v28, v24
	v_cvt_pk_bf16_f32 v25, v25, v30
	v_cvt_pk_bf16_f32 v26, v32, v29
	v_cvt_pk_bf16_f32 v27, v31, v27
	global_store_dwordx4 v[40:41], v[24:27], off
	global_load_dwordx4 v[24:27], v[144:145], off offset:512
	s_nop 0
	global_load_dwordx4 v[28:31], v[144:145], off offset:528
	v_lshl_add_u64 v[32:33], v[146:147], 0, s[40:41]
	s_waitcnt vmcnt(0)
	v_add_f32_e32 v20, v20, v24
	v_add_f32_e32 v16, v16, v28
	v_add_f32_e32 v21, v21, v25
	v_add_f32_e32 v17, v17, v29
	v_add_f32_e32 v22, v22, v26
	v_add_f32_e32 v18, v18, v30
	v_add_f32_e32 v23, v23, v27
	v_add_f32_e32 v19, v19, v31
	v_mul_f32_e32 v20, 0xbfb8aa3b, v20
	v_mul_f32_e32 v16, 0xbfb8aa3b, v16
	v_mul_f32_e32 v21, 0xbfb8aa3b, v21
	v_mul_f32_e32 v17, 0xbfb8aa3b, v17
	v_mul_f32_e32 v22, 0xbfb8aa3b, v22
	v_mul_f32_e32 v18, 0xbfb8aa3b, v18
	v_mul_f32_e32 v23, 0xbfb8aa3b, v23
	v_mul_f32_e32 v19, 0xbfb8aa3b, v19
	v_exp_f32_e32 v20, v20
	v_exp_f32_e32 v16, v16
	v_exp_f32_e32 v21, v21
	v_exp_f32_e32 v17, v17
	v_exp_f32_e32 v22, v22
	v_exp_f32_e32 v18, v18
	v_exp_f32_e32 v23, v23
	v_exp_f32_e32 v19, v19
	v_add_f32_e32 v20, 1.0, v20
	v_add_f32_e32 v16, 1.0, v16
	v_add_f32_e32 v21, 1.0, v21
	v_add_f32_e32 v17, 1.0, v17
	v_add_f32_e32 v22, 1.0, v22
	v_add_f32_e32 v18, 1.0, v18
	v_add_f32_e32 v23, 1.0, v23
	v_add_f32_e32 v19, 1.0, v19
	v_rcp_f32_e32 v20, v20
	v_rcp_f32_e32 v24, v16
	v_rcp_f32_e32 v16, v21
	v_rcp_f32_e32 v21, v17
	v_rcp_f32_e32 v17, v22
	v_rcp_f32_e32 v22, v23
	v_rcp_f32_e32 v23, v18
	v_rcp_f32_e32 v19, v19
	v_cvt_pk_bf16_f32 v16, v20, v16
	v_cvt_pk_bf16_f32 v17, v17, v22
	v_cvt_pk_bf16_f32 v18, v24, v21
	v_cvt_pk_bf16_f32 v19, v23, v19
	global_store_dwordx4 v[32:33], v[16:19], off offset:256
	global_load_dwordx4 v[16:19], v[144:145], off
	s_nop 0
	global_load_dwordx4 v[20:23], v[144:145], off offset:16
	v_add_co_u32_e32 v24, vcc, s77, v146
	s_waitcnt vmcnt(0)
	v_add_f32_e32 v12, v12, v16
	v_add_f32_e32 v8, v8, v20
	v_add_f32_e32 v13, v13, v17
	v_add_f32_e32 v9, v9, v21
	v_add_f32_e32 v14, v14, v18
	v_add_f32_e32 v10, v10, v22
	v_add_f32_e32 v15, v15, v19
	v_add_f32_e32 v11, v11, v23
	v_mul_f32_e32 v12, 0xbfb8aa3b, v12
	v_mul_f32_e32 v8, 0xbfb8aa3b, v8
	v_mul_f32_e32 v13, 0xbfb8aa3b, v13
	v_mul_f32_e32 v9, 0xbfb8aa3b, v9
	v_mul_f32_e32 v14, 0xbfb8aa3b, v14
	v_mul_f32_e32 v10, 0xbfb8aa3b, v10
	v_mul_f32_e32 v15, 0xbfb8aa3b, v15
	v_mul_f32_e32 v11, 0xbfb8aa3b, v11
	v_exp_f32_e32 v12, v12
	v_exp_f32_e32 v8, v8
	v_exp_f32_e32 v13, v13
	v_exp_f32_e32 v9, v9
	v_exp_f32_e32 v14, v14
	v_exp_f32_e32 v10, v10
	v_exp_f32_e32 v15, v15
	v_exp_f32_e32 v11, v11
	v_add_f32_e32 v12, 1.0, v12
	v_add_f32_e32 v8, 1.0, v8
	v_add_f32_e32 v13, 1.0, v13
	v_add_f32_e32 v9, 1.0, v9
	v_add_f32_e32 v14, 1.0, v14
	v_add_f32_e32 v10, 1.0, v10
	v_add_f32_e32 v15, 1.0, v15
	v_add_f32_e32 v11, 1.0, v11
	v_rcp_f32_e32 v12, v12
	v_rcp_f32_e32 v16, v8
	v_rcp_f32_e32 v8, v13
	v_rcp_f32_e32 v13, v9
	v_rcp_f32_e32 v9, v14
	v_rcp_f32_e32 v14, v15
	v_rcp_f32_e32 v15, v10
	v_rcp_f32_e32 v11, v11
	v_addc_co_u32_e32 v25, vcc, 0, v147, vcc
	v_cvt_pk_bf16_f32 v8, v12, v8
	v_cvt_pk_bf16_f32 v9, v9, v14
	v_cvt_pk_bf16_f32 v10, v16, v13
	v_cvt_pk_bf16_f32 v11, v15, v11
	global_store_dwordx4 v[24:25], v[8:11], off
	global_load_dwordx4 v[8:11], v[144:145], off offset:512
	s_nop 0
	global_load_dwordx4 v[12:15], v[144:145], off offset:528
	s_and_b64 vcc, exec, s[4:5]
	v_lshl_add_u64 v[16:17], v[146:147], 0, s[46:47]
	s_waitcnt vmcnt(0)
	v_add_f32_e32 v4, v4, v8
	v_add_f32_e32 v0, v0, v12
	v_add_f32_e32 v5, v5, v9
	v_add_f32_e32 v1, v1, v13
	v_add_f32_e32 v6, v6, v10
	v_add_f32_e32 v2, v2, v14
	v_add_f32_e32 v7, v7, v11
	v_add_f32_e32 v3, v3, v15
	v_mul_f32_e32 v4, 0xbfb8aa3b, v4
	v_mul_f32_e32 v0, 0xbfb8aa3b, v0
	v_mul_f32_e32 v5, 0xbfb8aa3b, v5
	v_mul_f32_e32 v1, 0xbfb8aa3b, v1
	v_mul_f32_e32 v6, 0xbfb8aa3b, v6
	v_mul_f32_e32 v2, 0xbfb8aa3b, v2
	v_mul_f32_e32 v7, 0xbfb8aa3b, v7
	v_mul_f32_e32 v3, 0xbfb8aa3b, v3
	v_exp_f32_e32 v4, v4
	v_exp_f32_e32 v0, v0
	v_exp_f32_e32 v5, v5
	v_exp_f32_e32 v1, v1
	v_exp_f32_e32 v6, v6
	v_exp_f32_e32 v2, v2
	v_exp_f32_e32 v7, v7
	v_exp_f32_e32 v3, v3
	v_add_f32_e32 v4, 1.0, v4
	v_add_f32_e32 v0, 1.0, v0
	v_add_f32_e32 v5, 1.0, v5
	v_add_f32_e32 v1, 1.0, v1
	v_add_f32_e32 v6, 1.0, v6
	v_add_f32_e32 v2, 1.0, v2
	v_add_f32_e32 v7, 1.0, v7
	v_add_f32_e32 v3, 1.0, v3
	v_rcp_f32_e32 v4, v4
	v_rcp_f32_e32 v8, v0
	v_rcp_f32_e32 v0, v5
	v_rcp_f32_e32 v5, v1
	v_rcp_f32_e32 v1, v6
	v_rcp_f32_e32 v6, v7
	v_rcp_f32_e32 v7, v2
	v_rcp_f32_e32 v3, v3
	v_cvt_pk_bf16_f32 v0, v4, v0
	v_cvt_pk_bf16_f32 v1, v1, v6
	v_cvt_pk_bf16_f32 v2, v8, v5
	v_cvt_pk_bf16_f32 v3, v7, v3
	global_store_dwordx4 v[16:17], v[0:3], off offset:256
	s_cbranch_vccz .LBB0_566
	s_waitcnt vmcnt(0)
	v_readlane_b32 s78, v228, 33
	s_cmpk_gt_u32 s0, 0xff
	v_readlane_b32 s76, v228, 32
	v_readlane_b32 s79, v228, 34
	v_readlane_b32 s77, v228, 35
	s_cbranch_scc1 .LBB0_573
	s_barrier

.LBB0_591:
	ds_read_b128 v[144:147], v151
	ds_read_b128 v[156:159], v151 offset:1024
	ds_read_b128 v[160:163], v151 offset:2048
	ds_read_b128 v[164:167], v151 offset:3072
	s_add_u32 s52, s50, 0xfffe0080
	s_addc_u32 s53, s51, -1
	s_cmp_eq_u32 s68, 4
	s_cselect_b32 s55, s41, s53
	s_cselect_b32 s54, s64, s52
	s_cselect_b32 s53, s25, s67
	s_cselect_b32 s52, s65, s66
	v_lshl_add_u64 v[200:201], s[50:51], 0, v[136:137]
	s_add_i32 m0, s35, 0xc000
	ds_read_b128 v[168:171], v152
	ds_read_b128 v[172:175], v152 offset:1024
	ds_read_b128 v[176:179], v152 offset:2048
	ds_read_b128 v[180:183], v152 offset:3072
	ds_read_b128 v[184:187], v152 offset:4096
	ds_read_b128 v[188:191], v152 offset:5120
	ds_read_b128 v[192:195], v152 offset:6144
	ds_read_b128 v[196:199], v152 offset:7168
	global_load_lds_dwordx4 v[200:201], off
	s_add_i32 m0, s35, 0xe000
	v_lshl_add_u64 v[200:201], s[50:51], 0, v[138:139]
	global_load_lds_dwordx4 v[200:201], off
	s_barrier
	s_waitcnt lgkmcnt(0)
	v_mfma_f32_16x16x32_bf16 v[124:127], v[144:147], v[168:171], v[124:127]
	v_mfma_f32_16x16x32_bf16 v[120:123], v[160:163], v[168:171], v[120:123]
	v_mfma_f32_16x16x32_bf16 v[108:111], v[144:147], v[176:179], v[108:111]
	v_mfma_f32_16x16x32_bf16 v[104:107], v[160:163], v[176:179], v[104:107]
	v_mfma_f32_16x16x32_bf16 v[92:95], v[144:147], v[184:187], v[92:95]
	v_mfma_f32_16x16x32_bf16 v[88:91], v[160:163], v[184:187], v[88:91]
	v_mfma_f32_16x16x32_bf16 v[76:79], v[144:147], v[192:195], v[76:79]
	v_mfma_f32_16x16x32_bf16 v[72:75], v[160:163], v[192:195], v[72:75]
	v_mfma_f32_16x16x32_bf16 v[124:127], v[156:159], v[172:175], v[124:127]
	v_mfma_f32_16x16x32_bf16 v[120:123], v[164:167], v[172:175], v[120:123]
	v_mfma_f32_16x16x32_bf16 v[108:111], v[156:159], v[180:183], v[108:111]
	v_mfma_f32_16x16x32_bf16 v[104:107], v[164:167], v[180:183], v[104:107]
	v_mfma_f32_16x16x32_bf16 v[92:95], v[156:159], v[188:191], v[92:95]
	v_mfma_f32_16x16x32_bf16 v[88:91], v[164:167], v[188:191], v[88:91]
	v_mfma_f32_16x16x32_bf16 v[76:79], v[156:159], v[196:199], v[76:79]
	v_mfma_f32_16x16x32_bf16 v[72:75], v[164:167], v[196:199], v[72:75]
	s_barrier
	s_add_i32 s69, s62, s1
	v_lshl_add_u64 v[216:217], s[52:53], 0, v[132:133]
	s_mov_b32 m0, s69
	ds_read_b128 v[200:203], v153
	ds_read_b128 v[204:207], v153 offset:1024
	ds_read_b128 v[208:211], v153 offset:2048
	ds_read_b128 v[212:215], v153 offset:3072
	global_load_lds_dwordx4 v[216:217], off
	s_add_i32 m0, s69, 0x2000
	v_lshl_add_u64 v[218:219], s[52:53], 0, v[128:129]
	global_load_lds_dwordx4 v[218:219], off
	s_barrier
	s_waitcnt lgkmcnt(0)
	v_mfma_f32_16x16x32_bf16 v[116:119], v[200:203], v[168:171], v[116:119]
	v_mfma_f32_16x16x32_bf16 v[112:115], v[208:211], v[168:171], v[112:115]
	v_mfma_f32_16x16x32_bf16 v[100:103], v[200:203], v[176:179], v[100:103]
	v_mfma_f32_16x16x32_bf16 v[96:99], v[208:211], v[176:179], v[96:99]
	v_mfma_f32_16x16x32_bf16 v[84:87], v[200:203], v[184:187], v[84:87]
	v_mfma_f32_16x16x32_bf16 v[80:83], v[208:211], v[184:187], v[80:83]
	v_mfma_f32_16x16x32_bf16 v[68:71], v[200:203], v[192:195], v[68:71]
	v_mfma_f32_16x16x32_bf16 v[64:67], v[208:211], v[192:195], v[64:67]
	v_mfma_f32_16x16x32_bf16 v[116:119], v[204:207], v[172:175], v[116:119]
	v_mfma_f32_16x16x32_bf16 v[112:115], v[212:215], v[172:175], v[112:115]
	v_mfma_f32_16x16x32_bf16 v[100:103], v[204:207], v[180:183], v[100:103]
	v_mfma_f32_16x16x32_bf16 v[96:99], v[212:215], v[180:183], v[96:99]
	v_mfma_f32_16x16x32_bf16 v[84:87], v[204:207], v[188:191], v[84:87]
	v_mfma_f32_16x16x32_bf16 v[80:83], v[212:215], v[188:191], v[80:83]
	v_mfma_f32_16x16x32_bf16 v[68:71], v[204:207], v[196:199], v[68:71]
	v_mfma_f32_16x16x32_bf16 v[64:67], v[212:215], v[196:199], v[64:67]
	s_mov_b32 m0, s35
	v_lshl_add_u64 v[220:221], s[54:55], 0, v[134:135]
	s_barrier
	ds_read_b128 v[168:171], v152 offset:16384
	ds_read_b128 v[172:175], v152 offset:17408
	ds_read_b128 v[176:179], v152 offset:18432
	ds_read_b128 v[180:183], v152 offset:19456
	ds_read_b128 v[184:187], v152 offset:20480
	ds_read_b128 v[188:191], v152 offset:21504
	ds_read_b128 v[192:195], v152 offset:22528
	ds_read_b128 v[196:199], v152 offset:23552
	global_load_lds_dwordx4 v[220:221], off
	s_mov_b32 m0, s49
	v_lshl_add_u64 v[222:223], s[54:55], 0, v[130:131]
	global_load_lds_dwordx4 v[222:223], off
	s_barrier
	s_waitcnt lgkmcnt(0)
	v_mfma_f32_16x16x32_bf16 v[60:63], v[144:147], v[168:171], v[60:63]
	v_mfma_f32_16x16x32_bf16 v[56:59], v[160:163], v[168:171], v[56:59]
	v_mfma_f32_16x16x32_bf16 v[44:47], v[144:147], v[176:179], v[44:47]
	v_mfma_f32_16x16x32_bf16 v[40:43], v[160:163], v[176:179], v[40:43]
	v_mfma_f32_16x16x32_bf16 v[28:31], v[144:147], v[184:187], v[28:31]
	v_mfma_f32_16x16x32_bf16 v[24:27], v[160:163], v[184:187], v[24:27]
	v_mfma_f32_16x16x32_bf16 v[12:15], v[144:147], v[192:195], v[12:15]
	v_mfma_f32_16x16x32_bf16 v[8:11], v[160:163], v[192:195], v[8:11]
	v_mfma_f32_16x16x32_bf16 v[60:63], v[156:159], v[172:175], v[60:63]
	v_mfma_f32_16x16x32_bf16 v[56:59], v[164:167], v[172:175], v[56:59]
	v_mfma_f32_16x16x32_bf16 v[44:47], v[156:159], v[180:183], v[44:47]
	v_mfma_f32_16x16x32_bf16 v[40:43], v[164:167], v[180:183], v[40:43]
	v_mfma_f32_16x16x32_bf16 v[28:31], v[156:159], v[188:191], v[28:31]
	v_mfma_f32_16x16x32_bf16 v[24:27], v[164:167], v[188:191], v[24:27]
	v_mfma_f32_16x16x32_bf16 v[12:15], v[156:159], v[196:199], v[12:15]
	v_mfma_f32_16x16x32_bf16 v[8:11], v[164:167], v[196:199], v[8:11]
	s_barrier
	s_add_u32 s70, s52, 0x20000
	s_addc_u32 s71, s53, 0
	s_add_i32 s69, s72, s1
	s_mov_b32 m0, s69
	v_lshl_add_u64 v[144:145], s[70:71], 0, v[132:133]
	global_load_lds_dwordx4 v[144:145], off
	s_add_i32 m0, s69, 0x2000
	v_lshl_add_u64 v[144:145], s[70:71], 0, v[128:129]
	global_load_lds_dwordx4 v[144:145], off
	s_waitcnt vmcnt(6)
	s_barrier
	v_mfma_f32_16x16x32_bf16 v[52:55], v[200:203], v[168:171], v[52:55]
	v_mfma_f32_16x16x32_bf16 v[48:51], v[208:211], v[168:171], v[48:51]
	v_mfma_f32_16x16x32_bf16 v[36:39], v[200:203], v[176:179], v[36:39]
	v_mfma_f32_16x16x32_bf16 v[32:35], v[208:211], v[176:179], v[32:35]
	v_mfma_f32_16x16x32_bf16 v[20:23], v[200:203], v[184:187], v[20:23]
	v_mfma_f32_16x16x32_bf16 v[16:19], v[208:211], v[184:187], v[16:19]
	v_mfma_f32_16x16x32_bf16 v[4:7], v[200:203], v[192:195], v[4:7]
	v_mfma_f32_16x16x32_bf16 v[0:3], v[208:211], v[192:195], v[0:3]
	v_mfma_f32_16x16x32_bf16 v[52:55], v[204:207], v[172:175], v[52:55]
	v_mfma_f32_16x16x32_bf16 v[48:51], v[212:215], v[172:175], v[48:51]
	v_mfma_f32_16x16x32_bf16 v[36:39], v[204:207], v[180:183], v[36:39]
	v_mfma_f32_16x16x32_bf16 v[32:35], v[212:215], v[180:183], v[32:35]
	v_mfma_f32_16x16x32_bf16 v[20:23], v[204:207], v[188:191], v[20:23]
	v_mfma_f32_16x16x32_bf16 v[16:19], v[212:215], v[188:191], v[16:19]
	v_mfma_f32_16x16x32_bf16 v[4:7], v[204:207], v[196:199], v[4:7]
	v_mfma_f32_16x16x32_bf16 v[0:3], v[212:215], v[196:199], v[0:3]
	s_add_i32 s69, 0, 0x18000
	v_add_u32_e32 v164, s69, v149
	s_barrier
	ds_read_b128 v[144:147], v164
	ds_read_b128 v[156:159], v164 offset:1024
	ds_read_b128 v[160:163], v164 offset:2048
	ds_read_b128 v[164:167], v164 offset:3072
	s_add_u32 s54, s54, 0x20000
	s_addc_u32 s55, s55, 0
	s_mov_b32 m0, s56
	v_lshl_add_u64 v[200:201], s[54:55], 0, v[134:135]
	ds_read_b128 v[168:171], v152 offset:32768
	ds_read_b128 v[172:175], v152 offset:33792
	ds_read_b128 v[176:179], v152 offset:34816
	ds_read_b128 v[180:183], v152 offset:35840
	ds_read_b128 v[184:187], v152 offset:36864
	ds_read_b128 v[188:191], v152 offset:37888
	ds_read_b128 v[192:195], v152 offset:38912
	ds_read_b128 v[196:199], v152 offset:39936
	global_load_lds_dwordx4 v[200:201], off
	s_mov_b32 m0, s57
	v_lshl_add_u64 v[200:201], s[54:55], 0, v[130:131]
	global_load_lds_dwordx4 v[200:201], off
	s_barrier
	s_waitcnt lgkmcnt(0)
	v_mfma_f32_16x16x32_bf16 v[124:127], v[144:147], v[168:171], v[124:127]
	v_mfma_f32_16x16x32_bf16 v[120:123], v[160:163], v[168:171], v[120:123]
	v_mfma_f32_16x16x32_bf16 v[108:111], v[144:147], v[176:179], v[108:111]
	v_mfma_f32_16x16x32_bf16 v[104:107], v[160:163], v[176:179], v[104:107]
	v_mfma_f32_16x16x32_bf16 v[92:95], v[144:147], v[184:187], v[92:95]
	v_mfma_f32_16x16x32_bf16 v[88:91], v[160:163], v[184:187], v[88:91]
	v_mfma_f32_16x16x32_bf16 v[76:79], v[144:147], v[192:195], v[76:79]
	v_mfma_f32_16x16x32_bf16 v[72:75], v[160:163], v[192:195], v[72:75]
	v_mfma_f32_16x16x32_bf16 v[124:127], v[156:159], v[172:175], v[124:127]
	v_mfma_f32_16x16x32_bf16 v[120:123], v[164:167], v[172:175], v[120:123]
	v_mfma_f32_16x16x32_bf16 v[108:111], v[156:159], v[180:183], v[108:111]
	v_mfma_f32_16x16x32_bf16 v[104:107], v[164:167], v[180:183], v[104:107]
	v_mfma_f32_16x16x32_bf16 v[92:95], v[156:159], v[188:191], v[92:95]
	v_mfma_f32_16x16x32_bf16 v[88:91], v[164:167], v[188:191], v[88:91]
	v_mfma_f32_16x16x32_bf16 v[76:79], v[156:159], v[196:199], v[76:79]
	v_mfma_f32_16x16x32_bf16 v[72:75], v[164:167], v[196:199], v[72:75]
	s_barrier
	s_add_i32 s54, s69, s1
	v_add_u32_e32 v212, s97, v149
	v_lshl_add_u64 v[216:217], v[216:217], 0, s[20:21]
	s_mov_b32 m0, s54
	ds_read_b128 v[200:203], v212
	ds_read_b128 v[204:207], v212 offset:1024
	ds_read_b128 v[208:211], v212 offset:2048
	ds_read_b128 v[212:215], v212 offset:3072
	global_load_lds_dwordx4 v[216:217], off
	s_add_i32 m0, s54, 0x2000
	v_lshl_add_u64 v[216:217], v[218:219], 0, s[20:21]
	global_load_lds_dwordx4 v[216:217], off
	s_barrier
	s_waitcnt lgkmcnt(0)
	v_mfma_f32_16x16x32_bf16 v[116:119], v[200:203], v[168:171], v[116:119]
	v_mfma_f32_16x16x32_bf16 v[112:115], v[208:211], v[168:171], v[112:115]
	v_mfma_f32_16x16x32_bf16 v[100:103], v[200:203], v[176:179], v[100:103]
	v_mfma_f32_16x16x32_bf16 v[96:99], v[208:211], v[176:179], v[96:99]
	v_mfma_f32_16x16x32_bf16 v[84:87], v[200:203], v[184:187], v[84:87]
	v_mfma_f32_16x16x32_bf16 v[80:83], v[208:211], v[184:187], v[80:83]
	v_mfma_f32_16x16x32_bf16 v[68:71], v[200:203], v[192:195], v[68:71]
	v_mfma_f32_16x16x32_bf16 v[64:67], v[208:211], v[192:195], v[64:67]
	v_mfma_f32_16x16x32_bf16 v[116:119], v[204:207], v[172:175], v[116:119]
	v_mfma_f32_16x16x32_bf16 v[112:115], v[212:215], v[172:175], v[112:115]
	v_mfma_f32_16x16x32_bf16 v[100:103], v[204:207], v[180:183], v[100:103]
	v_mfma_f32_16x16x32_bf16 v[96:99], v[212:215], v[180:183], v[96:99]
	v_mfma_f32_16x16x32_bf16 v[84:87], v[204:207], v[188:191], v[84:87]
	v_mfma_f32_16x16x32_bf16 v[80:83], v[212:215], v[188:191], v[80:83]
	v_mfma_f32_16x16x32_bf16 v[68:71], v[204:207], v[196:199], v[68:71]
	v_mfma_f32_16x16x32_bf16 v[64:67], v[212:215], v[196:199], v[64:67]
	s_mov_b32 m0, s59
	v_lshl_add_u64 v[216:217], v[220:221], 0, s[20:21]
	s_barrier
	ds_read_b128 v[168:171], v152 offset:49152
	ds_read_b128 v[172:175], v152 offset:50176
	ds_read_b128 v[176:179], v152 offset:51200
	ds_read_b128 v[180:183], v152 offset:52224
	ds_read_b128 v[184:187], v152 offset:53248
	ds_read_b128 v[188:191], v152 offset:54272
	ds_read_b128 v[192:195], v152 offset:55296
	ds_read_b128 v[196:199], v152 offset:56320
	global_load_lds_dwordx4 v[216:217], off
	s_mov_b32 m0, s60
	v_lshl_add_u64 v[216:217], v[222:223], 0, s[20:21]
	global_load_lds_dwordx4 v[216:217], off
	s_barrier
	s_waitcnt lgkmcnt(0)
	v_mfma_f32_16x16x32_bf16 v[60:63], v[144:147], v[168:171], v[60:63]
	v_mfma_f32_16x16x32_bf16 v[56:59], v[160:163], v[168:171], v[56:59]
	v_mfma_f32_16x16x32_bf16 v[44:47], v[144:147], v[176:179], v[44:47]
	v_mfma_f32_16x16x32_bf16 v[40:43], v[160:163], v[176:179], v[40:43]
	v_mfma_f32_16x16x32_bf16 v[28:31], v[144:147], v[184:187], v[28:31]
	v_mfma_f32_16x16x32_bf16 v[24:27], v[160:163], v[184:187], v[24:27]
	v_mfma_f32_16x16x32_bf16 v[12:15], v[144:147], v[192:195], v[12:15]
	v_mfma_f32_16x16x32_bf16 v[8:11], v[160:163], v[192:195], v[8:11]
	v_mfma_f32_16x16x32_bf16 v[60:63], v[156:159], v[172:175], v[60:63]
	v_mfma_f32_16x16x32_bf16 v[56:59], v[164:167], v[172:175], v[56:59]
	v_mfma_f32_16x16x32_bf16 v[44:47], v[156:159], v[180:183], v[44:47]
	v_mfma_f32_16x16x32_bf16 v[40:43], v[164:167], v[180:183], v[40:43]
	v_mfma_f32_16x16x32_bf16 v[28:31], v[156:159], v[188:191], v[28:31]
	v_mfma_f32_16x16x32_bf16 v[24:27], v[164:167], v[188:191], v[24:27]
	v_mfma_f32_16x16x32_bf16 v[12:15], v[156:159], v[196:199], v[12:15]
	v_mfma_f32_16x16x32_bf16 v[8:11], v[164:167], v[196:199], v[8:11]
	s_barrier
	s_add_u32 s52, s52, 0x20080
	s_addc_u32 s53, s53, 0
	s_add_i32 s54, s97, s1
	s_mov_b32 m0, s54
	v_lshl_add_u64 v[144:145], s[52:53], 0, v[132:133]
	global_load_lds_dwordx4 v[144:145], off
	s_add_i32 m0, s54, 0x2000
	v_lshl_add_u64 v[144:145], s[52:53], 0, v[128:129]
	global_load_lds_dwordx4 v[144:145], off
	s_waitcnt vmcnt(6)
	s_barrier
	v_mfma_f32_16x16x32_bf16 v[52:55], v[200:203], v[168:171], v[52:55]
	v_mfma_f32_16x16x32_bf16 v[48:51], v[208:211], v[168:171], v[48:51]
	v_mfma_f32_16x16x32_bf16 v[36:39], v[200:203], v[176:179], v[36:39]
	v_mfma_f32_16x16x32_bf16 v[32:35], v[208:211], v[176:179], v[32:35]
	v_mfma_f32_16x16x32_bf16 v[20:23], v[200:203], v[184:187], v[20:23]
	v_mfma_f32_16x16x32_bf16 v[16:19], v[208:211], v[184:187], v[16:19]
	v_mfma_f32_16x16x32_bf16 v[4:7], v[200:203], v[192:195], v[4:7]
	v_mfma_f32_16x16x32_bf16 v[0:3], v[208:211], v[192:195], v[0:3]
	v_mfma_f32_16x16x32_bf16 v[52:55], v[204:207], v[172:175], v[52:55]
	v_mfma_f32_16x16x32_bf16 v[48:51], v[212:215], v[172:175], v[48:51]
	v_mfma_f32_16x16x32_bf16 v[36:39], v[204:207], v[180:183], v[36:39]
	v_mfma_f32_16x16x32_bf16 v[32:35], v[212:215], v[180:183], v[32:35]
	v_mfma_f32_16x16x32_bf16 v[20:23], v[204:207], v[188:191], v[20:23]
	v_mfma_f32_16x16x32_bf16 v[16:19], v[212:215], v[188:191], v[16:19]
	v_mfma_f32_16x16x32_bf16 v[4:7], v[204:207], v[196:199], v[4:7]
	v_mfma_f32_16x16x32_bf16 v[0:3], v[212:215], v[196:199], v[0:3]
	s_add_i32 s68, s68, 2
	s_add_u32 s50, s50, 0x100
	s_addc_u32 s51, s51, 0
	s_add_u32 s66, s66, 0x100
	s_addc_u32 s67, s67, 0
	s_cmp_gt_u32 s68, 5
	s_barrier
	s_cbranch_scc0 .LBB0_591
	v_lshl_add_u32 v146, s48, 8, v148
	v_lshl_or_b32 v144, s63, 8, v150
	v_ashrrev_i32_e32 v147, 31, v146
	v_lshlrev_b64 v[156:157], 12, v[146:147]
	v_ashrrev_i32_e32 v145, 31, v144
	v_lshl_add_u64 v[156:157], s[6:7], 0, v[156:157]
	v_lshlrev_b64 v[144:145], 1, v[144:145]
	v_lshl_add_u64 v[160:161], v[156:157], 0, v[144:145]
	global_load_dwordx4 v[156:159], v[160:161], off
	s_nop 0
	global_load_dwordx4 v[160:163], v[160:161], off offset:256
	v_or_b32_e32 v164, 16, v146
	v_lshlrev_b64 v[166:167], 11, v[146:147]
	v_ashrrev_i32_e32 v165, 31, v164
	v_lshl_add_u64 v[166:167], s[14:15], 0, v[166:167]
	v_lshlrev_b64 v[168:169], 12, v[164:165]
	v_lshl_add_u64 v[166:167], v[166:167], 0, v[144:145]
	v_lshl_add_u64 v[168:169], s[6:7], 0, v[168:169]
	v_lshl_add_u64 v[168:169], v[168:169], 0, v[144:145]
	s_and_b64 vcc, exec, s[4:5]
	s_mov_b32 s63, s24
	s_mov_b32 s48, s40
	s_mov_b64 s[52:53], s[46:47]
	s_mov_b64 s[50:51], s[44:45]
	s_waitcnt vmcnt(0)
	v_lshlrev_b32_e32 v170, 16, v156
	v_and_b32_e32 v171, 0xffff0000, v156
	v_lshlrev_b32_e32 v156, 16, v157
	v_and_b32_e32 v157, 0xffff0000, v157
	v_lshlrev_b32_e32 v172, 16, v158
	v_and_b32_e32 v173, 0xffff0000, v158
	v_lshlrev_b32_e32 v158, 16, v159
	v_and_b32_e32 v159, 0xffff0000, v159
	v_lshlrev_b32_e32 v174, 16, v160
	v_and_b32_e32 v175, 0xffff0000, v160
	v_lshlrev_b32_e32 v160, 16, v161
	v_and_b32_e32 v161, 0xffff0000, v161
	v_lshlrev_b32_e32 v176, 16, v162
	v_and_b32_e32 v177, 0xffff0000, v162
	v_lshlrev_b32_e32 v162, 16, v163
	v_and_b32_e32 v163, 0xffff0000, v163
	v_pk_mul_f32 v[126:127], v[126:127], v[156:157]
	v_pk_mul_f32 v[124:125], v[124:125], v[170:171]
	v_pk_mul_f32 v[122:123], v[122:123], v[158:159]
	v_pk_mul_f32 v[120:121], v[120:121], v[172:173]
	v_pk_mul_f32 v[156:157], v[118:119], v[160:161]
	v_pk_mul_f32 v[158:159], v[116:117], v[174:175]
	v_cvt_pk_bf16_f32 v116, v124, v125
	v_cvt_pk_bf16_f32 v117, v126, v127
	v_cvt_pk_bf16_f32 v118, v120, v121
	v_cvt_pk_bf16_f32 v119, v122, v123
	v_pk_mul_f32 v[120:121], v[114:115], v[162:163]
	v_pk_mul_f32 v[114:115], v[112:113], v[176:177]
	global_store_dwordx4 v[166:167], v[116:119], off
	v_cvt_pk_bf16_f32 v112, v158, v159
	v_cvt_pk_bf16_f32 v113, v156, v157
	v_cvt_pk_bf16_f32 v114, v114, v115
	v_cvt_pk_bf16_f32 v115, v120, v121
	global_load_dwordx4 v[116:119], v[168:169], off
	v_or_b32_e32 v120, 32, v146
	global_store_dwordx4 v[166:167], v[112:115], off offset:256
	global_load_dwordx4 v[112:115], v[168:169], off offset:256
	v_ashrrev_i32_e32 v121, 31, v120
	v_lshlrev_b64 v[122:123], 11, v[164:165]
	v_lshlrev_b64 v[124:125], 12, v[120:121]
	v_lshl_add_u64 v[122:123], s[14:15], 0, v[122:123]
	v_lshl_add_u64 v[124:125], s[6:7], 0, v[124:125]
	v_lshl_add_u64 v[122:123], v[122:123], 0, v[144:145]
	v_lshl_add_u64 v[124:125], v[124:125], 0, v[144:145]
	s_waitcnt vmcnt(0)
	v_lshlrev_b32_e32 v126, 16, v116
	v_and_b32_e32 v127, 0xffff0000, v116
	v_lshlrev_b32_e32 v116, 16, v117
	v_and_b32_e32 v117, 0xffff0000, v117
	v_lshlrev_b32_e32 v156, 16, v118
	v_and_b32_e32 v157, 0xffff0000, v118
	v_lshlrev_b32_e32 v118, 16, v119
	v_and_b32_e32 v119, 0xffff0000, v119
	v_lshlrev_b32_e32 v158, 16, v112
	v_and_b32_e32 v159, 0xffff0000, v112
	v_lshlrev_b32_e32 v112, 16, v113
	v_and_b32_e32 v113, 0xffff0000, v113
	v_lshlrev_b32_e32 v160, 16, v114
	v_and_b32_e32 v161, 0xffff0000, v114
	v_lshlrev_b32_e32 v114, 16, v115
	v_and_b32_e32 v115, 0xffff0000, v115
	v_pk_mul_f32 v[110:111], v[110:111], v[116:117]
	v_pk_mul_f32 v[108:109], v[108:109], v[126:127]
	v_pk_mul_f32 v[106:107], v[106:107], v[118:119]
	v_pk_mul_f32 v[104:105], v[104:105], v[156:157]
	v_pk_mul_f32 v[112:113], v[102:103], v[112:113]
	v_pk_mul_f32 v[116:117], v[100:101], v[158:159]
	v_cvt_pk_bf16_f32 v100, v108, v109
	v_cvt_pk_bf16_f32 v101, v110, v111
	v_cvt_pk_bf16_f32 v102, v104, v105
	v_cvt_pk_bf16_f32 v103, v106, v107
	v_pk_mul_f32 v[104:105], v[98:99], v[114:115]
	v_pk_mul_f32 v[98:99], v[96:97], v[160:161]
	global_store_dwordx4 v[122:123], v[100:103], off
	v_cvt_pk_bf16_f32 v96, v116, v117
	v_cvt_pk_bf16_f32 v97, v112, v113
	v_cvt_pk_bf16_f32 v98, v98, v99
	v_cvt_pk_bf16_f32 v99, v104, v105
	global_load_dwordx4 v[100:103], v[124:125], off
	v_or_b32_e32 v104, 48, v146
	global_store_dwordx4 v[122:123], v[96:99], off offset:256
	global_load_dwordx4 v[96:99], v[124:125], off offset:256
	v_ashrrev_i32_e32 v105, 31, v104
	v_lshlrev_b64 v[106:107], 11, v[120:121]
	v_lshlrev_b64 v[108:109], 12, v[104:105]
	v_lshl_add_u64 v[106:107], s[14:15], 0, v[106:107]
	v_lshl_add_u64 v[108:109], s[6:7], 0, v[108:109]
	v_lshl_add_u64 v[106:107], v[106:107], 0, v[144:145]
	v_lshl_add_u64 v[108:109], v[108:109], 0, v[144:145]
	s_waitcnt vmcnt(0)
	v_lshlrev_b32_e32 v110, 16, v100
	v_and_b32_e32 v111, 0xffff0000, v100
	v_lshlrev_b32_e32 v100, 16, v101
	v_and_b32_e32 v101, 0xffff0000, v101
	v_lshlrev_b32_e32 v112, 16, v102
	v_and_b32_e32 v113, 0xffff0000, v102
	v_lshlrev_b32_e32 v102, 16, v103
	v_and_b32_e32 v103, 0xffff0000, v103
	v_lshlrev_b32_e32 v114, 16, v96
	v_and_b32_e32 v115, 0xffff0000, v96
	v_lshlrev_b32_e32 v96, 16, v97
	v_and_b32_e32 v97, 0xffff0000, v97
	v_lshlrev_b32_e32 v116, 16, v98
	v_and_b32_e32 v117, 0xffff0000, v98
	v_lshlrev_b32_e32 v98, 16, v99
	v_and_b32_e32 v99, 0xffff0000, v99
	v_pk_mul_f32 v[94:95], v[94:95], v[100:101]
	v_pk_mul_f32 v[92:93], v[92:93], v[110:111]
	v_pk_mul_f32 v[90:91], v[90:91], v[102:103]
	v_pk_mul_f32 v[88:89], v[88:89], v[112:113]
	v_pk_mul_f32 v[96:97], v[86:87], v[96:97]
	v_pk_mul_f32 v[100:101], v[84:85], v[114:115]
	v_cvt_pk_bf16_f32 v84, v92, v93
	v_cvt_pk_bf16_f32 v85, v94, v95
	v_cvt_pk_bf16_f32 v86, v88, v89
	v_cvt_pk_bf16_f32 v87, v90, v91
	v_pk_mul_f32 v[88:89], v[82:83], v[98:99]
	v_pk_mul_f32 v[82:83], v[80:81], v[116:117]
	global_store_dwordx4 v[106:107], v[84:87], off
	v_cvt_pk_bf16_f32 v80, v100, v101
	v_cvt_pk_bf16_f32 v81, v96, v97
	v_cvt_pk_bf16_f32 v82, v82, v83
	v_cvt_pk_bf16_f32 v83, v88, v89
	global_load_dwordx4 v[84:87], v[108:109], off
	v_add_u32_e32 v88, 0x80, v146
	global_store_dwordx4 v[106:107], v[80:83], off offset:256
	global_load_dwordx4 v[80:83], v[108:109], off offset:256
	v_ashrrev_i32_e32 v89, 31, v88
	v_lshlrev_b64 v[90:91], 11, v[104:105]
	v_lshlrev_b64 v[92:93], 12, v[88:89]
	v_lshl_add_u64 v[90:91], s[14:15], 0, v[90:91]
	v_lshl_add_u64 v[92:93], s[6:7], 0, v[92:93]
	v_lshl_add_u64 v[90:91], v[90:91], 0, v[144:145]
	v_lshl_add_u64 v[92:93], v[92:93], 0, v[144:145]
	s_waitcnt vmcnt(0)
	v_lshlrev_b32_e32 v94, 16, v84
	v_and_b32_e32 v95, 0xffff0000, v84
	v_lshlrev_b32_e32 v84, 16, v85
	v_and_b32_e32 v85, 0xffff0000, v85
	v_lshlrev_b32_e32 v96, 16, v86
	v_and_b32_e32 v97, 0xffff0000, v86
	v_lshlrev_b32_e32 v86, 16, v87
	v_and_b32_e32 v87, 0xffff0000, v87
	v_lshlrev_b32_e32 v98, 16, v80
	v_and_b32_e32 v99, 0xffff0000, v80
	v_lshlrev_b32_e32 v80, 16, v81
	v_and_b32_e32 v81, 0xffff0000, v81
	v_lshlrev_b32_e32 v100, 16, v82
	v_and_b32_e32 v101, 0xffff0000, v82
	v_lshlrev_b32_e32 v82, 16, v83
	v_and_b32_e32 v83, 0xffff0000, v83
	v_pk_mul_f32 v[78:79], v[78:79], v[84:85]
	v_pk_mul_f32 v[76:77], v[76:77], v[94:95]
	v_pk_mul_f32 v[74:75], v[74:75], v[86:87]
	v_pk_mul_f32 v[72:73], v[72:73], v[96:97]
	v_pk_mul_f32 v[80:81], v[70:71], v[80:81]
	v_pk_mul_f32 v[84:85], v[68:69], v[98:99]
	v_cvt_pk_bf16_f32 v68, v76, v77
	v_cvt_pk_bf16_f32 v69, v78, v79
	v_cvt_pk_bf16_f32 v70, v72, v73
	v_cvt_pk_bf16_f32 v71, v74, v75
	v_pk_mul_f32 v[72:73], v[66:67], v[82:83]
	v_pk_mul_f32 v[66:67], v[64:65], v[100:101]
	global_store_dwordx4 v[90:91], v[68:71], off
	v_cvt_pk_bf16_f32 v64, v84, v85
	v_cvt_pk_bf16_f32 v65, v80, v81
	v_cvt_pk_bf16_f32 v66, v66, v67
	v_cvt_pk_bf16_f32 v67, v72, v73
	global_load_dwordx4 v[68:71], v[92:93], off
	v_add_u32_e32 v72, 0x90, v146
	global_store_dwordx4 v[90:91], v[64:67], off offset:256
	global_load_dwordx4 v[64:67], v[92:93], off offset:256
	v_ashrrev_i32_e32 v73, 31, v72
	v_lshlrev_b64 v[74:75], 11, v[88:89]
	v_lshlrev_b64 v[76:77], 12, v[72:73]
	v_lshl_add_u64 v[74:75], s[14:15], 0, v[74:75]
	v_lshl_add_u64 v[76:77], s[6:7], 0, v[76:77]
	v_lshl_add_u64 v[74:75], v[74:75], 0, v[144:145]
	v_lshl_add_u64 v[76:77], v[76:77], 0, v[144:145]
	s_waitcnt vmcnt(0)
	v_lshlrev_b32_e32 v78, 16, v68
	v_and_b32_e32 v79, 0xffff0000, v68
	v_lshlrev_b32_e32 v68, 16, v69
	v_and_b32_e32 v69, 0xffff0000, v69
	v_lshlrev_b32_e32 v80, 16, v70
	v_and_b32_e32 v81, 0xffff0000, v70
	v_lshlrev_b32_e32 v70, 16, v71
	v_and_b32_e32 v71, 0xffff0000, v71
	v_lshlrev_b32_e32 v82, 16, v64
	v_and_b32_e32 v83, 0xffff0000, v64
	v_lshlrev_b32_e32 v64, 16, v65
	v_and_b32_e32 v65, 0xffff0000, v65
	v_lshlrev_b32_e32 v84, 16, v66
	v_and_b32_e32 v85, 0xffff0000, v66
	v_lshlrev_b32_e32 v66, 16, v67
	v_and_b32_e32 v67, 0xffff0000, v67
	v_pk_mul_f32 v[62:63], v[62:63], v[68:69]
	v_pk_mul_f32 v[60:61], v[60:61], v[78:79]
	v_pk_mul_f32 v[58:59], v[58:59], v[70:71]
	v_pk_mul_f32 v[56:57], v[56:57], v[80:81]
	v_pk_mul_f32 v[64:65], v[54:55], v[64:65]
	v_pk_mul_f32 v[68:69], v[52:53], v[82:83]
	v_cvt_pk_bf16_f32 v52, v60, v61
	v_cvt_pk_bf16_f32 v53, v62, v63
	v_cvt_pk_bf16_f32 v54, v56, v57
	v_cvt_pk_bf16_f32 v55, v58, v59
	v_pk_mul_f32 v[56:57], v[50:51], v[66:67]
	v_pk_mul_f32 v[50:51], v[48:49], v[84:85]
	global_store_dwordx4 v[74:75], v[52:55], off
	v_cvt_pk_bf16_f32 v48, v68, v69
	v_cvt_pk_bf16_f32 v49, v64, v65
	v_cvt_pk_bf16_f32 v50, v50, v51
	v_cvt_pk_bf16_f32 v51, v56, v57
	global_load_dwordx4 v[52:55], v[76:77], off
	v_add_u32_e32 v56, 0xa0, v146
	global_store_dwordx4 v[74:75], v[48:51], off offset:256
	global_load_dwordx4 v[48:51], v[76:77], off offset:256
	v_ashrrev_i32_e32 v57, 31, v56
	v_lshlrev_b64 v[58:59], 11, v[72:73]
	v_lshlrev_b64 v[60:61], 12, v[56:57]
	v_lshl_add_u64 v[58:59], s[14:15], 0, v[58:59]
	v_lshl_add_u64 v[60:61], s[6:7], 0, v[60:61]
	v_lshl_add_u64 v[58:59], v[58:59], 0, v[144:145]
	v_lshl_add_u64 v[60:61], v[60:61], 0, v[144:145]
	s_waitcnt vmcnt(0)
	v_lshlrev_b32_e32 v62, 16, v52
	v_and_b32_e32 v63, 0xffff0000, v52
	v_lshlrev_b32_e32 v52, 16, v53
	v_and_b32_e32 v53, 0xffff0000, v53
	v_lshlrev_b32_e32 v64, 16, v54
	v_and_b32_e32 v65, 0xffff0000, v54
	v_lshlrev_b32_e32 v54, 16, v55
	v_and_b32_e32 v55, 0xffff0000, v55
	v_lshlrev_b32_e32 v66, 16, v48
	v_and_b32_e32 v67, 0xffff0000, v48
	v_lshlrev_b32_e32 v48, 16, v49
	v_and_b32_e32 v49, 0xffff0000, v49
	v_lshlrev_b32_e32 v68, 16, v50
	v_and_b32_e32 v69, 0xffff0000, v50
	v_lshlrev_b32_e32 v50, 16, v51
	v_and_b32_e32 v51, 0xffff0000, v51
	v_pk_mul_f32 v[46:47], v[46:47], v[52:53]
	v_pk_mul_f32 v[44:45], v[44:45], v[62:63]
	v_pk_mul_f32 v[42:43], v[42:43], v[54:55]
	v_pk_mul_f32 v[40:41], v[40:41], v[64:65]
	v_pk_mul_f32 v[48:49], v[38:39], v[48:49]
	v_pk_mul_f32 v[52:53], v[36:37], v[66:67]
	v_cvt_pk_bf16_f32 v36, v44, v45
	v_cvt_pk_bf16_f32 v37, v46, v47
	v_cvt_pk_bf16_f32 v38, v40, v41
	v_cvt_pk_bf16_f32 v39, v42, v43
	v_pk_mul_f32 v[40:41], v[34:35], v[50:51]
	v_pk_mul_f32 v[34:35], v[32:33], v[68:69]
	global_store_dwordx4 v[58:59], v[36:39], off
	v_cvt_pk_bf16_f32 v32, v52, v53
	v_cvt_pk_bf16_f32 v33, v48, v49
	v_cvt_pk_bf16_f32 v34, v34, v35
	v_cvt_pk_bf16_f32 v35, v40, v41
	global_load_dwordx4 v[36:39], v[60:61], off
	v_add_u32_e32 v40, 0xb0, v146
	global_store_dwordx4 v[58:59], v[32:35], off offset:256
	global_load_dwordx4 v[32:35], v[60:61], off offset:256
	v_ashrrev_i32_e32 v41, 31, v40
	v_lshlrev_b64 v[42:43], 11, v[56:57]
	v_lshlrev_b64 v[44:45], 12, v[40:41]
	v_lshl_add_u64 v[42:43], s[14:15], 0, v[42:43]
	v_lshl_add_u64 v[44:45], s[6:7], 0, v[44:45]
	v_lshl_add_u64 v[42:43], v[42:43], 0, v[144:145]
	v_lshl_add_u64 v[44:45], v[44:45], 0, v[144:145]
	s_waitcnt vmcnt(0)
	v_lshlrev_b32_e32 v46, 16, v36
	v_and_b32_e32 v47, 0xffff0000, v36
	v_lshlrev_b32_e32 v36, 16, v37
	v_and_b32_e32 v37, 0xffff0000, v37
	v_lshlrev_b32_e32 v48, 16, v38
	v_and_b32_e32 v49, 0xffff0000, v38
	v_lshlrev_b32_e32 v38, 16, v39
	v_and_b32_e32 v39, 0xffff0000, v39
	v_lshlrev_b32_e32 v50, 16, v32
	v_and_b32_e32 v51, 0xffff0000, v32
	v_lshlrev_b32_e32 v32, 16, v33
	v_and_b32_e32 v33, 0xffff0000, v33
	v_lshlrev_b32_e32 v52, 16, v34
	v_and_b32_e32 v53, 0xffff0000, v34
	v_lshlrev_b32_e32 v34, 16, v35
	v_and_b32_e32 v35, 0xffff0000, v35
	v_pk_mul_f32 v[30:31], v[30:31], v[36:37]
	v_pk_mul_f32 v[28:29], v[28:29], v[46:47]
	v_pk_mul_f32 v[26:27], v[26:27], v[38:39]
	v_pk_mul_f32 v[24:25], v[24:25], v[48:49]
	v_pk_mul_f32 v[32:33], v[22:23], v[32:33]
	v_pk_mul_f32 v[36:37], v[20:21], v[50:51]
	v_cvt_pk_bf16_f32 v20, v28, v29
	v_cvt_pk_bf16_f32 v21, v30, v31
	v_cvt_pk_bf16_f32 v22, v24, v25
	v_cvt_pk_bf16_f32 v23, v26, v27
	v_pk_mul_f32 v[24:25], v[18:19], v[34:35]
	v_pk_mul_f32 v[18:19], v[16:17], v[52:53]
	global_store_dwordx4 v[42:43], v[20:23], off
	v_cvt_pk_bf16_f32 v16, v36, v37
	v_cvt_pk_bf16_f32 v17, v32, v33
	v_cvt_pk_bf16_f32 v18, v18, v19
	v_cvt_pk_bf16_f32 v19, v24, v25
	global_load_dwordx4 v[20:23], v[44:45], off
	v_lshlrev_b64 v[24:25], 11, v[40:41]
	global_store_dwordx4 v[42:43], v[16:19], off offset:256
	global_load_dwordx4 v[16:19], v[44:45], off offset:256
	v_lshl_add_u64 v[24:25], s[14:15], 0, v[24:25]
	v_lshl_add_u64 v[24:25], v[24:25], 0, v[144:145]
	s_waitcnt vmcnt(0)
	v_lshlrev_b32_e32 v26, 16, v20
	v_and_b32_e32 v27, 0xffff0000, v20
	v_lshlrev_b32_e32 v20, 16, v21
	v_and_b32_e32 v21, 0xffff0000, v21
	v_lshlrev_b32_e32 v28, 16, v22
	v_and_b32_e32 v29, 0xffff0000, v22
	v_lshlrev_b32_e32 v22, 16, v23
	v_and_b32_e32 v23, 0xffff0000, v23
	v_lshlrev_b32_e32 v30, 16, v16
	v_and_b32_e32 v31, 0xffff0000, v16
	v_lshlrev_b32_e32 v16, 16, v17
	v_and_b32_e32 v17, 0xffff0000, v17
	v_lshlrev_b32_e32 v32, 16, v18
	v_and_b32_e32 v33, 0xffff0000, v18
	v_lshlrev_b32_e32 v18, 16, v19
	v_and_b32_e32 v19, 0xffff0000, v19
	v_pk_mul_f32 v[14:15], v[14:15], v[20:21]
	v_pk_mul_f32 v[12:13], v[12:13], v[26:27]
	v_pk_mul_f32 v[10:11], v[10:11], v[22:23]
	v_pk_mul_f32 v[8:9], v[8:9], v[28:29]
	v_pk_mul_f32 v[6:7], v[6:7], v[16:17]
	v_pk_mul_f32 v[4:5], v[4:5], v[30:31]
	v_pk_mul_f32 v[16:17], v[2:3], v[18:19]
	v_pk_mul_f32 v[18:19], v[0:1], v[32:33]
	v_cvt_pk_bf16_f32 v0, v12, v13
	v_cvt_pk_bf16_f32 v1, v14, v15
	v_cvt_pk_bf16_f32 v2, v8, v9
	v_cvt_pk_bf16_f32 v3, v10, v11
	v_cvt_pk_bf16_f32 v4, v4, v5
	v_cvt_pk_bf16_f32 v5, v6, v7
	v_cvt_pk_bf16_f32 v6, v18, v19
	v_cvt_pk_bf16_f32 v7, v16, v17
	global_store_dwordx4 v[24:25], v[0:3], off
	global_store_dwordx4 v[24:25], v[4:7], off offset:256
	s_cbranch_vccz .LBB0_588
	s_waitcnt vmcnt(0)
	s_cmpk_gt_u32 s0, 0xff
	s_cbranch_scc1 .LBB0_595
	s_barrier

.LBB0_603:
	ds_read_b128 v[144:147], v153
	ds_read_b128 v[158:161], v153 offset:1024
	ds_read_b128 v[162:165], v153 offset:2048
	ds_read_b128 v[166:169], v153 offset:3072
	s_add_u32 s50, s48, 0xfffc0080
	s_addc_u32 s51, s49, -1
	s_cmp_eq_u32 s66, 12
	s_cselect_b32 s53, s25, s51
	s_cselect_b32 s52, s62, s50
	s_cselect_b32 s51, s23, s65
	s_cselect_b32 s50, s63, s64
	v_lshl_add_u64 v[148:149], s[48:49], 0, v[136:137]
	s_add_i32 m0, s35, 0xc000
	ds_read_b128 v[170:173], v156
	ds_read_b128 v[174:177], v156 offset:1024
	ds_read_b128 v[178:181], v156 offset:2048
	ds_read_b128 v[182:185], v156 offset:3072
	ds_read_b128 v[186:189], v156 offset:4096
	ds_read_b128 v[190:193], v156 offset:5120
	ds_read_b128 v[194:197], v156 offset:6144
	ds_read_b128 v[198:201], v156 offset:7168
	global_load_lds_dwordx4 v[148:149], off
	s_add_i32 m0, s35, 0xe000
	v_lshl_add_u64 v[148:149], s[48:49], 0, v[138:139]
	global_load_lds_dwordx4 v[148:149], off
	s_barrier
	s_waitcnt lgkmcnt(0)
	v_mfma_f32_16x16x32_bf16 v[124:127], v[144:147], v[170:173], v[124:127]
	v_mfma_f32_16x16x32_bf16 v[120:123], v[162:165], v[170:173], v[120:123]
	v_mfma_f32_16x16x32_bf16 v[108:111], v[144:147], v[178:181], v[108:111]
	v_mfma_f32_16x16x32_bf16 v[104:107], v[162:165], v[178:181], v[104:107]
	v_mfma_f32_16x16x32_bf16 v[92:95], v[144:147], v[186:189], v[92:95]
	v_mfma_f32_16x16x32_bf16 v[88:91], v[162:165], v[186:189], v[88:91]
	v_mfma_f32_16x16x32_bf16 v[76:79], v[144:147], v[194:197], v[76:79]
	v_mfma_f32_16x16x32_bf16 v[72:75], v[162:165], v[194:197], v[72:75]
	v_mfma_f32_16x16x32_bf16 v[124:127], v[158:161], v[174:177], v[124:127]
	v_mfma_f32_16x16x32_bf16 v[120:123], v[166:169], v[174:177], v[120:123]
	v_mfma_f32_16x16x32_bf16 v[108:111], v[158:161], v[182:185], v[108:111]
	v_mfma_f32_16x16x32_bf16 v[104:107], v[166:169], v[182:185], v[104:107]
	v_mfma_f32_16x16x32_bf16 v[92:95], v[158:161], v[190:193], v[92:95]
	v_mfma_f32_16x16x32_bf16 v[88:91], v[166:169], v[190:193], v[88:91]
	v_mfma_f32_16x16x32_bf16 v[76:79], v[158:161], v[198:201], v[76:79]
	v_mfma_f32_16x16x32_bf16 v[72:75], v[166:169], v[198:201], v[72:75]
	s_barrier
	s_add_i32 s67, s60, s1
	v_lshl_add_u64 v[148:149], s[50:51], 0, v[132:133]
	s_mov_b32 m0, s67
	ds_read_b128 v[202:205], v157
	ds_read_b128 v[206:209], v157 offset:1024
	ds_read_b128 v[210:213], v157 offset:2048
	ds_read_b128 v[214:217], v157 offset:3072
	global_load_lds_dwordx4 v[148:149], off
	s_add_i32 m0, s67, 0x2000
	v_lshl_add_u64 v[218:219], s[50:51], 0, v[128:129]
	global_load_lds_dwordx4 v[218:219], off
	s_barrier
	s_waitcnt lgkmcnt(0)
	v_mfma_f32_16x16x32_bf16 v[116:119], v[202:205], v[170:173], v[116:119]
	v_mfma_f32_16x16x32_bf16 v[112:115], v[210:213], v[170:173], v[112:115]
	v_mfma_f32_16x16x32_bf16 v[100:103], v[202:205], v[178:181], v[100:103]
	v_mfma_f32_16x16x32_bf16 v[96:99], v[210:213], v[178:181], v[96:99]
	v_mfma_f32_16x16x32_bf16 v[84:87], v[202:205], v[186:189], v[84:87]
	v_mfma_f32_16x16x32_bf16 v[80:83], v[210:213], v[186:189], v[80:83]
	v_mfma_f32_16x16x32_bf16 v[68:71], v[202:205], v[194:197], v[68:71]
	v_mfma_f32_16x16x32_bf16 v[64:67], v[210:213], v[194:197], v[64:67]
	v_mfma_f32_16x16x32_bf16 v[116:119], v[206:209], v[174:177], v[116:119]
	v_mfma_f32_16x16x32_bf16 v[112:115], v[214:217], v[174:177], v[112:115]
	v_mfma_f32_16x16x32_bf16 v[100:103], v[206:209], v[182:185], v[100:103]
	v_mfma_f32_16x16x32_bf16 v[96:99], v[214:217], v[182:185], v[96:99]
	v_mfma_f32_16x16x32_bf16 v[84:87], v[206:209], v[190:193], v[84:87]
	v_mfma_f32_16x16x32_bf16 v[80:83], v[214:217], v[190:193], v[80:83]
	v_mfma_f32_16x16x32_bf16 v[68:71], v[206:209], v[198:201], v[68:71]
	v_mfma_f32_16x16x32_bf16 v[64:67], v[214:217], v[198:201], v[64:67]
	s_mov_b32 m0, s35
	v_lshl_add_u64 v[220:221], s[52:53], 0, v[134:135]
	s_barrier
	ds_read_b128 v[170:173], v156 offset:16384
	ds_read_b128 v[174:177], v156 offset:17408
	ds_read_b128 v[178:181], v156 offset:18432
	ds_read_b128 v[182:185], v156 offset:19456
	ds_read_b128 v[186:189], v156 offset:20480
	ds_read_b128 v[190:193], v156 offset:21504
	ds_read_b128 v[194:197], v156 offset:22528
	ds_read_b128 v[198:201], v156 offset:23552
	global_load_lds_dwordx4 v[220:221], off
	s_mov_b32 m0, s47
	v_lshl_add_u64 v[222:223], s[52:53], 0, v[130:131]
	global_load_lds_dwordx4 v[222:223], off
	s_barrier
	s_waitcnt lgkmcnt(0)
	v_mfma_f32_16x16x32_bf16 v[60:63], v[144:147], v[170:173], v[60:63]
	v_mfma_f32_16x16x32_bf16 v[56:59], v[162:165], v[170:173], v[56:59]
	v_mfma_f32_16x16x32_bf16 v[44:47], v[144:147], v[178:181], v[44:47]
	v_mfma_f32_16x16x32_bf16 v[40:43], v[162:165], v[178:181], v[40:43]
	v_mfma_f32_16x16x32_bf16 v[28:31], v[144:147], v[186:189], v[28:31]
	v_mfma_f32_16x16x32_bf16 v[24:27], v[162:165], v[186:189], v[24:27]
	v_mfma_f32_16x16x32_bf16 v[12:15], v[144:147], v[194:197], v[12:15]
	v_mfma_f32_16x16x32_bf16 v[8:11], v[162:165], v[194:197], v[8:11]
	v_mfma_f32_16x16x32_bf16 v[60:63], v[158:161], v[174:177], v[60:63]
	v_mfma_f32_16x16x32_bf16 v[56:59], v[166:169], v[174:177], v[56:59]
	v_mfma_f32_16x16x32_bf16 v[44:47], v[158:161], v[182:185], v[44:47]
	v_mfma_f32_16x16x32_bf16 v[40:43], v[166:169], v[182:185], v[40:43]
	v_mfma_f32_16x16x32_bf16 v[28:31], v[158:161], v[190:193], v[28:31]
	v_mfma_f32_16x16x32_bf16 v[24:27], v[166:169], v[190:193], v[24:27]
	v_mfma_f32_16x16x32_bf16 v[12:15], v[158:161], v[198:201], v[12:15]
	v_mfma_f32_16x16x32_bf16 v[8:11], v[166:169], v[198:201], v[8:11]
	s_barrier
	s_add_u32 s68, s50, 0x40000
	s_addc_u32 s69, s51, 0
	s_add_i32 s67, s72, s1
	s_mov_b32 m0, s67
	v_lshl_add_u64 v[144:145], s[68:69], 0, v[132:133]
	global_load_lds_dwordx4 v[144:145], off
	s_add_i32 m0, s67, 0x2000
	v_lshl_add_u64 v[144:145], s[68:69], 0, v[128:129]
	global_load_lds_dwordx4 v[144:145], off
	s_waitcnt vmcnt(6)
	s_barrier
	v_mfma_f32_16x16x32_bf16 v[52:55], v[202:205], v[170:173], v[52:55]
	v_mfma_f32_16x16x32_bf16 v[48:51], v[210:213], v[170:173], v[48:51]
	v_mfma_f32_16x16x32_bf16 v[36:39], v[202:205], v[178:181], v[36:39]
	v_mfma_f32_16x16x32_bf16 v[32:35], v[210:213], v[178:181], v[32:35]
	v_mfma_f32_16x16x32_bf16 v[20:23], v[202:205], v[186:189], v[20:23]
	v_mfma_f32_16x16x32_bf16 v[16:19], v[210:213], v[186:189], v[16:19]
	v_mfma_f32_16x16x32_bf16 v[4:7], v[202:205], v[194:197], v[4:7]
	v_mfma_f32_16x16x32_bf16 v[0:3], v[210:213], v[194:197], v[0:3]
	v_mfma_f32_16x16x32_bf16 v[52:55], v[206:209], v[174:177], v[52:55]
	v_mfma_f32_16x16x32_bf16 v[48:51], v[214:217], v[174:177], v[48:51]
	v_mfma_f32_16x16x32_bf16 v[36:39], v[206:209], v[182:185], v[36:39]
	v_mfma_f32_16x16x32_bf16 v[32:35], v[214:217], v[182:185], v[32:35]
	v_mfma_f32_16x16x32_bf16 v[20:23], v[206:209], v[190:193], v[20:23]
	v_mfma_f32_16x16x32_bf16 v[16:19], v[214:217], v[190:193], v[16:19]
	v_mfma_f32_16x16x32_bf16 v[4:7], v[206:209], v[198:201], v[4:7]
	v_mfma_f32_16x16x32_bf16 v[0:3], v[214:217], v[198:201], v[0:3]
	s_add_i32 s67, 0, 0x18000
	v_add_u32_e32 v166, s67, v151
	s_barrier
	ds_read_b128 v[144:147], v166
	ds_read_b128 v[158:161], v166 offset:1024
	ds_read_b128 v[162:165], v166 offset:2048
	ds_read_b128 v[166:169], v166 offset:3072
	s_add_u32 s52, s52, 0x40000
	s_addc_u32 s53, s53, 0
	s_mov_b32 m0, s54
	v_lshl_add_u64 v[202:203], s[52:53], 0, v[134:135]
	ds_read_b128 v[170:173], v156 offset:32768
	ds_read_b128 v[174:177], v156 offset:33792
	ds_read_b128 v[178:181], v156 offset:34816
	ds_read_b128 v[182:185], v156 offset:35840
	ds_read_b128 v[186:189], v156 offset:36864
	ds_read_b128 v[190:193], v156 offset:37888
	ds_read_b128 v[194:197], v156 offset:38912
	ds_read_b128 v[198:201], v156 offset:39936
	global_load_lds_dwordx4 v[202:203], off
	s_mov_b32 m0, s55
	v_lshl_add_u64 v[202:203], s[52:53], 0, v[130:131]
	global_load_lds_dwordx4 v[202:203], off
	s_barrier
	s_waitcnt lgkmcnt(0)
	v_mfma_f32_16x16x32_bf16 v[124:127], v[144:147], v[170:173], v[124:127]
	v_mfma_f32_16x16x32_bf16 v[120:123], v[162:165], v[170:173], v[120:123]
	v_mfma_f32_16x16x32_bf16 v[108:111], v[144:147], v[178:181], v[108:111]
	v_mfma_f32_16x16x32_bf16 v[104:107], v[162:165], v[178:181], v[104:107]
	v_mfma_f32_16x16x32_bf16 v[92:95], v[144:147], v[186:189], v[92:95]
	v_mfma_f32_16x16x32_bf16 v[88:91], v[162:165], v[186:189], v[88:91]
	v_mfma_f32_16x16x32_bf16 v[76:79], v[144:147], v[194:197], v[76:79]
	v_mfma_f32_16x16x32_bf16 v[72:75], v[162:165], v[194:197], v[72:75]
	v_mfma_f32_16x16x32_bf16 v[124:127], v[158:161], v[174:177], v[124:127]
	v_mfma_f32_16x16x32_bf16 v[120:123], v[166:169], v[174:177], v[120:123]
	v_mfma_f32_16x16x32_bf16 v[108:111], v[158:161], v[182:185], v[108:111]
	v_mfma_f32_16x16x32_bf16 v[104:107], v[166:169], v[182:185], v[104:107]
	v_mfma_f32_16x16x32_bf16 v[92:95], v[158:161], v[190:193], v[92:95]
	v_mfma_f32_16x16x32_bf16 v[88:91], v[166:169], v[190:193], v[88:91]
	v_mfma_f32_16x16x32_bf16 v[76:79], v[158:161], v[198:201], v[76:79]
	v_mfma_f32_16x16x32_bf16 v[72:75], v[166:169], v[198:201], v[72:75]
	s_barrier
	s_add_i32 s52, s67, s1
	v_add_u32_e32 v214, s97, v151
	v_lshl_add_u64 v[148:149], v[148:149], 0, s[20:21]
	s_mov_b32 m0, s52
	ds_read_b128 v[202:205], v214
	ds_read_b128 v[206:209], v214 offset:1024
	ds_read_b128 v[210:213], v214 offset:2048
	ds_read_b128 v[214:217], v214 offset:3072
	global_load_lds_dwordx4 v[148:149], off
	s_add_i32 m0, s52, 0x2000
	v_lshl_add_u64 v[148:149], v[218:219], 0, s[20:21]
	global_load_lds_dwordx4 v[148:149], off
	s_barrier
	s_waitcnt lgkmcnt(0)
	v_mfma_f32_16x16x32_bf16 v[116:119], v[202:205], v[170:173], v[116:119]
	v_mfma_f32_16x16x32_bf16 v[112:115], v[210:213], v[170:173], v[112:115]
	v_mfma_f32_16x16x32_bf16 v[100:103], v[202:205], v[178:181], v[100:103]
	v_mfma_f32_16x16x32_bf16 v[96:99], v[210:213], v[178:181], v[96:99]
	v_mfma_f32_16x16x32_bf16 v[84:87], v[202:205], v[186:189], v[84:87]
	v_mfma_f32_16x16x32_bf16 v[80:83], v[210:213], v[186:189], v[80:83]
	v_mfma_f32_16x16x32_bf16 v[68:71], v[202:205], v[194:197], v[68:71]
	v_mfma_f32_16x16x32_bf16 v[64:67], v[210:213], v[194:197], v[64:67]
	v_mfma_f32_16x16x32_bf16 v[116:119], v[206:209], v[174:177], v[116:119]
	v_mfma_f32_16x16x32_bf16 v[112:115], v[214:217], v[174:177], v[112:115]
	v_mfma_f32_16x16x32_bf16 v[100:103], v[206:209], v[182:185], v[100:103]
	v_mfma_f32_16x16x32_bf16 v[96:99], v[214:217], v[182:185], v[96:99]
	v_mfma_f32_16x16x32_bf16 v[84:87], v[206:209], v[190:193], v[84:87]
	v_mfma_f32_16x16x32_bf16 v[80:83], v[214:217], v[190:193], v[80:83]
	v_mfma_f32_16x16x32_bf16 v[68:71], v[206:209], v[198:201], v[68:71]
	v_mfma_f32_16x16x32_bf16 v[64:67], v[214:217], v[198:201], v[64:67]
	s_mov_b32 m0, s57
	v_lshl_add_u64 v[148:149], v[220:221], 0, s[20:21]
	s_barrier
	ds_read_b128 v[170:173], v156 offset:49152
	ds_read_b128 v[174:177], v156 offset:50176
	ds_read_b128 v[178:181], v156 offset:51200
	ds_read_b128 v[182:185], v156 offset:52224
	ds_read_b128 v[186:189], v156 offset:53248
	ds_read_b128 v[190:193], v156 offset:54272
	ds_read_b128 v[194:197], v156 offset:55296
	ds_read_b128 v[198:201], v156 offset:56320
	global_load_lds_dwordx4 v[148:149], off
	s_mov_b32 m0, s58
	v_lshl_add_u64 v[148:149], v[222:223], 0, s[20:21]
	global_load_lds_dwordx4 v[148:149], off
	s_barrier
	s_waitcnt lgkmcnt(0)
	v_mfma_f32_16x16x32_bf16 v[60:63], v[144:147], v[170:173], v[60:63]
	v_mfma_f32_16x16x32_bf16 v[56:59], v[162:165], v[170:173], v[56:59]
	v_mfma_f32_16x16x32_bf16 v[44:47], v[144:147], v[178:181], v[44:47]
	v_mfma_f32_16x16x32_bf16 v[40:43], v[162:165], v[178:181], v[40:43]
	v_mfma_f32_16x16x32_bf16 v[28:31], v[144:147], v[186:189], v[28:31]
	v_mfma_f32_16x16x32_bf16 v[24:27], v[162:165], v[186:189], v[24:27]
	v_mfma_f32_16x16x32_bf16 v[12:15], v[144:147], v[194:197], v[12:15]
	v_mfma_f32_16x16x32_bf16 v[8:11], v[162:165], v[194:197], v[8:11]
	v_mfma_f32_16x16x32_bf16 v[60:63], v[158:161], v[174:177], v[60:63]
	v_mfma_f32_16x16x32_bf16 v[56:59], v[166:169], v[174:177], v[56:59]
	v_mfma_f32_16x16x32_bf16 v[44:47], v[158:161], v[182:185], v[44:47]
	v_mfma_f32_16x16x32_bf16 v[40:43], v[166:169], v[182:185], v[40:43]
	v_mfma_f32_16x16x32_bf16 v[28:31], v[158:161], v[190:193], v[28:31]
	v_mfma_f32_16x16x32_bf16 v[24:27], v[166:169], v[190:193], v[24:27]
	v_mfma_f32_16x16x32_bf16 v[12:15], v[158:161], v[198:201], v[12:15]
	v_mfma_f32_16x16x32_bf16 v[8:11], v[166:169], v[198:201], v[8:11]
	s_barrier
	s_add_u32 s50, s50, 0x40080
	s_addc_u32 s51, s51, 0
	s_add_i32 s52, s97, s1
	s_mov_b32 m0, s52
	v_lshl_add_u64 v[144:145], s[50:51], 0, v[132:133]
	global_load_lds_dwordx4 v[144:145], off
	s_add_i32 m0, s52, 0x2000
	v_lshl_add_u64 v[144:145], s[50:51], 0, v[128:129]
	global_load_lds_dwordx4 v[144:145], off
	s_waitcnt vmcnt(6)
	s_barrier
	v_mfma_f32_16x16x32_bf16 v[52:55], v[202:205], v[170:173], v[52:55]
	v_mfma_f32_16x16x32_bf16 v[48:51], v[210:213], v[170:173], v[48:51]
	v_mfma_f32_16x16x32_bf16 v[36:39], v[202:205], v[178:181], v[36:39]
	v_mfma_f32_16x16x32_bf16 v[32:35], v[210:213], v[178:181], v[32:35]
	v_mfma_f32_16x16x32_bf16 v[20:23], v[202:205], v[186:189], v[20:23]
	v_mfma_f32_16x16x32_bf16 v[16:19], v[210:213], v[186:189], v[16:19]
	v_mfma_f32_16x16x32_bf16 v[4:7], v[202:205], v[194:197], v[4:7]
	v_mfma_f32_16x16x32_bf16 v[0:3], v[210:213], v[194:197], v[0:3]
	v_mfma_f32_16x16x32_bf16 v[52:55], v[206:209], v[174:177], v[52:55]
	v_mfma_f32_16x16x32_bf16 v[48:51], v[214:217], v[174:177], v[48:51]
	v_mfma_f32_16x16x32_bf16 v[36:39], v[206:209], v[182:185], v[36:39]
	v_mfma_f32_16x16x32_bf16 v[32:35], v[214:217], v[182:185], v[32:35]
	v_mfma_f32_16x16x32_bf16 v[20:23], v[206:209], v[190:193], v[20:23]
	v_mfma_f32_16x16x32_bf16 v[16:19], v[214:217], v[190:193], v[16:19]
	v_mfma_f32_16x16x32_bf16 v[4:7], v[206:209], v[198:201], v[4:7]
	v_mfma_f32_16x16x32_bf16 v[0:3], v[214:217], v[198:201], v[0:3]
	s_add_i32 s66, s66, 2
	s_add_u32 s48, s48, 0x100
	s_addc_u32 s49, s49, 0
	s_add_u32 s64, s64, 0x100
	s_addc_u32 s65, s65, 0
	s_cmp_gt_u32 s66, 13
	s_barrier
	s_cbranch_scc0 .LBB0_603
	v_lshl_add_u32 v146, s46, 8, v150
	v_lshl_or_b32 v144, s61, 8, v152
	v_ashrrev_i32_e32 v147, 31, v146
	v_lshlrev_b64 v[148:149], 12, v[146:147]
	v_ashrrev_i32_e32 v145, 31, v144
	v_lshl_add_u64 v[148:149], s[6:7], 0, v[148:149]
	v_lshlrev_b64 v[144:145], 1, v[144:145]
	v_lshlrev_b64 v[162:163], 11, v[146:147]
	v_lshl_add_u64 v[148:149], v[148:149], 0, v[144:145]
	v_lshl_add_u64 v[162:163], s[14:15], 0, v[162:163]
	global_load_dwordx4 v[158:161], v[148:149], off offset:2048
	v_lshl_add_u64 v[182:183], v[162:163], 0, v[144:145]
	global_load_dwordx4 v[162:165], v[182:183], off
	global_load_dwordx4 v[166:169], v[148:149], off offset:2304
	global_load_dwordx4 v[170:173], v[182:183], off offset:256
	v_or_b32_e32 v148, 16, v146
	v_ashrrev_i32_e32 v149, 31, v148
	v_lshlrev_b64 v[174:175], 12, v[148:149]
	v_lshlrev_b64 v[148:149], 11, v[148:149]
	v_lshl_add_u64 v[148:149], s[14:15], 0, v[148:149]
	v_lshl_add_u64 v[174:175], s[6:7], 0, v[174:175]
	v_lshl_add_u64 v[148:149], v[148:149], 0, v[144:145]
	v_lshl_add_u64 v[184:185], v[174:175], 0, v[144:145]
	global_load_dwordx4 v[174:177], v[148:149], off
	global_load_dwordx4 v[178:181], v[148:149], off offset:256
	s_and_b64 vcc, exec, s[4:5]
	s_mov_b32 s61, s22
	s_mov_b32 s46, s24
	s_mov_b64 s[50:51], s[44:45]
	s_mov_b64 s[48:49], s[40:41]
	s_waitcnt vmcnt(0)
	v_lshlrev_b32_e32 v190, 16, v162
	v_lshlrev_b32_e32 v186, 16, v158
	v_and_b32_e32 v187, 0xffff0000, v158
	v_lshlrev_b32_e32 v158, 16, v159
	v_and_b32_e32 v159, 0xffff0000, v159
	v_lshlrev_b32_e32 v188, 16, v160
	v_and_b32_e32 v189, 0xffff0000, v160
	v_lshlrev_b32_e32 v160, 16, v161
	v_and_b32_e32 v161, 0xffff0000, v161
	v_and_b32_e32 v191, 0xffff0000, v162
	v_lshlrev_b32_e32 v162, 16, v163
	v_and_b32_e32 v163, 0xffff0000, v163
	v_lshlrev_b32_e32 v192, 16, v164
	v_and_b32_e32 v193, 0xffff0000, v164
	v_lshlrev_b32_e32 v164, 16, v165
	v_and_b32_e32 v165, 0xffff0000, v165
	v_lshlrev_b32_e32 v194, 16, v166
	v_and_b32_e32 v195, 0xffff0000, v166
	v_lshlrev_b32_e32 v166, 16, v167
	v_and_b32_e32 v167, 0xffff0000, v167
	v_lshlrev_b32_e32 v196, 16, v168
	v_and_b32_e32 v197, 0xffff0000, v168
	v_lshlrev_b32_e32 v168, 16, v169
	v_and_b32_e32 v169, 0xffff0000, v169
	v_lshlrev_b32_e32 v198, 16, v170
	v_and_b32_e32 v199, 0xffff0000, v170
	v_lshlrev_b32_e32 v170, 16, v171
	v_and_b32_e32 v171, 0xffff0000, v171
	v_lshlrev_b32_e32 v200, 16, v172
	v_and_b32_e32 v201, 0xffff0000, v172
	v_lshlrev_b32_e32 v172, 16, v173
	v_and_b32_e32 v173, 0xffff0000, v173
	v_pk_fma_f32 v[126:127], v[126:127], v[158:159], v[162:163]
	v_pk_fma_f32 v[124:125], v[124:125], v[186:187], v[190:191]
	v_pk_fma_f32 v[122:123], v[122:123], v[160:161], v[164:165]
	v_pk_fma_f32 v[120:121], v[120:121], v[188:189], v[192:193]
	v_pk_fma_f32 v[158:159], v[118:119], v[166:167], v[170:171]
	v_pk_fma_f32 v[160:161], v[116:117], v[194:195], v[198:199]
	v_cvt_pk_bf16_f32 v116, v124, v125
	v_cvt_pk_bf16_f32 v117, v126, v127
	v_cvt_pk_bf16_f32 v118, v120, v121
	v_cvt_pk_bf16_f32 v119, v122, v123
	v_pk_fma_f32 v[120:121], v[114:115], v[168:169], v[172:173]
	v_pk_fma_f32 v[114:115], v[112:113], v[196:197], v[200:201]
	global_store_dwordx4 v[182:183], v[116:119], off
	v_cvt_pk_bf16_f32 v112, v160, v161
	v_cvt_pk_bf16_f32 v113, v158, v159
	v_cvt_pk_bf16_f32 v114, v114, v115
	v_cvt_pk_bf16_f32 v115, v120, v121
	global_load_dwordx4 v[116:119], v[184:185], off offset:2048
	v_lshlrev_b32_e32 v162, 16, v174
	global_store_dwordx4 v[182:183], v[112:115], off offset:256
	global_load_dwordx4 v[120:123], v[184:185], off offset:2304
	v_and_b32_e32 v163, 0xffff0000, v174
	v_or_b32_e32 v112, 32, v146
	v_ashrrev_i32_e32 v113, 31, v112
	v_lshlrev_b64 v[114:115], 12, v[112:113]
	v_lshlrev_b64 v[112:113], 11, v[112:113]
	v_lshlrev_b32_e32 v164, 16, v175
	v_and_b32_e32 v165, 0xffff0000, v175
	v_lshlrev_b32_e32 v166, 16, v176
	v_and_b32_e32 v167, 0xffff0000, v176
	v_lshlrev_b32_e32 v168, 16, v177
	v_and_b32_e32 v169, 0xffff0000, v177
	v_lshlrev_b32_e32 v170, 16, v178
	v_and_b32_e32 v171, 0xffff0000, v178
	v_lshlrev_b32_e32 v172, 16, v179
	v_and_b32_e32 v173, 0xffff0000, v179
	v_lshlrev_b32_e32 v174, 16, v180
	v_and_b32_e32 v175, 0xffff0000, v180
	v_lshlrev_b32_e32 v176, 16, v181
	v_and_b32_e32 v177, 0xffff0000, v181
	v_lshl_add_u64 v[112:113], s[14:15], 0, v[112:113]
	v_lshl_add_u64 v[114:115], s[6:7], 0, v[114:115]
	v_lshl_add_u64 v[112:113], v[112:113], 0, v[144:145]
	v_lshl_add_u64 v[114:115], v[114:115], 0, v[144:145]
	global_load_dwordx4 v[124:127], v[112:113], off
	global_load_dwordx4 v[158:161], v[112:113], off offset:256
	s_waitcnt vmcnt(0)
	v_lshlrev_b32_e32 v178, 16, v116
	v_and_b32_e32 v179, 0xffff0000, v116
	v_lshlrev_b32_e32 v116, 16, v117
	v_and_b32_e32 v117, 0xffff0000, v117
	v_lshlrev_b32_e32 v180, 16, v118
	v_and_b32_e32 v181, 0xffff0000, v118
	v_lshlrev_b32_e32 v118, 16, v119
	v_and_b32_e32 v119, 0xffff0000, v119
	v_lshlrev_b32_e32 v182, 16, v120
	v_and_b32_e32 v183, 0xffff0000, v120
	v_lshlrev_b32_e32 v120, 16, v121
	v_and_b32_e32 v121, 0xffff0000, v121
	v_lshlrev_b32_e32 v184, 16, v122
	v_and_b32_e32 v185, 0xffff0000, v122
	v_lshlrev_b32_e32 v122, 16, v123
	v_and_b32_e32 v123, 0xffff0000, v123
	v_pk_fma_f32 v[110:111], v[110:111], v[116:117], v[164:165]
	v_pk_fma_f32 v[108:109], v[108:109], v[178:179], v[162:163]
	v_pk_fma_f32 v[106:107], v[106:107], v[118:119], v[168:169]
	v_pk_fma_f32 v[104:105], v[104:105], v[180:181], v[166:167]
	v_pk_fma_f32 v[116:117], v[102:103], v[120:121], v[172:173]
	v_pk_fma_f32 v[118:119], v[100:101], v[182:183], v[170:171]
	v_cvt_pk_bf16_f32 v100, v108, v109
	v_cvt_pk_bf16_f32 v101, v110, v111
	v_cvt_pk_bf16_f32 v102, v104, v105
	v_cvt_pk_bf16_f32 v103, v106, v107
	v_pk_fma_f32 v[104:105], v[98:99], v[122:123], v[176:177]
	v_pk_fma_f32 v[98:99], v[96:97], v[184:185], v[174:175]
	global_store_dwordx4 v[148:149], v[100:103], off
	v_cvt_pk_bf16_f32 v96, v118, v119
	v_cvt_pk_bf16_f32 v97, v116, v117
	v_cvt_pk_bf16_f32 v98, v98, v99
	v_cvt_pk_bf16_f32 v99, v104, v105
	global_load_dwordx4 v[100:103], v[114:115], off offset:2048
	v_lshlrev_b32_e32 v118, 16, v124
	global_store_dwordx4 v[148:149], v[96:99], off offset:256
	global_load_dwordx4 v[104:107], v[114:115], off offset:2304
	v_and_b32_e32 v119, 0xffff0000, v124
	v_or_b32_e32 v96, 48, v146
	v_ashrrev_i32_e32 v97, 31, v96
	v_lshlrev_b64 v[98:99], 12, v[96:97]
	v_lshlrev_b64 v[96:97], 11, v[96:97]
	v_lshlrev_b32_e32 v120, 16, v125
	v_and_b32_e32 v121, 0xffff0000, v125
	v_lshlrev_b32_e32 v122, 16, v126
	v_and_b32_e32 v123, 0xffff0000, v126
	v_lshlrev_b32_e32 v124, 16, v127
	v_and_b32_e32 v125, 0xffff0000, v127
	v_lshl_add_u64 v[96:97], s[14:15], 0, v[96:97]
	v_lshlrev_b32_e32 v126, 16, v158
	v_and_b32_e32 v127, 0xffff0000, v158
	v_lshlrev_b32_e32 v148, 16, v159
	v_and_b32_e32 v149, 0xffff0000, v159
	v_lshlrev_b32_e32 v158, 16, v160
	v_and_b32_e32 v159, 0xffff0000, v160
	v_lshlrev_b32_e32 v160, 16, v161
	v_and_b32_e32 v161, 0xffff0000, v161
	v_lshl_add_u64 v[98:99], s[6:7], 0, v[98:99]
	v_lshl_add_u64 v[96:97], v[96:97], 0, v[144:145]
	v_lshl_add_u64 v[98:99], v[98:99], 0, v[144:145]
	global_load_dwordx4 v[108:111], v[96:97], off
	global_load_dwordx4 v[114:117], v[96:97], off offset:256
	s_waitcnt vmcnt(0)
	v_lshlrev_b32_e32 v162, 16, v100
	v_and_b32_e32 v163, 0xffff0000, v100
	v_lshlrev_b32_e32 v100, 16, v101
	v_and_b32_e32 v101, 0xffff0000, v101
	v_lshlrev_b32_e32 v164, 16, v102
	v_and_b32_e32 v165, 0xffff0000, v102
	v_lshlrev_b32_e32 v102, 16, v103
	v_and_b32_e32 v103, 0xffff0000, v103
	v_lshlrev_b32_e32 v166, 16, v104
	v_and_b32_e32 v167, 0xffff0000, v104
	v_lshlrev_b32_e32 v104, 16, v105
	v_and_b32_e32 v105, 0xffff0000, v105
	v_lshlrev_b32_e32 v168, 16, v106
	v_and_b32_e32 v169, 0xffff0000, v106
	v_lshlrev_b32_e32 v106, 16, v107
	v_and_b32_e32 v107, 0xffff0000, v107
	v_pk_fma_f32 v[94:95], v[94:95], v[100:101], v[120:121]
	v_pk_fma_f32 v[92:93], v[92:93], v[162:163], v[118:119]
	v_pk_fma_f32 v[90:91], v[90:91], v[102:103], v[124:125]
	v_pk_fma_f32 v[88:89], v[88:89], v[164:165], v[122:123]
	v_pk_fma_f32 v[100:101], v[86:87], v[104:105], v[148:149]
	v_pk_fma_f32 v[102:103], v[84:85], v[166:167], v[126:127]
	v_cvt_pk_bf16_f32 v84, v92, v93
	v_cvt_pk_bf16_f32 v85, v94, v95
	v_cvt_pk_bf16_f32 v86, v88, v89
	v_cvt_pk_bf16_f32 v87, v90, v91
	v_pk_fma_f32 v[88:89], v[82:83], v[106:107], v[160:161]
	v_pk_fma_f32 v[82:83], v[80:81], v[168:169], v[158:159]
	global_store_dwordx4 v[112:113], v[84:87], off
	v_cvt_pk_bf16_f32 v80, v102, v103
	v_cvt_pk_bf16_f32 v81, v100, v101
	v_cvt_pk_bf16_f32 v82, v82, v83
	v_cvt_pk_bf16_f32 v83, v88, v89
	global_load_dwordx4 v[84:87], v[98:99], off offset:2048
	v_lshlrev_b32_e32 v102, 16, v108
	global_store_dwordx4 v[112:113], v[80:83], off offset:256
	global_load_dwordx4 v[88:91], v[98:99], off offset:2304
	v_and_b32_e32 v103, 0xffff0000, v108
	v_add_u32_e32 v80, 0x80, v146
	v_ashrrev_i32_e32 v81, 31, v80
	v_lshlrev_b64 v[82:83], 12, v[80:81]
	v_lshlrev_b64 v[80:81], 11, v[80:81]
	v_lshlrev_b32_e32 v104, 16, v109
	v_and_b32_e32 v105, 0xffff0000, v109
	v_lshlrev_b32_e32 v106, 16, v110
	v_and_b32_e32 v107, 0xffff0000, v110
	v_lshlrev_b32_e32 v108, 16, v111
	v_and_b32_e32 v109, 0xffff0000, v111
	v_lshl_add_u64 v[80:81], s[14:15], 0, v[80:81]
	v_lshlrev_b32_e32 v110, 16, v114
	v_and_b32_e32 v111, 0xffff0000, v114
	v_lshlrev_b32_e32 v112, 16, v115
	v_and_b32_e32 v113, 0xffff0000, v115
	v_lshlrev_b32_e32 v114, 16, v116
	v_and_b32_e32 v115, 0xffff0000, v116
	v_lshlrev_b32_e32 v116, 16, v117
	v_and_b32_e32 v117, 0xffff0000, v117
	v_lshl_add_u64 v[82:83], s[6:7], 0, v[82:83]
	v_lshl_add_u64 v[80:81], v[80:81], 0, v[144:145]
	v_lshl_add_u64 v[82:83], v[82:83], 0, v[144:145]
	global_load_dwordx4 v[92:95], v[80:81], off
	global_load_dwordx4 v[98:101], v[80:81], off offset:256
	s_waitcnt vmcnt(0)
	v_lshlrev_b32_e32 v118, 16, v84
	v_and_b32_e32 v119, 0xffff0000, v84
	v_lshlrev_b32_e32 v84, 16, v85
	v_and_b32_e32 v85, 0xffff0000, v85
	v_lshlrev_b32_e32 v120, 16, v86
	v_and_b32_e32 v121, 0xffff0000, v86
	v_lshlrev_b32_e32 v86, 16, v87
	v_and_b32_e32 v87, 0xffff0000, v87
	v_lshlrev_b32_e32 v122, 16, v88
	v_and_b32_e32 v123, 0xffff0000, v88
	v_lshlrev_b32_e32 v88, 16, v89
	v_and_b32_e32 v89, 0xffff0000, v89
	v_lshlrev_b32_e32 v124, 16, v90
	v_and_b32_e32 v125, 0xffff0000, v90
	v_lshlrev_b32_e32 v90, 16, v91
	v_and_b32_e32 v91, 0xffff0000, v91
	v_pk_fma_f32 v[78:79], v[78:79], v[84:85], v[104:105]
	v_pk_fma_f32 v[76:77], v[76:77], v[118:119], v[102:103]
	v_pk_fma_f32 v[74:75], v[74:75], v[86:87], v[108:109]
	v_pk_fma_f32 v[72:73], v[72:73], v[120:121], v[106:107]
	v_pk_fma_f32 v[84:85], v[70:71], v[88:89], v[112:113]
	v_pk_fma_f32 v[86:87], v[68:69], v[122:123], v[110:111]
	v_cvt_pk_bf16_f32 v68, v76, v77
	v_cvt_pk_bf16_f32 v69, v78, v79
	v_cvt_pk_bf16_f32 v70, v72, v73
	v_cvt_pk_bf16_f32 v71, v74, v75
	v_pk_fma_f32 v[72:73], v[66:67], v[90:91], v[116:117]
	v_pk_fma_f32 v[66:67], v[64:65], v[124:125], v[114:115]
	global_store_dwordx4 v[96:97], v[68:71], off
	v_cvt_pk_bf16_f32 v64, v86, v87
	v_cvt_pk_bf16_f32 v65, v84, v85
	v_cvt_pk_bf16_f32 v66, v66, v67
	v_cvt_pk_bf16_f32 v67, v72, v73
	global_load_dwordx4 v[68:71], v[82:83], off offset:2048
	v_lshlrev_b32_e32 v86, 16, v92
	global_store_dwordx4 v[96:97], v[64:67], off offset:256
	global_load_dwordx4 v[72:75], v[82:83], off offset:2304
	v_and_b32_e32 v87, 0xffff0000, v92
	v_add_u32_e32 v64, 0x90, v146
	v_ashrrev_i32_e32 v65, 31, v64
	v_lshlrev_b64 v[66:67], 12, v[64:65]
	v_lshlrev_b64 v[64:65], 11, v[64:65]
	v_lshlrev_b32_e32 v88, 16, v93
	v_and_b32_e32 v89, 0xffff0000, v93
	v_lshlrev_b32_e32 v90, 16, v94
	v_and_b32_e32 v91, 0xffff0000, v94
	v_lshlrev_b32_e32 v92, 16, v95
	v_and_b32_e32 v93, 0xffff0000, v95
	v_lshl_add_u64 v[64:65], s[14:15], 0, v[64:65]
	v_lshlrev_b32_e32 v94, 16, v98
	v_and_b32_e32 v95, 0xffff0000, v98
	v_lshlrev_b32_e32 v96, 16, v99
	v_and_b32_e32 v97, 0xffff0000, v99
	v_lshlrev_b32_e32 v98, 16, v100
	v_and_b32_e32 v99, 0xffff0000, v100
	v_lshlrev_b32_e32 v100, 16, v101
	v_and_b32_e32 v101, 0xffff0000, v101
	v_lshl_add_u64 v[66:67], s[6:7], 0, v[66:67]
	v_lshl_add_u64 v[64:65], v[64:65], 0, v[144:145]
	v_lshl_add_u64 v[66:67], v[66:67], 0, v[144:145]
	global_load_dwordx4 v[76:79], v[64:65], off
	global_load_dwordx4 v[82:85], v[64:65], off offset:256
	s_waitcnt vmcnt(0)
	v_lshlrev_b32_e32 v102, 16, v68
	v_and_b32_e32 v103, 0xffff0000, v68
	v_lshlrev_b32_e32 v68, 16, v69
	v_and_b32_e32 v69, 0xffff0000, v69
	v_lshlrev_b32_e32 v104, 16, v70
	v_and_b32_e32 v105, 0xffff0000, v70
	v_lshlrev_b32_e32 v70, 16, v71
	v_and_b32_e32 v71, 0xffff0000, v71
	v_lshlrev_b32_e32 v106, 16, v72
	v_and_b32_e32 v107, 0xffff0000, v72
	v_lshlrev_b32_e32 v72, 16, v73
	v_and_b32_e32 v73, 0xffff0000, v73
	v_lshlrev_b32_e32 v108, 16, v74
	v_and_b32_e32 v109, 0xffff0000, v74
	v_lshlrev_b32_e32 v74, 16, v75
	v_and_b32_e32 v75, 0xffff0000, v75
	v_pk_fma_f32 v[62:63], v[62:63], v[68:69], v[88:89]
	v_pk_fma_f32 v[60:61], v[60:61], v[102:103], v[86:87]
	v_pk_fma_f32 v[58:59], v[58:59], v[70:71], v[92:93]
	v_pk_fma_f32 v[56:57], v[56:57], v[104:105], v[90:91]
	v_pk_fma_f32 v[68:69], v[54:55], v[72:73], v[96:97]
	v_pk_fma_f32 v[70:71], v[52:53], v[106:107], v[94:95]
	v_cvt_pk_bf16_f32 v52, v60, v61
	v_cvt_pk_bf16_f32 v53, v62, v63
	v_cvt_pk_bf16_f32 v54, v56, v57
	v_cvt_pk_bf16_f32 v55, v58, v59
	v_pk_fma_f32 v[56:57], v[50:51], v[74:75], v[100:101]
	v_pk_fma_f32 v[50:51], v[48:49], v[108:109], v[98:99]
	global_store_dwordx4 v[80:81], v[52:55], off
	v_cvt_pk_bf16_f32 v48, v70, v71
	v_cvt_pk_bf16_f32 v49, v68, v69
	v_cvt_pk_bf16_f32 v50, v50, v51
	v_cvt_pk_bf16_f32 v51, v56, v57
	global_load_dwordx4 v[52:55], v[66:67], off offset:2048
	v_lshlrev_b32_e32 v70, 16, v76
	global_store_dwordx4 v[80:81], v[48:51], off offset:256
	global_load_dwordx4 v[56:59], v[66:67], off offset:2304
	v_and_b32_e32 v71, 0xffff0000, v76
	v_add_u32_e32 v48, 0xa0, v146
	v_ashrrev_i32_e32 v49, 31, v48
	v_lshlrev_b64 v[50:51], 12, v[48:49]
	v_lshlrev_b64 v[48:49], 11, v[48:49]
	v_lshlrev_b32_e32 v72, 16, v77
	v_and_b32_e32 v73, 0xffff0000, v77
	v_lshlrev_b32_e32 v74, 16, v78
	v_and_b32_e32 v75, 0xffff0000, v78
	v_lshlrev_b32_e32 v76, 16, v79
	v_and_b32_e32 v77, 0xffff0000, v79
	v_lshl_add_u64 v[48:49], s[14:15], 0, v[48:49]
	v_lshlrev_b32_e32 v78, 16, v82
	v_and_b32_e32 v79, 0xffff0000, v82
	v_lshlrev_b32_e32 v80, 16, v83
	v_and_b32_e32 v81, 0xffff0000, v83
	v_lshlrev_b32_e32 v82, 16, v84
	v_and_b32_e32 v83, 0xffff0000, v84
	v_lshlrev_b32_e32 v84, 16, v85
	v_and_b32_e32 v85, 0xffff0000, v85
	v_lshl_add_u64 v[50:51], s[6:7], 0, v[50:51]
	v_lshl_add_u64 v[48:49], v[48:49], 0, v[144:145]
	v_lshl_add_u64 v[50:51], v[50:51], 0, v[144:145]
	global_load_dwordx4 v[60:63], v[48:49], off
	global_load_dwordx4 v[66:69], v[48:49], off offset:256
	s_waitcnt vmcnt(0)
	v_lshlrev_b32_e32 v86, 16, v52
	v_and_b32_e32 v87, 0xffff0000, v52
	v_lshlrev_b32_e32 v52, 16, v53
	v_and_b32_e32 v53, 0xffff0000, v53
	v_lshlrev_b32_e32 v88, 16, v54
	v_and_b32_e32 v89, 0xffff0000, v54
	v_lshlrev_b32_e32 v54, 16, v55
	v_and_b32_e32 v55, 0xffff0000, v55
	v_lshlrev_b32_e32 v90, 16, v56
	v_and_b32_e32 v91, 0xffff0000, v56
	v_lshlrev_b32_e32 v56, 16, v57
	v_and_b32_e32 v57, 0xffff0000, v57
	v_lshlrev_b32_e32 v92, 16, v58
	v_and_b32_e32 v93, 0xffff0000, v58
	v_lshlrev_b32_e32 v58, 16, v59
	v_and_b32_e32 v59, 0xffff0000, v59
	v_pk_fma_f32 v[46:47], v[46:47], v[52:53], v[72:73]
	v_pk_fma_f32 v[44:45], v[44:45], v[86:87], v[70:71]
	v_pk_fma_f32 v[42:43], v[42:43], v[54:55], v[76:77]
	v_pk_fma_f32 v[40:41], v[40:41], v[88:89], v[74:75]
	v_pk_fma_f32 v[52:53], v[38:39], v[56:57], v[80:81]
	v_pk_fma_f32 v[54:55], v[36:37], v[90:91], v[78:79]
	v_cvt_pk_bf16_f32 v36, v44, v45
	v_cvt_pk_bf16_f32 v37, v46, v47
	v_cvt_pk_bf16_f32 v38, v40, v41
	v_cvt_pk_bf16_f32 v39, v42, v43
	v_pk_fma_f32 v[40:41], v[34:35], v[58:59], v[84:85]
	v_pk_fma_f32 v[34:35], v[32:33], v[92:93], v[82:83]
	global_store_dwordx4 v[64:65], v[36:39], off
	v_cvt_pk_bf16_f32 v32, v54, v55
	v_cvt_pk_bf16_f32 v33, v52, v53
	v_cvt_pk_bf16_f32 v34, v34, v35
	v_cvt_pk_bf16_f32 v35, v40, v41
	global_load_dwordx4 v[36:39], v[50:51], off offset:2048
	v_add_u32_e32 v40, 0xb0, v146
	global_store_dwordx4 v[64:65], v[32:35], off offset:256
	global_load_dwordx4 v[32:35], v[50:51], off offset:2304
	v_ashrrev_i32_e32 v41, 31, v40
	v_lshlrev_b64 v[42:43], 12, v[40:41]
	v_lshlrev_b64 v[40:41], 11, v[40:41]
	v_lshlrev_b32_e32 v54, 16, v60
	v_and_b32_e32 v55, 0xffff0000, v60
	v_lshlrev_b32_e32 v56, 16, v61
	v_and_b32_e32 v57, 0xffff0000, v61
	v_lshlrev_b32_e32 v58, 16, v62
	v_and_b32_e32 v59, 0xffff0000, v62
	v_lshlrev_b32_e32 v60, 16, v63
	v_and_b32_e32 v61, 0xffff0000, v63
	v_lshl_add_u64 v[40:41], s[14:15], 0, v[40:41]
	v_lshlrev_b32_e32 v62, 16, v66
	v_and_b32_e32 v63, 0xffff0000, v66
	v_lshlrev_b32_e32 v64, 16, v67
	v_and_b32_e32 v65, 0xffff0000, v67
	v_lshlrev_b32_e32 v66, 16, v68
	v_and_b32_e32 v67, 0xffff0000, v68
	v_lshlrev_b32_e32 v68, 16, v69
	v_and_b32_e32 v69, 0xffff0000, v69
	v_lshl_add_u64 v[42:43], s[6:7], 0, v[42:43]
	v_lshl_add_u64 v[52:53], v[40:41], 0, v[144:145]
	v_lshl_add_u64 v[50:51], v[42:43], 0, v[144:145]
	global_load_dwordx4 v[40:43], v[52:53], off
	global_load_dwordx4 v[44:47], v[52:53], off offset:256
	s_waitcnt vmcnt(0)
	v_lshlrev_b32_e32 v70, 16, v36
	v_and_b32_e32 v71, 0xffff0000, v36
	v_lshlrev_b32_e32 v36, 16, v37
	v_and_b32_e32 v37, 0xffff0000, v37
	v_lshlrev_b32_e32 v72, 16, v38
	v_and_b32_e32 v73, 0xffff0000, v38
	v_lshlrev_b32_e32 v38, 16, v39
	v_and_b32_e32 v39, 0xffff0000, v39
	v_lshlrev_b32_e32 v74, 16, v32
	v_and_b32_e32 v75, 0xffff0000, v32
	v_lshlrev_b32_e32 v32, 16, v33
	v_and_b32_e32 v33, 0xffff0000, v33
	v_lshlrev_b32_e32 v76, 16, v34
	v_and_b32_e32 v77, 0xffff0000, v34
	v_lshlrev_b32_e32 v34, 16, v35
	v_and_b32_e32 v35, 0xffff0000, v35
	v_pk_fma_f32 v[30:31], v[30:31], v[36:37], v[56:57]
	v_pk_fma_f32 v[28:29], v[28:29], v[70:71], v[54:55]
	v_pk_fma_f32 v[26:27], v[26:27], v[38:39], v[60:61]
	v_pk_fma_f32 v[24:25], v[24:25], v[72:73], v[58:59]
	v_pk_fma_f32 v[32:33], v[22:23], v[32:33], v[64:65]
	v_pk_fma_f32 v[36:37], v[20:21], v[74:75], v[62:63]
	v_cvt_pk_bf16_f32 v20, v28, v29
	v_cvt_pk_bf16_f32 v21, v30, v31
	v_cvt_pk_bf16_f32 v22, v24, v25
	v_cvt_pk_bf16_f32 v23, v26, v27
	v_pk_fma_f32 v[24:25], v[18:19], v[34:35], v[68:69]
	v_pk_fma_f32 v[18:19], v[16:17], v[76:77], v[66:67]
	global_store_dwordx4 v[48:49], v[20:23], off
	v_cvt_pk_bf16_f32 v16, v36, v37
	v_cvt_pk_bf16_f32 v17, v32, v33
	v_cvt_pk_bf16_f32 v18, v18, v19
	v_cvt_pk_bf16_f32 v19, v24, v25
	global_load_dwordx4 v[20:23], v[50:51], off offset:2048
	v_lshlrev_b32_e32 v24, 16, v40
	global_store_dwordx4 v[48:49], v[16:19], off offset:256
	global_load_dwordx4 v[16:19], v[50:51], off offset:2304
	v_and_b32_e32 v25, 0xffff0000, v40
	v_lshlrev_b32_e32 v26, 16, v41
	v_and_b32_e32 v27, 0xffff0000, v41
	v_lshlrev_b32_e32 v28, 16, v42
	v_and_b32_e32 v29, 0xffff0000, v42
	v_lshlrev_b32_e32 v30, 16, v43
	v_and_b32_e32 v31, 0xffff0000, v43
	v_lshlrev_b32_e32 v32, 16, v44
	v_and_b32_e32 v33, 0xffff0000, v44
	v_lshlrev_b32_e32 v34, 16, v45
	v_and_b32_e32 v35, 0xffff0000, v45
	v_lshlrev_b32_e32 v36, 16, v46
	v_and_b32_e32 v37, 0xffff0000, v46
	v_lshlrev_b32_e32 v38, 16, v47
	v_and_b32_e32 v39, 0xffff0000, v47
	s_waitcnt vmcnt(0)
	v_lshlrev_b32_e32 v40, 16, v20
	v_and_b32_e32 v41, 0xffff0000, v20
	v_lshlrev_b32_e32 v20, 16, v21
	v_and_b32_e32 v21, 0xffff0000, v21
	v_lshlrev_b32_e32 v42, 16, v22
	v_and_b32_e32 v43, 0xffff0000, v22
	v_lshlrev_b32_e32 v22, 16, v23
	v_and_b32_e32 v23, 0xffff0000, v23
	v_lshlrev_b32_e32 v44, 16, v16
	v_and_b32_e32 v45, 0xffff0000, v16
	v_lshlrev_b32_e32 v16, 16, v17
	v_and_b32_e32 v17, 0xffff0000, v17
	v_lshlrev_b32_e32 v46, 16, v18
	v_and_b32_e32 v47, 0xffff0000, v18
	v_lshlrev_b32_e32 v18, 16, v19
	v_and_b32_e32 v19, 0xffff0000, v19
	v_pk_fma_f32 v[14:15], v[14:15], v[20:21], v[26:27]
	v_pk_fma_f32 v[12:13], v[12:13], v[40:41], v[24:25]
	v_pk_fma_f32 v[10:11], v[10:11], v[22:23], v[30:31]
	v_pk_fma_f32 v[8:9], v[8:9], v[42:43], v[28:29]
	v_pk_fma_f32 v[6:7], v[6:7], v[16:17], v[34:35]
	v_pk_fma_f32 v[4:5], v[4:5], v[44:45], v[32:33]
	v_pk_fma_f32 v[16:17], v[2:3], v[18:19], v[38:39]
	v_pk_fma_f32 v[18:19], v[0:1], v[46:47], v[36:37]
	v_cvt_pk_bf16_f32 v0, v12, v13
	v_cvt_pk_bf16_f32 v1, v14, v15
	v_cvt_pk_bf16_f32 v2, v8, v9
	v_cvt_pk_bf16_f32 v3, v10, v11
	v_cvt_pk_bf16_f32 v4, v4, v5
	v_cvt_pk_bf16_f32 v5, v6, v7
	v_cvt_pk_bf16_f32 v6, v18, v19
	v_cvt_pk_bf16_f32 v7, v16, v17
	global_store_dwordx4 v[52:53], v[0:3], off
	global_store_dwordx4 v[52:53], v[4:7], off offset:256
	s_cbranch_vccz .LBB0_600
	s_waitcnt vmcnt(0)
	s_cmpk_gt_u32 s0, 0xff
	s_cbranch_scc1 .LBB0_607
	s_barrier

.LBB0_628:
	ds_read_b128 v[146:149], v159
	ds_read_b128 v[150:153], v159 offset:1024
	ds_read_b128 v[164:167], v159 offset:2048
	ds_read_b128 v[168:171], v159 offset:3072
	s_add_u32 s52, s50, 0xfffc0080
	s_addc_u32 s53, s51, -1
	s_cmp_eq_u32 s71, 12
	s_cselect_b32 s55, s25, s53
	s_cselect_b32 s54, s47, s52
	s_cselect_b32 s53, s23, s70
	s_cselect_b32 s52, s49, s69
	v_lshl_add_u64 v[204:205], s[50:51], 0, v[138:139]
	s_add_i32 m0, s33, 0xc000
	ds_read_b128 v[172:175], v160
	ds_read_b128 v[176:179], v160 offset:1024
	ds_read_b128 v[180:183], v160 offset:2048
	ds_read_b128 v[184:187], v160 offset:3072
	ds_read_b128 v[188:191], v160 offset:4096
	ds_read_b128 v[192:195], v160 offset:5120
	ds_read_b128 v[196:199], v160 offset:6144
	ds_read_b128 v[200:203], v160 offset:7168
	global_load_lds_dwordx4 v[204:205], off
	s_add_i32 m0, s33, 0xe000
	v_lshl_add_u64 v[204:205], s[50:51], 0, v[140:141]
	global_load_lds_dwordx4 v[204:205], off
	s_barrier
	s_waitcnt lgkmcnt(0)
	v_mfma_f32_16x16x32_bf16 v[124:127], v[146:149], v[172:175], v[124:127]
	v_mfma_f32_16x16x32_bf16 v[120:123], v[164:167], v[172:175], v[120:123]
	v_mfma_f32_16x16x32_bf16 v[108:111], v[146:149], v[180:183], v[108:111]
	v_mfma_f32_16x16x32_bf16 v[104:107], v[164:167], v[180:183], v[104:107]
	v_mfma_f32_16x16x32_bf16 v[92:95], v[146:149], v[188:191], v[92:95]
	v_mfma_f32_16x16x32_bf16 v[88:91], v[164:167], v[188:191], v[88:91]
	v_mfma_f32_16x16x32_bf16 v[76:79], v[146:149], v[196:199], v[76:79]
	v_mfma_f32_16x16x32_bf16 v[72:75], v[164:167], v[196:199], v[72:75]
	v_mfma_f32_16x16x32_bf16 v[124:127], v[150:153], v[176:179], v[124:127]
	v_mfma_f32_16x16x32_bf16 v[120:123], v[168:171], v[176:179], v[120:123]
	v_mfma_f32_16x16x32_bf16 v[108:111], v[150:153], v[184:187], v[108:111]
	v_mfma_f32_16x16x32_bf16 v[104:107], v[168:171], v[184:187], v[104:107]
	v_mfma_f32_16x16x32_bf16 v[92:95], v[150:153], v[192:195], v[92:95]
	v_mfma_f32_16x16x32_bf16 v[88:91], v[168:171], v[192:195], v[88:91]
	v_mfma_f32_16x16x32_bf16 v[76:79], v[150:153], v[200:203], v[76:79]
	v_mfma_f32_16x16x32_bf16 v[72:75], v[168:171], v[200:203], v[72:75]
	s_barrier
	s_add_i32 s73, s63, s1
	v_lshl_add_u64 v[220:221], s[52:53], 0, v[130:131]
	s_mov_b32 m0, s73
	ds_read_b128 v[204:207], v161
	ds_read_b128 v[208:211], v161 offset:1024
	ds_read_b128 v[212:215], v161 offset:2048
	ds_read_b128 v[216:219], v161 offset:3072
	global_load_lds_dwordx4 v[220:221], off
	s_add_i32 m0, s73, 0x2000
	v_lshl_add_u64 v[222:223], s[52:53], 0, v[134:135]
	global_load_lds_dwordx4 v[222:223], off
	s_barrier
	s_waitcnt lgkmcnt(0)
	v_mfma_f32_16x16x32_bf16 v[116:119], v[204:207], v[172:175], v[116:119]
	v_mfma_f32_16x16x32_bf16 v[112:115], v[212:215], v[172:175], v[112:115]
	v_mfma_f32_16x16x32_bf16 v[100:103], v[204:207], v[180:183], v[100:103]
	v_mfma_f32_16x16x32_bf16 v[96:99], v[212:215], v[180:183], v[96:99]
	v_mfma_f32_16x16x32_bf16 v[84:87], v[204:207], v[188:191], v[84:87]
	v_mfma_f32_16x16x32_bf16 v[80:83], v[212:215], v[188:191], v[80:83]
	v_mfma_f32_16x16x32_bf16 v[68:71], v[204:207], v[196:199], v[68:71]
	v_mfma_f32_16x16x32_bf16 v[64:67], v[212:215], v[196:199], v[64:67]
	v_mfma_f32_16x16x32_bf16 v[116:119], v[208:211], v[176:179], v[116:119]
	v_mfma_f32_16x16x32_bf16 v[112:115], v[216:219], v[176:179], v[112:115]
	v_mfma_f32_16x16x32_bf16 v[100:103], v[208:211], v[184:187], v[100:103]
	v_mfma_f32_16x16x32_bf16 v[96:99], v[216:219], v[184:187], v[96:99]
	v_mfma_f32_16x16x32_bf16 v[84:87], v[208:211], v[192:195], v[84:87]
	v_mfma_f32_16x16x32_bf16 v[80:83], v[216:219], v[192:195], v[80:83]
	v_mfma_f32_16x16x32_bf16 v[68:71], v[208:211], v[200:203], v[68:71]
	v_mfma_f32_16x16x32_bf16 v[64:67], v[216:219], v[200:203], v[64:67]
	s_mov_b32 m0, s33
	v_lshl_add_u64 v[224:225], s[54:55], 0, v[128:129]
	s_barrier
	ds_read_b128 v[172:175], v160 offset:16384
	ds_read_b128 v[176:179], v160 offset:17408
	ds_read_b128 v[180:183], v160 offset:18432
	ds_read_b128 v[184:187], v160 offset:19456
	ds_read_b128 v[188:191], v160 offset:20480
	ds_read_b128 v[192:195], v160 offset:21504
	ds_read_b128 v[196:199], v160 offset:22528
	ds_read_b128 v[200:203], v160 offset:23552
	global_load_lds_dwordx4 v[224:225], off
	s_mov_b32 m0, s34
	v_lshl_add_u64 v[226:227], s[54:55], 0, v[132:133]
	global_load_lds_dwordx4 v[226:227], off
	s_barrier
	s_waitcnt lgkmcnt(0)
	v_mfma_f32_16x16x32_bf16 v[60:63], v[146:149], v[172:175], v[60:63]
	v_mfma_f32_16x16x32_bf16 v[56:59], v[164:167], v[172:175], v[56:59]
	v_mfma_f32_16x16x32_bf16 v[44:47], v[146:149], v[180:183], v[44:47]
	v_mfma_f32_16x16x32_bf16 v[40:43], v[164:167], v[180:183], v[40:43]
	v_mfma_f32_16x16x32_bf16 v[28:31], v[146:149], v[188:191], v[28:31]
	v_mfma_f32_16x16x32_bf16 v[24:27], v[164:167], v[188:191], v[24:27]
	v_mfma_f32_16x16x32_bf16 v[12:15], v[146:149], v[196:199], v[12:15]
	v_mfma_f32_16x16x32_bf16 v[8:11], v[164:167], v[196:199], v[8:11]
	v_mfma_f32_16x16x32_bf16 v[60:63], v[150:153], v[176:179], v[60:63]
	v_mfma_f32_16x16x32_bf16 v[56:59], v[168:171], v[176:179], v[56:59]
	v_mfma_f32_16x16x32_bf16 v[44:47], v[150:153], v[184:187], v[44:47]
	v_mfma_f32_16x16x32_bf16 v[40:43], v[168:171], v[184:187], v[40:43]
	v_mfma_f32_16x16x32_bf16 v[28:31], v[150:153], v[192:195], v[28:31]
	v_mfma_f32_16x16x32_bf16 v[24:27], v[168:171], v[192:195], v[24:27]
	v_mfma_f32_16x16x32_bf16 v[12:15], v[150:153], v[200:203], v[12:15]
	v_mfma_f32_16x16x32_bf16 v[8:11], v[168:171], v[200:203], v[8:11]
	s_barrier
	s_add_u32 s74, s52, 0x40000
	s_addc_u32 s75, s53, 0
	s_add_i32 s73, s72, s1
	s_mov_b32 m0, s73
	v_lshl_add_u64 v[146:147], s[74:75], 0, v[130:131]
	global_load_lds_dwordx4 v[146:147], off
	s_add_i32 m0, s73, 0x2000
	v_lshl_add_u64 v[146:147], s[74:75], 0, v[134:135]
	global_load_lds_dwordx4 v[146:147], off
	s_waitcnt vmcnt(6)
	s_barrier
	v_mfma_f32_16x16x32_bf16 v[52:55], v[204:207], v[172:175], v[52:55]
	v_mfma_f32_16x16x32_bf16 v[48:51], v[212:215], v[172:175], v[48:51]
	v_mfma_f32_16x16x32_bf16 v[36:39], v[204:207], v[180:183], v[36:39]
	v_mfma_f32_16x16x32_bf16 v[32:35], v[212:215], v[180:183], v[32:35]
	v_mfma_f32_16x16x32_bf16 v[20:23], v[204:207], v[188:191], v[20:23]
	v_mfma_f32_16x16x32_bf16 v[16:19], v[212:215], v[188:191], v[16:19]
	v_mfma_f32_16x16x32_bf16 v[4:7], v[204:207], v[196:199], v[4:7]
	v_mfma_f32_16x16x32_bf16 v[0:3], v[212:215], v[196:199], v[0:3]
	v_mfma_f32_16x16x32_bf16 v[52:55], v[208:211], v[176:179], v[52:55]
	v_mfma_f32_16x16x32_bf16 v[48:51], v[216:219], v[176:179], v[48:51]
	v_mfma_f32_16x16x32_bf16 v[36:39], v[208:211], v[184:187], v[36:39]
	v_mfma_f32_16x16x32_bf16 v[32:35], v[216:219], v[184:187], v[32:35]
	v_mfma_f32_16x16x32_bf16 v[20:23], v[208:211], v[192:195], v[20:23]
	v_mfma_f32_16x16x32_bf16 v[16:19], v[216:219], v[192:195], v[16:19]
	v_mfma_f32_16x16x32_bf16 v[4:7], v[208:211], v[200:203], v[4:7]
	v_mfma_f32_16x16x32_bf16 v[0:3], v[216:219], v[200:203], v[0:3]
	s_add_i32 s73, 0, 0x18000
	v_add_u32_e32 v136, s73, v157
	s_barrier
	ds_read_b128 v[146:149], v136
	ds_read_b128 v[150:153], v136 offset:1024
	ds_read_b128 v[164:167], v136 offset:2048
	ds_read_b128 v[168:171], v136 offset:3072
	s_add_u32 s54, s54, 0x40000
	s_addc_u32 s55, s55, 0
	s_mov_b32 m0, s35
	v_lshl_add_u64 v[204:205], s[54:55], 0, v[128:129]
	ds_read_b128 v[172:175], v160 offset:32768
	ds_read_b128 v[176:179], v160 offset:33792
	ds_read_b128 v[180:183], v160 offset:34816
	ds_read_b128 v[184:187], v160 offset:35840
	ds_read_b128 v[188:191], v160 offset:36864
	ds_read_b128 v[192:195], v160 offset:37888
	ds_read_b128 v[196:199], v160 offset:38912
	ds_read_b128 v[200:203], v160 offset:39936
	global_load_lds_dwordx4 v[204:205], off
	s_mov_b32 m0, s56
	v_lshl_add_u64 v[204:205], s[54:55], 0, v[132:133]
	global_load_lds_dwordx4 v[204:205], off
	s_barrier
	s_waitcnt lgkmcnt(0)
	v_mfma_f32_16x16x32_bf16 v[124:127], v[146:149], v[172:175], v[124:127]
	v_mfma_f32_16x16x32_bf16 v[120:123], v[164:167], v[172:175], v[120:123]
	v_mfma_f32_16x16x32_bf16 v[108:111], v[146:149], v[180:183], v[108:111]
	v_mfma_f32_16x16x32_bf16 v[104:107], v[164:167], v[180:183], v[104:107]
	v_mfma_f32_16x16x32_bf16 v[92:95], v[146:149], v[188:191], v[92:95]
	v_mfma_f32_16x16x32_bf16 v[88:91], v[164:167], v[188:191], v[88:91]
	v_mfma_f32_16x16x32_bf16 v[76:79], v[146:149], v[196:199], v[76:79]
	v_mfma_f32_16x16x32_bf16 v[72:75], v[164:167], v[196:199], v[72:75]
	v_mfma_f32_16x16x32_bf16 v[124:127], v[150:153], v[176:179], v[124:127]
	v_mfma_f32_16x16x32_bf16 v[120:123], v[168:171], v[176:179], v[120:123]
	v_mfma_f32_16x16x32_bf16 v[108:111], v[150:153], v[184:187], v[108:111]
	v_mfma_f32_16x16x32_bf16 v[104:107], v[168:171], v[184:187], v[104:107]
	v_mfma_f32_16x16x32_bf16 v[92:95], v[150:153], v[192:195], v[92:95]
	v_mfma_f32_16x16x32_bf16 v[88:91], v[168:171], v[192:195], v[88:91]
	v_mfma_f32_16x16x32_bf16 v[76:79], v[150:153], v[200:203], v[76:79]
	v_mfma_f32_16x16x32_bf16 v[72:75], v[168:171], v[200:203], v[72:75]
	s_barrier
	s_add_i32 s54, s73, s1
	v_add_u32_e32 v136, s97, v157
	v_lshl_add_u64 v[220:221], v[220:221], 0, s[20:21]
	s_mov_b32 m0, s54
	ds_read_b128 v[204:207], v136
	ds_read_b128 v[208:211], v136 offset:1024
	ds_read_b128 v[212:215], v136 offset:2048
	ds_read_b128 v[216:219], v136 offset:3072
	global_load_lds_dwordx4 v[220:221], off
	s_add_i32 m0, s54, 0x2000
	v_lshl_add_u64 v[220:221], v[222:223], 0, s[20:21]
	global_load_lds_dwordx4 v[220:221], off
	s_barrier
	s_waitcnt lgkmcnt(0)
	v_mfma_f32_16x16x32_bf16 v[116:119], v[204:207], v[172:175], v[116:119]
	v_mfma_f32_16x16x32_bf16 v[112:115], v[212:215], v[172:175], v[112:115]
	v_mfma_f32_16x16x32_bf16 v[100:103], v[204:207], v[180:183], v[100:103]
	v_mfma_f32_16x16x32_bf16 v[96:99], v[212:215], v[180:183], v[96:99]
	v_mfma_f32_16x16x32_bf16 v[84:87], v[204:207], v[188:191], v[84:87]
	v_mfma_f32_16x16x32_bf16 v[80:83], v[212:215], v[188:191], v[80:83]
	v_mfma_f32_16x16x32_bf16 v[68:71], v[204:207], v[196:199], v[68:71]
	v_mfma_f32_16x16x32_bf16 v[64:67], v[212:215], v[196:199], v[64:67]
	v_mfma_f32_16x16x32_bf16 v[116:119], v[208:211], v[176:179], v[116:119]
	v_mfma_f32_16x16x32_bf16 v[112:115], v[216:219], v[176:179], v[112:115]
	v_mfma_f32_16x16x32_bf16 v[100:103], v[208:211], v[184:187], v[100:103]
	v_mfma_f32_16x16x32_bf16 v[96:99], v[216:219], v[184:187], v[96:99]
	v_mfma_f32_16x16x32_bf16 v[84:87], v[208:211], v[192:195], v[84:87]
	v_mfma_f32_16x16x32_bf16 v[80:83], v[216:219], v[192:195], v[80:83]
	v_mfma_f32_16x16x32_bf16 v[68:71], v[208:211], v[200:203], v[68:71]
	v_mfma_f32_16x16x32_bf16 v[64:67], v[216:219], v[200:203], v[64:67]
	s_mov_b32 m0, s58
	v_lshl_add_u64 v[220:221], v[224:225], 0, s[20:21]
	s_barrier
	ds_read_b128 v[172:175], v160 offset:49152
	ds_read_b128 v[176:179], v160 offset:50176
	ds_read_b128 v[180:183], v160 offset:51200
	ds_read_b128 v[184:187], v160 offset:52224
	ds_read_b128 v[188:191], v160 offset:53248
	ds_read_b128 v[192:195], v160 offset:54272
	ds_read_b128 v[196:199], v160 offset:55296
	ds_read_b128 v[200:203], v160 offset:56320
	global_load_lds_dwordx4 v[220:221], off
	s_mov_b32 m0, s59
	v_lshl_add_u64 v[220:221], v[226:227], 0, s[20:21]
	global_load_lds_dwordx4 v[220:221], off
	s_barrier
	s_waitcnt lgkmcnt(0)
	v_mfma_f32_16x16x32_bf16 v[60:63], v[146:149], v[172:175], v[60:63]
	v_mfma_f32_16x16x32_bf16 v[56:59], v[164:167], v[172:175], v[56:59]
	v_mfma_f32_16x16x32_bf16 v[44:47], v[146:149], v[180:183], v[44:47]
	v_mfma_f32_16x16x32_bf16 v[40:43], v[164:167], v[180:183], v[40:43]
	v_mfma_f32_16x16x32_bf16 v[28:31], v[146:149], v[188:191], v[28:31]
	v_mfma_f32_16x16x32_bf16 v[24:27], v[164:167], v[188:191], v[24:27]
	v_mfma_f32_16x16x32_bf16 v[12:15], v[146:149], v[196:199], v[12:15]
	v_mfma_f32_16x16x32_bf16 v[8:11], v[164:167], v[196:199], v[8:11]
	v_mfma_f32_16x16x32_bf16 v[60:63], v[150:153], v[176:179], v[60:63]
	v_mfma_f32_16x16x32_bf16 v[56:59], v[168:171], v[176:179], v[56:59]
	v_mfma_f32_16x16x32_bf16 v[44:47], v[150:153], v[184:187], v[44:47]
	v_mfma_f32_16x16x32_bf16 v[40:43], v[168:171], v[184:187], v[40:43]
	v_mfma_f32_16x16x32_bf16 v[28:31], v[150:153], v[192:195], v[28:31]
	v_mfma_f32_16x16x32_bf16 v[24:27], v[168:171], v[192:195], v[24:27]
	v_mfma_f32_16x16x32_bf16 v[12:15], v[150:153], v[200:203], v[12:15]
	v_mfma_f32_16x16x32_bf16 v[8:11], v[168:171], v[200:203], v[8:11]
	s_barrier
	s_add_u32 s52, s52, 0x40080
	s_addc_u32 s53, s53, 0
	s_add_i32 s54, s97, s1
	s_mov_b32 m0, s54
	v_lshl_add_u64 v[146:147], s[52:53], 0, v[130:131]
	global_load_lds_dwordx4 v[146:147], off
	s_add_i32 m0, s54, 0x2000
	v_lshl_add_u64 v[146:147], s[52:53], 0, v[134:135]
	global_load_lds_dwordx4 v[146:147], off
	s_waitcnt vmcnt(6)
	s_barrier
	v_mfma_f32_16x16x32_bf16 v[52:55], v[204:207], v[172:175], v[52:55]
	v_mfma_f32_16x16x32_bf16 v[48:51], v[212:215], v[172:175], v[48:51]
	v_mfma_f32_16x16x32_bf16 v[36:39], v[204:207], v[180:183], v[36:39]
	v_mfma_f32_16x16x32_bf16 v[32:35], v[212:215], v[180:183], v[32:35]
	v_mfma_f32_16x16x32_bf16 v[20:23], v[204:207], v[188:191], v[20:23]
	v_mfma_f32_16x16x32_bf16 v[16:19], v[212:215], v[188:191], v[16:19]
	v_mfma_f32_16x16x32_bf16 v[4:7], v[204:207], v[196:199], v[4:7]
	v_mfma_f32_16x16x32_bf16 v[0:3], v[212:215], v[196:199], v[0:3]
	v_mfma_f32_16x16x32_bf16 v[52:55], v[208:211], v[176:179], v[52:55]
	v_mfma_f32_16x16x32_bf16 v[48:51], v[216:219], v[176:179], v[48:51]
	v_mfma_f32_16x16x32_bf16 v[36:39], v[208:211], v[184:187], v[36:39]
	v_mfma_f32_16x16x32_bf16 v[32:35], v[216:219], v[184:187], v[32:35]
	v_mfma_f32_16x16x32_bf16 v[20:23], v[208:211], v[192:195], v[20:23]
	v_mfma_f32_16x16x32_bf16 v[16:19], v[216:219], v[192:195], v[16:19]
	v_mfma_f32_16x16x32_bf16 v[4:7], v[208:211], v[200:203], v[4:7]
	v_mfma_f32_16x16x32_bf16 v[0:3], v[216:219], v[200:203], v[0:3]
	s_add_i32 s71, s71, 2
	s_add_u32 s50, s50, 0x100
	s_addc_u32 s51, s51, 0
	s_add_u32 s69, s69, 0x100
	s_addc_u32 s70, s70, 0
	s_cmp_gt_u32 s71, 13
	s_barrier
	s_cbranch_scc0 .LBB0_628
	v_lshl_add_u32 v150, s48, 8, v156
	v_cmp_lt_i32_e32 vcc, s64, v150
	s_and_saveexec_b64 s[48:49], vcc
	s_xor_b64 s[48:49], exec, s[48:49]
	v_add_u32_e32 v136, 0xffff0000, v150
	v_lshlrev_b64 v[146:147], 12, v[136:137]
	v_lshl_add_u64 v[152:153], s[38:39], 0, v[146:147]
	v_mov_b32_e32 v151, v137
	s_andn2_saveexec_b64 s[48:49], s[48:49]
	v_ashrrev_i32_e32 v151, 31, v150
	v_lshlrev_b64 v[146:147], 12, v[150:151]
	v_lshl_add_u64 v[152:153], s[36:37], 0, v[146:147]
	s_or_b64 exec, exec, s[48:49]
	v_lshl_or_b32 v146, s46, 8, v158
	v_ashrrev_i32_e32 v147, 31, v146
	v_lshlrev_b64 v[148:149], 2, v[146:147]
	v_lshl_add_u64 v[152:153], v[152:153], 0, v[148:149]
	global_load_dwordx4 v[164:167], v[152:153], off
	global_load_dwordx4 v[168:171], v[152:153], off offset:16
	v_lshlrev_b64 v[172:173], 12, v[150:151]
	v_lshlrev_b64 v[174:175], 11, v[150:151]
	v_lshl_add_u64 v[172:173], s[42:43], 0, v[172:173]
	v_lshl_add_u64 v[174:175], s[84:85], 0, v[174:175]
	v_lshl_add_u64 v[176:177], v[146:147], 1, v[174:175]
	v_lshl_add_u64 v[178:179], v[172:173], 0, v[148:149]
	s_waitcnt vmcnt(0)
	v_pk_add_f32 v[126:127], v[126:127], v[166:167]
	v_pk_add_f32 v[124:125], v[124:125], v[164:165]
	v_pk_add_f32 v[166:167], v[122:123], v[170:171]
	v_pk_add_f32 v[164:165], v[120:121], v[168:169]
	v_cvt_pk_bf16_f32 v120, v124, v125
	v_cvt_pk_bf16_f32 v121, v126, v127
	v_cvt_pk_bf16_f32 v122, v164, v165
	v_cvt_pk_bf16_f32 v123, v166, v167
	global_store_dwordx4 v[178:179], v[124:127], off
	global_store_dwordx4 v[178:179], v[164:167], off offset:16
	global_store_dwordx4 v[176:177], v[120:123], off
	global_load_dwordx4 v[168:171], v[152:153], off offset:512
	global_load_dwordx4 v[172:175], v[152:153], off offset:528
	v_and_b32_e32 v121, 64, v162
	v_xor_b32_e32 v120, 16, v162
	v_add_u32_e32 v121, 64, v121
	v_xor_b32_e32 v122, 32, v162
	v_cmp_lt_i32_e32 vcc, v120, v121
	v_mul_f32_e32 v123, v165, v165
	v_mul_f32_e32 v136, v166, v166
	v_cndmask_b32_e32 v120, v162, v120, vcc
	v_cmp_lt_i32_e32 vcc, v122, v121
	v_fmac_f32_e32 v123, v125, v125
	v_mul_f32_e32 v152, v167, v167
	v_cndmask_b32_e32 v121, v162, v122, vcc
	v_mul_f32_e32 v122, v164, v164
	v_fmac_f32_e32 v122, v124, v124
	v_fmac_f32_e32 v136, v126, v126
	v_add_f32_e32 v122, v122, v123
	v_fmac_f32_e32 v152, v127, v127
	v_add_f32_e32 v122, v136, v122
	v_add_f32_e32 v126, v152, v122
	v_lshlrev_b32_e32 v120, 2, v120
	s_waitcnt vmcnt(0)
	v_pk_add_f32 v[122:123], v[116:117], v[168:169]
	v_pk_add_f32 v[164:165], v[112:113], v[172:173]
	v_pk_add_f32 v[166:167], v[114:115], v[174:175]
	v_mul_f32_e32 v112, v164, v164
	v_mul_f32_e32 v113, v165, v165
	v_fmac_f32_e32 v112, v122, v122
	v_pk_add_f32 v[124:125], v[118:119], v[170:171]
	v_mul_f32_e32 v114, v166, v166
	v_fmac_f32_e32 v113, v123, v123
	v_add_f32_e32 v112, v126, v112
	v_mul_f32_e32 v115, v167, v167
	v_fmac_f32_e32 v114, v124, v124
	v_add_f32_e32 v112, v113, v112
	v_add_f32_e32 v112, v114, v112
	v_fmac_f32_e32 v115, v125, v125
	v_add_f32_e32 v112, v115, v112
	ds_bpermute_b32 v113, v120, v112
	v_lshlrev_b32_e32 v116, 2, v121
	global_store_dwordx4 v[178:179], v[122:125], off offset:512
	global_store_dwordx4 v[178:179], v[164:167], off offset:528
	s_waitcnt lgkmcnt(0)
	v_add_f32_e32 v112, v112, v113
	ds_bpermute_b32 v113, v116, v112
	v_cvt_pk_bf16_f32 v122, v122, v123
	v_cvt_pk_bf16_f32 v123, v124, v125
	v_cvt_pk_bf16_f32 v124, v164, v165
	v_cvt_pk_bf16_f32 v125, v166, v167
	global_store_dwordx4 v[176:177], v[122:125], off offset:256
	s_and_saveexec_b64 s[46:47], s[4:5]
	s_cbranch_execz .LBB0_635
	v_lshl_add_u64 v[114:115], v[150:151], 2, s[18:19]
	s_waitcnt lgkmcnt(0)
	v_add_f32_e32 v112, v112, v113
	global_atomic_add_f32 v[114:115], v112, off

.LBB0_697:
	ds_read_b128 v[144:147], v157
	ds_read_b128 v[148:151], v157 offset:1024
	ds_read_b128 v[162:165], v157 offset:2048
	ds_read_b128 v[166:169], v157 offset:3072
	s_add_u32 s48, s6, 0xfffc0080
	s_addc_u32 s49, s7, -1
	s_cmp_eq_u32 s71, 12
	s_cselect_b32 s51, s39, s49
	s_cselect_b32 s50, s67, s48
	s_cselect_b32 s49, s37, s70
	s_cselect_b32 s48, s68, s69
	v_lshl_add_u64 v[202:203], s[6:7], 0, v[136:137]
	s_add_i32 m0, s47, 0xc000
	ds_read_b128 v[170:173], v158
	ds_read_b128 v[174:177], v158 offset:1024
	ds_read_b128 v[178:181], v158 offset:2048
	ds_read_b128 v[182:185], v158 offset:3072
	ds_read_b128 v[186:189], v158 offset:4096
	ds_read_b128 v[190:193], v158 offset:5120
	ds_read_b128 v[194:197], v158 offset:6144
	ds_read_b128 v[198:201], v158 offset:7168
	global_load_lds_dwordx4 v[202:203], off
	s_add_i32 m0, s47, 0xe000
	v_lshl_add_u64 v[202:203], s[6:7], 0, v[138:139]
	global_load_lds_dwordx4 v[202:203], off
	s_barrier
	s_waitcnt lgkmcnt(0)
	v_mfma_f32_16x16x32_bf16 v[124:127], v[144:147], v[170:173], v[124:127]
	v_mfma_f32_16x16x32_bf16 v[120:123], v[162:165], v[170:173], v[120:123]
	v_mfma_f32_16x16x32_bf16 v[108:111], v[144:147], v[178:181], v[108:111]
	v_mfma_f32_16x16x32_bf16 v[104:107], v[162:165], v[178:181], v[104:107]
	v_mfma_f32_16x16x32_bf16 v[92:95], v[144:147], v[186:189], v[92:95]
	v_mfma_f32_16x16x32_bf16 v[88:91], v[162:165], v[186:189], v[88:91]
	v_mfma_f32_16x16x32_bf16 v[76:79], v[144:147], v[194:197], v[76:79]
	v_mfma_f32_16x16x32_bf16 v[72:75], v[162:165], v[194:197], v[72:75]
	v_mfma_f32_16x16x32_bf16 v[124:127], v[148:151], v[174:177], v[124:127]
	v_mfma_f32_16x16x32_bf16 v[120:123], v[166:169], v[174:177], v[120:123]
	v_mfma_f32_16x16x32_bf16 v[108:111], v[148:151], v[182:185], v[108:111]
	v_mfma_f32_16x16x32_bf16 v[104:107], v[166:169], v[182:185], v[104:107]
	v_mfma_f32_16x16x32_bf16 v[92:95], v[148:151], v[190:193], v[92:95]
	v_mfma_f32_16x16x32_bf16 v[88:91], v[166:169], v[190:193], v[88:91]
	v_mfma_f32_16x16x32_bf16 v[76:79], v[148:151], v[198:201], v[76:79]
	v_mfma_f32_16x16x32_bf16 v[72:75], v[166:169], v[198:201], v[72:75]
	s_barrier
	s_add_i32 s73, s60, s34
	v_lshl_add_u64 v[218:219], s[48:49], 0, v[132:133]
	s_mov_b32 m0, s73
	ds_read_b128 v[202:205], v159
	ds_read_b128 v[206:209], v159 offset:1024
	ds_read_b128 v[210:213], v159 offset:2048
	ds_read_b128 v[214:217], v159 offset:3072
	global_load_lds_dwordx4 v[218:219], off
	s_add_i32 m0, s73, 0x2000
	v_lshl_add_u64 v[220:221], s[48:49], 0, v[128:129]
	global_load_lds_dwordx4 v[220:221], off
	s_barrier
	s_waitcnt lgkmcnt(0)
	v_mfma_f32_16x16x32_bf16 v[116:119], v[202:205], v[170:173], v[116:119]
	v_mfma_f32_16x16x32_bf16 v[112:115], v[210:213], v[170:173], v[112:115]
	v_mfma_f32_16x16x32_bf16 v[100:103], v[202:205], v[178:181], v[100:103]
	v_mfma_f32_16x16x32_bf16 v[96:99], v[210:213], v[178:181], v[96:99]
	v_mfma_f32_16x16x32_bf16 v[84:87], v[202:205], v[186:189], v[84:87]
	v_mfma_f32_16x16x32_bf16 v[80:83], v[210:213], v[186:189], v[80:83]
	v_mfma_f32_16x16x32_bf16 v[68:71], v[202:205], v[194:197], v[68:71]
	v_mfma_f32_16x16x32_bf16 v[64:67], v[210:213], v[194:197], v[64:67]
	v_mfma_f32_16x16x32_bf16 v[116:119], v[206:209], v[174:177], v[116:119]
	v_mfma_f32_16x16x32_bf16 v[112:115], v[214:217], v[174:177], v[112:115]
	v_mfma_f32_16x16x32_bf16 v[100:103], v[206:209], v[182:185], v[100:103]
	v_mfma_f32_16x16x32_bf16 v[96:99], v[214:217], v[182:185], v[96:99]
	v_mfma_f32_16x16x32_bf16 v[84:87], v[206:209], v[190:193], v[84:87]
	v_mfma_f32_16x16x32_bf16 v[80:83], v[214:217], v[190:193], v[80:83]
	v_mfma_f32_16x16x32_bf16 v[68:71], v[206:209], v[198:201], v[68:71]
	v_mfma_f32_16x16x32_bf16 v[64:67], v[214:217], v[198:201], v[64:67]
	s_mov_b32 m0, s47
	v_lshl_add_u64 v[222:223], s[50:51], 0, v[134:135]
	s_barrier
	ds_read_b128 v[170:173], v158 offset:16384
	ds_read_b128 v[174:177], v158 offset:17408
	ds_read_b128 v[178:181], v158 offset:18432
	ds_read_b128 v[182:185], v158 offset:19456
	ds_read_b128 v[186:189], v158 offset:20480
	ds_read_b128 v[190:193], v158 offset:21504
	ds_read_b128 v[194:197], v158 offset:22528
	ds_read_b128 v[198:201], v158 offset:23552
	global_load_lds_dwordx4 v[222:223], off
	s_mov_b32 m0, s53
	v_lshl_add_u64 v[224:225], s[50:51], 0, v[130:131]
	global_load_lds_dwordx4 v[224:225], off
	s_barrier
	s_waitcnt lgkmcnt(0)
	v_mfma_f32_16x16x32_bf16 v[60:63], v[144:147], v[170:173], v[60:63]
	v_mfma_f32_16x16x32_bf16 v[56:59], v[162:165], v[170:173], v[56:59]
	v_mfma_f32_16x16x32_bf16 v[44:47], v[144:147], v[178:181], v[44:47]
	v_mfma_f32_16x16x32_bf16 v[40:43], v[162:165], v[178:181], v[40:43]
	v_mfma_f32_16x16x32_bf16 v[28:31], v[144:147], v[186:189], v[28:31]
	v_mfma_f32_16x16x32_bf16 v[24:27], v[162:165], v[186:189], v[24:27]
	v_mfma_f32_16x16x32_bf16 v[12:15], v[144:147], v[194:197], v[12:15]
	v_mfma_f32_16x16x32_bf16 v[8:11], v[162:165], v[194:197], v[8:11]
	v_mfma_f32_16x16x32_bf16 v[60:63], v[148:151], v[174:177], v[60:63]
	v_mfma_f32_16x16x32_bf16 v[56:59], v[166:169], v[174:177], v[56:59]
	v_mfma_f32_16x16x32_bf16 v[44:47], v[148:151], v[182:185], v[44:47]
	v_mfma_f32_16x16x32_bf16 v[40:43], v[166:169], v[182:185], v[40:43]
	v_mfma_f32_16x16x32_bf16 v[28:31], v[148:151], v[190:193], v[28:31]
	v_mfma_f32_16x16x32_bf16 v[24:27], v[166:169], v[190:193], v[24:27]
	v_mfma_f32_16x16x32_bf16 v[12:15], v[148:151], v[198:201], v[12:15]
	v_mfma_f32_16x16x32_bf16 v[8:11], v[166:169], v[198:201], v[8:11]
	s_barrier
	s_add_u32 s74, s48, 0x40000
	s_addc_u32 s75, s49, 0
	s_add_i32 s73, s72, s34
	s_mov_b32 m0, s73
	v_lshl_add_u64 v[144:145], s[74:75], 0, v[132:133]
	global_load_lds_dwordx4 v[144:145], off
	s_add_i32 m0, s73, 0x2000
	v_lshl_add_u64 v[144:145], s[74:75], 0, v[128:129]
	global_load_lds_dwordx4 v[144:145], off
	s_waitcnt vmcnt(6)
	s_barrier
	v_mfma_f32_16x16x32_bf16 v[52:55], v[202:205], v[170:173], v[52:55]
	v_mfma_f32_16x16x32_bf16 v[48:51], v[210:213], v[170:173], v[48:51]
	v_mfma_f32_16x16x32_bf16 v[36:39], v[202:205], v[178:181], v[36:39]
	v_mfma_f32_16x16x32_bf16 v[32:35], v[210:213], v[178:181], v[32:35]
	v_mfma_f32_16x16x32_bf16 v[20:23], v[202:205], v[186:189], v[20:23]
	v_mfma_f32_16x16x32_bf16 v[16:19], v[210:213], v[186:189], v[16:19]
	v_mfma_f32_16x16x32_bf16 v[4:7], v[202:205], v[194:197], v[4:7]
	v_mfma_f32_16x16x32_bf16 v[0:3], v[210:213], v[194:197], v[0:3]
	v_mfma_f32_16x16x32_bf16 v[52:55], v[206:209], v[174:177], v[52:55]
	v_mfma_f32_16x16x32_bf16 v[48:51], v[214:217], v[174:177], v[48:51]
	v_mfma_f32_16x16x32_bf16 v[36:39], v[206:209], v[182:185], v[36:39]
	v_mfma_f32_16x16x32_bf16 v[32:35], v[214:217], v[182:185], v[32:35]
	v_mfma_f32_16x16x32_bf16 v[20:23], v[206:209], v[190:193], v[20:23]
	v_mfma_f32_16x16x32_bf16 v[16:19], v[214:217], v[190:193], v[16:19]
	v_mfma_f32_16x16x32_bf16 v[4:7], v[206:209], v[198:201], v[4:7]
	v_mfma_f32_16x16x32_bf16 v[0:3], v[214:217], v[198:201], v[0:3]
	s_add_i32 s73, 0, 0x18000
	v_add_u32_e32 v161, s73, v153
	s_barrier
	ds_read_b128 v[144:147], v161
	ds_read_b128 v[148:151], v161 offset:1024
	ds_read_b128 v[162:165], v161 offset:2048
	ds_read_b128 v[166:169], v161 offset:3072
	s_add_u32 s50, s50, 0x40000
	s_addc_u32 s51, s51, 0
	s_mov_b32 m0, s54
	v_lshl_add_u64 v[202:203], s[50:51], 0, v[134:135]
	ds_read_b128 v[170:173], v158 offset:32768
	ds_read_b128 v[174:177], v158 offset:33792
	ds_read_b128 v[178:181], v158 offset:34816
	ds_read_b128 v[182:185], v158 offset:35840
	ds_read_b128 v[186:189], v158 offset:36864
	ds_read_b128 v[190:193], v158 offset:37888
	ds_read_b128 v[194:197], v158 offset:38912
	ds_read_b128 v[198:201], v158 offset:39936
	global_load_lds_dwordx4 v[202:203], off
	s_mov_b32 m0, s55
	v_lshl_add_u64 v[202:203], s[50:51], 0, v[130:131]
	global_load_lds_dwordx4 v[202:203], off
	s_barrier
	s_waitcnt lgkmcnt(0)
	v_mfma_f32_16x16x32_bf16 v[124:127], v[144:147], v[170:173], v[124:127]
	v_mfma_f32_16x16x32_bf16 v[120:123], v[162:165], v[170:173], v[120:123]
	v_mfma_f32_16x16x32_bf16 v[108:111], v[144:147], v[178:181], v[108:111]
	v_mfma_f32_16x16x32_bf16 v[104:107], v[162:165], v[178:181], v[104:107]
	v_mfma_f32_16x16x32_bf16 v[92:95], v[144:147], v[186:189], v[92:95]
	v_mfma_f32_16x16x32_bf16 v[88:91], v[162:165], v[186:189], v[88:91]
	v_mfma_f32_16x16x32_bf16 v[76:79], v[144:147], v[194:197], v[76:79]
	v_mfma_f32_16x16x32_bf16 v[72:75], v[162:165], v[194:197], v[72:75]
	v_mfma_f32_16x16x32_bf16 v[124:127], v[148:151], v[174:177], v[124:127]
	v_mfma_f32_16x16x32_bf16 v[120:123], v[166:169], v[174:177], v[120:123]
	v_mfma_f32_16x16x32_bf16 v[108:111], v[148:151], v[182:185], v[108:111]
	v_mfma_f32_16x16x32_bf16 v[104:107], v[166:169], v[182:185], v[104:107]
	v_mfma_f32_16x16x32_bf16 v[92:95], v[148:151], v[190:193], v[92:95]
	v_mfma_f32_16x16x32_bf16 v[88:91], v[166:169], v[190:193], v[88:91]
	v_mfma_f32_16x16x32_bf16 v[76:79], v[148:151], v[198:201], v[76:79]
	v_mfma_f32_16x16x32_bf16 v[72:75], v[166:169], v[198:201], v[72:75]
	s_barrier
	s_add_i32 s50, s73, s34
	v_add_u32_e32 v161, s97, v153
	v_lshl_add_u64 v[218:219], v[218:219], 0, s[14:15]
	s_mov_b32 m0, s50
	ds_read_b128 v[202:205], v161
	ds_read_b128 v[206:209], v161 offset:1024
	ds_read_b128 v[210:213], v161 offset:2048
	ds_read_b128 v[214:217], v161 offset:3072
	global_load_lds_dwordx4 v[218:219], off
	s_add_i32 m0, s50, 0x2000
	v_lshl_add_u64 v[218:219], v[220:221], 0, s[14:15]
	global_load_lds_dwordx4 v[218:219], off
	s_barrier
	s_waitcnt lgkmcnt(0)
	v_mfma_f32_16x16x32_bf16 v[116:119], v[202:205], v[170:173], v[116:119]
	v_mfma_f32_16x16x32_bf16 v[112:115], v[210:213], v[170:173], v[112:115]
	v_mfma_f32_16x16x32_bf16 v[100:103], v[202:205], v[178:181], v[100:103]
	v_mfma_f32_16x16x32_bf16 v[96:99], v[210:213], v[178:181], v[96:99]
	v_mfma_f32_16x16x32_bf16 v[84:87], v[202:205], v[186:189], v[84:87]
	v_mfma_f32_16x16x32_bf16 v[80:83], v[210:213], v[186:189], v[80:83]
	v_mfma_f32_16x16x32_bf16 v[68:71], v[202:205], v[194:197], v[68:71]
	v_mfma_f32_16x16x32_bf16 v[64:67], v[210:213], v[194:197], v[64:67]
	v_mfma_f32_16x16x32_bf16 v[116:119], v[206:209], v[174:177], v[116:119]
	v_mfma_f32_16x16x32_bf16 v[112:115], v[214:217], v[174:177], v[112:115]
	v_mfma_f32_16x16x32_bf16 v[100:103], v[206:209], v[182:185], v[100:103]
	v_mfma_f32_16x16x32_bf16 v[96:99], v[214:217], v[182:185], v[96:99]
	v_mfma_f32_16x16x32_bf16 v[84:87], v[206:209], v[190:193], v[84:87]
	v_mfma_f32_16x16x32_bf16 v[80:83], v[214:217], v[190:193], v[80:83]
	v_mfma_f32_16x16x32_bf16 v[68:71], v[206:209], v[198:201], v[68:71]
	v_mfma_f32_16x16x32_bf16 v[64:67], v[214:217], v[198:201], v[64:67]
	s_mov_b32 m0, s57
	v_lshl_add_u64 v[218:219], v[222:223], 0, s[14:15]
	s_barrier
	ds_read_b128 v[170:173], v158 offset:49152
	ds_read_b128 v[174:177], v158 offset:50176
	ds_read_b128 v[178:181], v158 offset:51200
	ds_read_b128 v[182:185], v158 offset:52224
	ds_read_b128 v[186:189], v158 offset:53248
	ds_read_b128 v[190:193], v158 offset:54272
	ds_read_b128 v[194:197], v158 offset:55296
	ds_read_b128 v[198:201], v158 offset:56320
	global_load_lds_dwordx4 v[218:219], off
	s_mov_b32 m0, s58
	v_lshl_add_u64 v[218:219], v[224:225], 0, s[14:15]
	global_load_lds_dwordx4 v[218:219], off
	s_barrier
	s_waitcnt lgkmcnt(0)
	v_mfma_f32_16x16x32_bf16 v[60:63], v[144:147], v[170:173], v[60:63]
	v_mfma_f32_16x16x32_bf16 v[56:59], v[162:165], v[170:173], v[56:59]
	v_mfma_f32_16x16x32_bf16 v[44:47], v[144:147], v[178:181], v[44:47]
	v_mfma_f32_16x16x32_bf16 v[40:43], v[162:165], v[178:181], v[40:43]
	v_mfma_f32_16x16x32_bf16 v[28:31], v[144:147], v[186:189], v[28:31]
	v_mfma_f32_16x16x32_bf16 v[24:27], v[162:165], v[186:189], v[24:27]
	v_mfma_f32_16x16x32_bf16 v[12:15], v[144:147], v[194:197], v[12:15]
	v_mfma_f32_16x16x32_bf16 v[8:11], v[162:165], v[194:197], v[8:11]
	v_mfma_f32_16x16x32_bf16 v[60:63], v[148:151], v[174:177], v[60:63]
	v_mfma_f32_16x16x32_bf16 v[56:59], v[166:169], v[174:177], v[56:59]
	v_mfma_f32_16x16x32_bf16 v[44:47], v[148:151], v[182:185], v[44:47]
	v_mfma_f32_16x16x32_bf16 v[40:43], v[166:169], v[182:185], v[40:43]
	v_mfma_f32_16x16x32_bf16 v[28:31], v[148:151], v[190:193], v[28:31]
	v_mfma_f32_16x16x32_bf16 v[24:27], v[166:169], v[190:193], v[24:27]
	v_mfma_f32_16x16x32_bf16 v[12:15], v[148:151], v[198:201], v[12:15]
	v_mfma_f32_16x16x32_bf16 v[8:11], v[166:169], v[198:201], v[8:11]
	s_barrier
	s_add_u32 s48, s48, 0x40080
	s_addc_u32 s49, s49, 0
	s_add_i32 s50, s97, s34
	s_mov_b32 m0, s50
	v_lshl_add_u64 v[144:145], s[48:49], 0, v[132:133]
	global_load_lds_dwordx4 v[144:145], off
	s_add_i32 m0, s50, 0x2000
	v_lshl_add_u64 v[144:145], s[48:49], 0, v[128:129]
	global_load_lds_dwordx4 v[144:145], off
	s_waitcnt vmcnt(6)
	s_barrier
	v_mfma_f32_16x16x32_bf16 v[52:55], v[202:205], v[170:173], v[52:55]
	v_mfma_f32_16x16x32_bf16 v[48:51], v[210:213], v[170:173], v[48:51]
	v_mfma_f32_16x16x32_bf16 v[36:39], v[202:205], v[178:181], v[36:39]
	v_mfma_f32_16x16x32_bf16 v[32:35], v[210:213], v[178:181], v[32:35]
	v_mfma_f32_16x16x32_bf16 v[20:23], v[202:205], v[186:189], v[20:23]
	v_mfma_f32_16x16x32_bf16 v[16:19], v[210:213], v[186:189], v[16:19]
	v_mfma_f32_16x16x32_bf16 v[4:7], v[202:205], v[194:197], v[4:7]
	v_mfma_f32_16x16x32_bf16 v[0:3], v[210:213], v[194:197], v[0:3]
	v_mfma_f32_16x16x32_bf16 v[52:55], v[206:209], v[174:177], v[52:55]
	v_mfma_f32_16x16x32_bf16 v[48:51], v[214:217], v[174:177], v[48:51]
	v_mfma_f32_16x16x32_bf16 v[36:39], v[206:209], v[182:185], v[36:39]
	v_mfma_f32_16x16x32_bf16 v[32:35], v[214:217], v[182:185], v[32:35]
	v_mfma_f32_16x16x32_bf16 v[20:23], v[206:209], v[190:193], v[20:23]
	v_mfma_f32_16x16x32_bf16 v[16:19], v[214:217], v[190:193], v[16:19]
	v_mfma_f32_16x16x32_bf16 v[4:7], v[206:209], v[198:201], v[4:7]
	v_mfma_f32_16x16x32_bf16 v[0:3], v[214:217], v[198:201], v[0:3]
	s_add_i32 s71, s71, 2
	s_add_u32 s6, s6, 0x100
	s_addc_u32 s7, s7, 0
	s_add_u32 s69, s69, 0x100
	s_addc_u32 s70, s70, 0
	s_cmp_gt_u32 s71, 13
	s_barrier
	s_cbranch_scc0 .LBB0_697
	v_lshl_add_u32 v148, s46, 8, v152
	v_ashrrev_i32_e32 v149, 31, v148
	v_lshl_add_u64 v[144:145], v[148:149], 2, s[18:19]
	global_load_dword v151, v[144:145], off
	v_lshlrev_b64 v[146:147], 12, v[148:149]
	s_cmp_lt_i32 s66, 8
	s_cselect_b32 s7, s1, s29
	s_cselect_b32 s6, s0, s28
	s_cselect_b32 s37, 0, 0xfffff800
	s_lshl_b32 s39, s66, 8
	s_add_i32 s37, s37, s39
	v_or_b32_e32 v150, s37, v156
	v_or_b32_e32 v162, 16, v148
	v_lshl_add_u64 v[146:147], s[6:7], 0, v[146:147]
	v_ashrrev_i32_e32 v163, 31, v162
	v_lshl_add_u64 v[164:165], v[162:163], 2, s[18:19]
	s_mov_b32 s46, s38
	s_mov_b64 s[48:49], s[44:45]
	s_mov_b64 s[50:51], s[40:41]
	s_mov_b32 s66, s36
	s_waitcnt vmcnt(0)
	v_fmamk_f32 v149, v151, 0x3a800000, v160
	v_mul_f32_e32 v151, 0x4b800000, v149
	v_cmp_gt_f32_e32 vcc, s61, v149
	s_nop 1
	v_cndmask_b32_e32 v149, v149, v151, vcc
	v_rsq_f32_e32 v149, v149
	v_ashrrev_i32_e32 v151, 31, v150
	v_lshlrev_b64 v[150:151], 1, v[150:151]
	v_lshl_add_u64 v[146:147], v[146:147], 0, v[150:151]
	v_mul_f32_e32 v161, 0x45800000, v149
	v_cndmask_b32_e32 v149, v149, v161, vcc
	v_mul_f32_e32 v124, v124, v149
	v_mul_f32_e32 v120, v120, v149
	v_mul_f32_e32 v125, v125, v149
	v_mul_f32_e32 v121, v121, v149
	v_mul_f32_e32 v126, v126, v149
	v_mul_f32_e32 v122, v122, v149
	v_mul_f32_e32 v127, v127, v149
	v_mul_f32_e32 v123, v123, v149
	v_mul_f32_e32 v161, v116, v149
	v_mul_f32_e32 v166, v112, v149
	v_mul_f32_e32 v167, v117, v149
	v_mul_f32_e32 v168, v113, v149
	v_mul_f32_e32 v169, v118, v149
	v_mul_f32_e32 v170, v114, v149
	v_mul_f32_e32 v171, v119, v149
	v_mul_f32_e32 v149, v115, v149
	v_max_f32_e32 v112, 0, v124
	v_max_f32_e32 v114, 0, v120
	v_max_f32_e32 v113, 0, v125
	v_max_f32_e32 v115, 0, v121
	v_max_f32_e32 v116, 0, v126
	v_max_f32_e32 v118, 0, v122
	v_max_f32_e32 v117, 0, v127
	v_max_f32_e32 v119, 0, v123
	v_max_f32_e32 v120, 0, v161
	v_max_f32_e32 v122, 0, v166
	v_max_f32_e32 v121, 0, v167
	v_max_f32_e32 v123, 0, v168
	v_max_f32_e32 v124, 0, v169
	v_max_f32_e32 v126, 0, v170
	v_max_f32_e32 v125, 0, v171
	v_max_f32_e32 v127, 0, v149
	v_pk_mul_f32 v[112:113], v[112:113], v[112:113]
	v_pk_mul_f32 v[114:115], v[114:115], v[114:115]
	v_pk_mul_f32 v[116:117], v[116:117], v[116:117]
	v_pk_mul_f32 v[118:119], v[118:119], v[118:119]
	v_pk_mul_f32 v[120:121], v[120:121], v[120:121]
	v_pk_mul_f32 v[122:123], v[122:123], v[122:123]
	v_pk_mul_f32 v[124:125], v[124:125], v[124:125]
	v_pk_mul_f32 v[126:127], v[126:127], v[126:127]
	v_cvt_pk_bf16_f32 v112, v112, v113
	v_cvt_pk_bf16_f32 v113, v116, v117
	v_cvt_pk_bf16_f32 v114, v114, v115
	v_cvt_pk_bf16_f32 v115, v118, v119
	v_cvt_pk_bf16_f32 v116, v120, v121
	v_cvt_pk_bf16_f32 v117, v124, v125
	v_cvt_pk_bf16_f32 v118, v122, v123
	v_cvt_pk_bf16_f32 v119, v126, v127
	global_store_dwordx4 v[146:147], v[112:115], off
	global_store_dwordx4 v[146:147], v[116:119], off offset:256
	global_load_dword v116, v[164:165], off
	v_lshlrev_b64 v[114:115], 12, v[162:163]
	v_or_b32_e32 v112, 32, v148
	v_lshl_add_u64 v[114:115], s[6:7], 0, v[114:115]
	v_ashrrev_i32_e32 v113, 31, v112
	v_lshl_add_u64 v[114:115], v[114:115], 0, v[150:151]
	s_waitcnt vmcnt(0)
	v_fmamk_f32 v116, v116, 0x3a800000, v160
	v_mul_f32_e32 v117, 0x4b800000, v116
	v_cmp_gt_f32_e32 vcc, s61, v116
	s_nop 1
	v_cndmask_b32_e32 v116, v116, v117, vcc
	v_rsq_f32_e32 v118, v116
	v_lshl_add_u64 v[116:117], v[112:113], 2, s[18:19]
	v_mul_f32_e32 v119, 0x45800000, v118
	v_cndmask_b32_e32 v118, v118, v119, vcc
	v_mul_f32_e32 v108, v108, v118
	v_mul_f32_e32 v104, v104, v118
	v_mul_f32_e32 v109, v109, v118
	v_mul_f32_e32 v105, v105, v118
	v_mul_f32_e32 v110, v110, v118
	v_mul_f32_e32 v106, v106, v118
	v_mul_f32_e32 v111, v111, v118
	v_mul_f32_e32 v107, v107, v118
	v_mul_f32_e32 v119, v100, v118
	v_mul_f32_e32 v120, v96, v118
	v_mul_f32_e32 v121, v101, v118
	v_mul_f32_e32 v122, v97, v118
	v_mul_f32_e32 v123, v102, v118
	v_mul_f32_e32 v124, v98, v118
	v_mul_f32_e32 v125, v103, v118
	v_mul_f32_e32 v118, v99, v118
	v_max_f32_e32 v96, 0, v108
	v_max_f32_e32 v98, 0, v104
	v_max_f32_e32 v97, 0, v109
	v_max_f32_e32 v99, 0, v105
	v_max_f32_e32 v100, 0, v110
	v_max_f32_e32 v102, 0, v106
	v_max_f32_e32 v101, 0, v111
	v_max_f32_e32 v103, 0, v107
	v_max_f32_e32 v104, 0, v119
	v_max_f32_e32 v106, 0, v120
	v_max_f32_e32 v105, 0, v121
	v_max_f32_e32 v107, 0, v122
	v_max_f32_e32 v108, 0, v123
	v_max_f32_e32 v110, 0, v124
	v_max_f32_e32 v109, 0, v125
	v_max_f32_e32 v111, 0, v118
	v_pk_mul_f32 v[96:97], v[96:97], v[96:97]
	v_pk_mul_f32 v[98:99], v[98:99], v[98:99]
	v_pk_mul_f32 v[100:101], v[100:101], v[100:101]
	v_pk_mul_f32 v[102:103], v[102:103], v[102:103]
	v_pk_mul_f32 v[104:105], v[104:105], v[104:105]
	v_pk_mul_f32 v[106:107], v[106:107], v[106:107]
	v_pk_mul_f32 v[108:109], v[108:109], v[108:109]
	v_pk_mul_f32 v[110:111], v[110:111], v[110:111]
	v_cvt_pk_bf16_f32 v96, v96, v97
	v_cvt_pk_bf16_f32 v97, v100, v101
	v_cvt_pk_bf16_f32 v98, v98, v99
	v_cvt_pk_bf16_f32 v99, v102, v103
	v_cvt_pk_bf16_f32 v100, v104, v105
	v_cvt_pk_bf16_f32 v101, v108, v109
	v_cvt_pk_bf16_f32 v102, v106, v107
	v_cvt_pk_bf16_f32 v103, v110, v111
	global_store_dwordx4 v[114:115], v[96:99], off
	global_store_dwordx4 v[114:115], v[100:103], off offset:256
	global_load_dword v100, v[116:117], off
	v_lshlrev_b64 v[98:99], 12, v[112:113]
	v_or_b32_e32 v96, 48, v148
	v_lshl_add_u64 v[98:99], s[6:7], 0, v[98:99]
	v_ashrrev_i32_e32 v97, 31, v96
	v_lshl_add_u64 v[98:99], v[98:99], 0, v[150:151]
	s_waitcnt vmcnt(0)
	v_fmamk_f32 v100, v100, 0x3a800000, v160
	v_mul_f32_e32 v101, 0x4b800000, v100
	v_cmp_gt_f32_e32 vcc, s61, v100
	s_nop 1
	v_cndmask_b32_e32 v100, v100, v101, vcc
	v_rsq_f32_e32 v102, v100
	v_lshl_add_u64 v[100:101], v[96:97], 2, s[18:19]
	v_mul_f32_e32 v103, 0x45800000, v102
	v_cndmask_b32_e32 v102, v102, v103, vcc
	v_mul_f32_e32 v92, v92, v102
	v_mul_f32_e32 v88, v88, v102
	v_mul_f32_e32 v93, v93, v102
	v_mul_f32_e32 v89, v89, v102
	v_mul_f32_e32 v94, v94, v102
	v_mul_f32_e32 v90, v90, v102
	v_mul_f32_e32 v95, v95, v102
	v_mul_f32_e32 v91, v91, v102
	v_mul_f32_e32 v103, v84, v102
	v_mul_f32_e32 v104, v80, v102
	v_mul_f32_e32 v105, v85, v102
	v_mul_f32_e32 v106, v81, v102
	v_mul_f32_e32 v107, v86, v102
	v_mul_f32_e32 v108, v82, v102
	v_mul_f32_e32 v109, v87, v102
	v_mul_f32_e32 v102, v83, v102
	v_max_f32_e32 v80, 0, v92
	v_max_f32_e32 v82, 0, v88
	v_max_f32_e32 v81, 0, v93
	v_max_f32_e32 v83, 0, v89
	v_max_f32_e32 v84, 0, v94
	v_max_f32_e32 v86, 0, v90
	v_max_f32_e32 v85, 0, v95
	v_max_f32_e32 v87, 0, v91
	v_max_f32_e32 v88, 0, v103
	v_max_f32_e32 v90, 0, v104
	v_max_f32_e32 v89, 0, v105
	v_max_f32_e32 v91, 0, v106
	v_max_f32_e32 v92, 0, v107
	v_max_f32_e32 v94, 0, v108
	v_max_f32_e32 v93, 0, v109
	v_max_f32_e32 v95, 0, v102
	v_pk_mul_f32 v[80:81], v[80:81], v[80:81]
	v_pk_mul_f32 v[82:83], v[82:83], v[82:83]
	v_pk_mul_f32 v[84:85], v[84:85], v[84:85]
	v_pk_mul_f32 v[86:87], v[86:87], v[86:87]
	v_pk_mul_f32 v[88:89], v[88:89], v[88:89]
	v_pk_mul_f32 v[90:91], v[90:91], v[90:91]
	v_pk_mul_f32 v[92:93], v[92:93], v[92:93]
	v_pk_mul_f32 v[94:95], v[94:95], v[94:95]
	v_cvt_pk_bf16_f32 v80, v80, v81
	v_cvt_pk_bf16_f32 v81, v84, v85
	v_cvt_pk_bf16_f32 v82, v82, v83
	v_cvt_pk_bf16_f32 v83, v86, v87
	v_cvt_pk_bf16_f32 v84, v88, v89
	v_cvt_pk_bf16_f32 v85, v92, v93
	v_cvt_pk_bf16_f32 v86, v90, v91
	v_cvt_pk_bf16_f32 v87, v94, v95
	global_store_dwordx4 v[98:99], v[80:83], off
	global_store_dwordx4 v[98:99], v[84:87], off offset:256
	global_load_dword v80, v[100:101], off
	s_waitcnt vmcnt(0)
	v_fmamk_f32 v80, v80, 0x3a800000, v160
	v_mul_f32_e32 v81, 0x4b800000, v80
	v_cmp_gt_f32_e32 vcc, s61, v80
	s_nop 1
	v_cndmask_b32_e32 v80, v80, v81, vcc
	v_rsq_f32_e32 v82, v80
	v_lshlrev_b64 v[80:81], 12, v[96:97]
	v_lshl_add_u64 v[80:81], s[6:7], 0, v[80:81]
	v_lshl_add_u64 v[80:81], v[80:81], 0, v[150:151]
	v_mul_f32_e32 v83, 0x45800000, v82
	v_cndmask_b32_e32 v82, v82, v83, vcc
	v_mul_f32_e32 v76, v76, v82
	v_mul_f32_e32 v72, v72, v82
	v_mul_f32_e32 v77, v77, v82
	v_mul_f32_e32 v73, v73, v82
	v_mul_f32_e32 v78, v78, v82
	v_mul_f32_e32 v74, v74, v82
	v_mul_f32_e32 v79, v79, v82
	v_mul_f32_e32 v75, v75, v82
	v_mul_f32_e32 v83, v68, v82
	v_mul_f32_e32 v84, v64, v82
	v_mul_f32_e32 v85, v69, v82
	v_mul_f32_e32 v86, v65, v82
	v_mul_f32_e32 v87, v70, v82
	v_mul_f32_e32 v88, v66, v82
	v_mul_f32_e32 v89, v71, v82
	v_mul_f32_e32 v82, v67, v82
	v_max_f32_e32 v64, 0, v76
	v_max_f32_e32 v66, 0, v72
	v_max_f32_e32 v65, 0, v77
	v_max_f32_e32 v67, 0, v73
	v_max_f32_e32 v68, 0, v78
	v_max_f32_e32 v70, 0, v74
	v_max_f32_e32 v69, 0, v79
	v_max_f32_e32 v71, 0, v75
	v_max_f32_e32 v72, 0, v83
	v_max_f32_e32 v74, 0, v84
	v_max_f32_e32 v73, 0, v85
	v_max_f32_e32 v75, 0, v86
	v_max_f32_e32 v76, 0, v87
	v_max_f32_e32 v78, 0, v88
	v_max_f32_e32 v77, 0, v89
	v_max_f32_e32 v79, 0, v82
	v_pk_mul_f32 v[64:65], v[64:65], v[64:65]
	v_pk_mul_f32 v[66:67], v[66:67], v[66:67]
	v_pk_mul_f32 v[68:69], v[68:69], v[68:69]
	v_pk_mul_f32 v[70:71], v[70:71], v[70:71]
	v_pk_mul_f32 v[72:73], v[72:73], v[72:73]
	v_pk_mul_f32 v[74:75], v[74:75], v[74:75]
	v_pk_mul_f32 v[76:77], v[76:77], v[76:77]
	v_pk_mul_f32 v[78:79], v[78:79], v[78:79]
	v_cvt_pk_bf16_f32 v64, v64, v65
	v_cvt_pk_bf16_f32 v65, v68, v69
	v_cvt_pk_bf16_f32 v66, v66, v67
	v_cvt_pk_bf16_f32 v67, v70, v71
	v_cvt_pk_bf16_f32 v68, v72, v73
	v_cvt_pk_bf16_f32 v69, v76, v77
	v_cvt_pk_bf16_f32 v70, v74, v75
	v_cvt_pk_bf16_f32 v71, v78, v79
	global_store_dwordx4 v[80:81], v[64:67], off
	global_store_dwordx4 v[80:81], v[68:71], off offset:256
	global_load_dword v66, v[144:145], off offset:512
	v_lshl_add_u64 v[64:65], v[146:147], 0, s[16:17]
	s_waitcnt vmcnt(0)
	v_fmamk_f32 v66, v66, 0x3a800000, v160
	v_mul_f32_e32 v67, 0x4b800000, v66
	v_cmp_gt_f32_e32 vcc, s61, v66
	s_nop 1
	v_cndmask_b32_e32 v66, v66, v67, vcc
	v_rsq_f32_e32 v68, v66
	v_add_co_u32_e64 v66, s[6:7], s62, v146
	v_mul_f32_e32 v69, 0x45800000, v68
	v_cndmask_b32_e32 v68, v68, v69, vcc
	v_mul_f32_e32 v60, v60, v68
	v_mul_f32_e32 v56, v56, v68
	v_mul_f32_e32 v61, v61, v68
	v_mul_f32_e32 v57, v57, v68
	v_mul_f32_e32 v62, v62, v68
	v_mul_f32_e32 v58, v58, v68
	v_mul_f32_e32 v63, v63, v68
	v_mul_f32_e32 v59, v59, v68
	v_mul_f32_e32 v69, v52, v68
	v_mul_f32_e32 v70, v48, v68
	v_mul_f32_e32 v71, v53, v68
	v_mul_f32_e32 v72, v49, v68
	v_mul_f32_e32 v73, v54, v68
	v_mul_f32_e32 v74, v50, v68
	v_mul_f32_e32 v75, v55, v68
	v_mul_f32_e32 v68, v51, v68
	v_max_f32_e32 v48, 0, v60
	v_max_f32_e32 v50, 0, v56
	v_max_f32_e32 v49, 0, v61
	v_max_f32_e32 v51, 0, v57
	v_max_f32_e32 v52, 0, v62
	v_max_f32_e32 v54, 0, v58
	v_max_f32_e32 v53, 0, v63
	v_max_f32_e32 v55, 0, v59
	v_max_f32_e32 v56, 0, v69
	v_max_f32_e32 v58, 0, v70
	v_max_f32_e32 v57, 0, v71
	v_max_f32_e32 v59, 0, v72
	v_max_f32_e32 v60, 0, v73
	v_max_f32_e32 v62, 0, v74
	v_max_f32_e32 v61, 0, v75
	v_max_f32_e32 v63, 0, v68
	v_pk_mul_f32 v[48:49], v[48:49], v[48:49]
	v_pk_mul_f32 v[50:51], v[50:51], v[50:51]
	v_pk_mul_f32 v[52:53], v[52:53], v[52:53]
	v_pk_mul_f32 v[54:55], v[54:55], v[54:55]
	v_addc_co_u32_e64 v67, s[6:7], 0, v147, s[6:7]
	v_pk_mul_f32 v[56:57], v[56:57], v[56:57]
	v_pk_mul_f32 v[58:59], v[58:59], v[58:59]
	v_pk_mul_f32 v[60:61], v[60:61], v[60:61]
	v_pk_mul_f32 v[62:63], v[62:63], v[62:63]
	v_cvt_pk_bf16_f32 v48, v48, v49
	v_cvt_pk_bf16_f32 v49, v52, v53
	v_cvt_pk_bf16_f32 v50, v50, v51
	v_cvt_pk_bf16_f32 v51, v54, v55
	v_cvt_pk_bf16_f32 v52, v56, v57
	v_cvt_pk_bf16_f32 v53, v60, v61
	v_cvt_pk_bf16_f32 v54, v58, v59
	v_cvt_pk_bf16_f32 v55, v62, v63
	global_store_dwordx4 v[66:67], v[48:51], off
	global_store_dwordx4 v[64:65], v[52:55], off offset:256
	global_load_dword v50, v[144:145], off offset:576
	v_lshl_add_u64 v[48:49], v[146:147], 0, s[20:21]
	s_waitcnt vmcnt(0)
	v_fmamk_f32 v50, v50, 0x3a800000, v160
	v_mul_f32_e32 v51, 0x4b800000, v50
	v_cmp_gt_f32_e32 vcc, s61, v50
	s_nop 1
	v_cndmask_b32_e32 v50, v50, v51, vcc
	v_rsq_f32_e32 v52, v50
	v_add_co_u32_e64 v50, s[6:7], s63, v146
	v_mul_f32_e32 v53, 0x45800000, v52
	v_cndmask_b32_e32 v52, v52, v53, vcc
	v_mul_f32_e32 v44, v44, v52
	v_mul_f32_e32 v40, v40, v52
	v_mul_f32_e32 v45, v45, v52
	v_mul_f32_e32 v41, v41, v52
	v_mul_f32_e32 v46, v46, v52
	v_mul_f32_e32 v42, v42, v52
	v_mul_f32_e32 v47, v47, v52
	v_mul_f32_e32 v43, v43, v52
	v_mul_f32_e32 v53, v36, v52
	v_mul_f32_e32 v54, v32, v52
	v_mul_f32_e32 v55, v37, v52
	v_mul_f32_e32 v56, v33, v52
	v_mul_f32_e32 v57, v38, v52
	v_mul_f32_e32 v58, v34, v52
	v_mul_f32_e32 v59, v39, v52
	v_mul_f32_e32 v52, v35, v52
	v_max_f32_e32 v32, 0, v44
	v_max_f32_e32 v34, 0, v40
	v_max_f32_e32 v33, 0, v45
	v_max_f32_e32 v35, 0, v41
	v_max_f32_e32 v36, 0, v46
	v_max_f32_e32 v38, 0, v42
	v_max_f32_e32 v37, 0, v47
	v_max_f32_e32 v39, 0, v43
	v_max_f32_e32 v40, 0, v53
	v_max_f32_e32 v42, 0, v54
	v_max_f32_e32 v41, 0, v55
	v_max_f32_e32 v43, 0, v56
	v_max_f32_e32 v44, 0, v57
	v_max_f32_e32 v46, 0, v58
	v_max_f32_e32 v45, 0, v59
	v_max_f32_e32 v47, 0, v52
	v_pk_mul_f32 v[32:33], v[32:33], v[32:33]
	v_pk_mul_f32 v[34:35], v[34:35], v[34:35]
	v_pk_mul_f32 v[36:37], v[36:37], v[36:37]
	v_pk_mul_f32 v[38:39], v[38:39], v[38:39]
	v_addc_co_u32_e64 v51, s[6:7], 0, v147, s[6:7]
	v_pk_mul_f32 v[40:41], v[40:41], v[40:41]
	v_pk_mul_f32 v[42:43], v[42:43], v[42:43]
	v_pk_mul_f32 v[44:45], v[44:45], v[44:45]
	v_pk_mul_f32 v[46:47], v[46:47], v[46:47]
	v_cvt_pk_bf16_f32 v32, v32, v33
	v_cvt_pk_bf16_f32 v33, v36, v37
	v_cvt_pk_bf16_f32 v34, v34, v35
	v_cvt_pk_bf16_f32 v35, v38, v39
	v_cvt_pk_bf16_f32 v36, v40, v41
	v_cvt_pk_bf16_f32 v37, v44, v45
	v_cvt_pk_bf16_f32 v38, v42, v43
	v_cvt_pk_bf16_f32 v39, v46, v47
	global_store_dwordx4 v[50:51], v[32:35], off
	global_store_dwordx4 v[48:49], v[36:39], off offset:256
	global_load_dword v34, v[144:145], off offset:640
	v_lshl_add_u64 v[32:33], v[146:147], 0, s[22:23]
	s_waitcnt vmcnt(0)
	v_fmamk_f32 v34, v34, 0x3a800000, v160
	v_mul_f32_e32 v35, 0x4b800000, v34
	v_cmp_gt_f32_e32 vcc, s61, v34
	s_nop 1
	v_cndmask_b32_e32 v34, v34, v35, vcc
	v_rsq_f32_e32 v36, v34
	v_add_co_u32_e64 v34, s[6:7], s64, v146
	v_mul_f32_e32 v37, 0x45800000, v36
	v_cndmask_b32_e32 v36, v36, v37, vcc
	v_mul_f32_e32 v28, v28, v36
	v_mul_f32_e32 v24, v24, v36
	v_mul_f32_e32 v29, v29, v36
	v_mul_f32_e32 v25, v25, v36
	v_mul_f32_e32 v30, v30, v36
	v_mul_f32_e32 v26, v26, v36
	v_mul_f32_e32 v31, v31, v36
	v_mul_f32_e32 v27, v27, v36
	v_mul_f32_e32 v37, v20, v36
	v_mul_f32_e32 v38, v16, v36
	v_mul_f32_e32 v39, v21, v36
	v_mul_f32_e32 v40, v17, v36
	v_mul_f32_e32 v41, v22, v36
	v_mul_f32_e32 v42, v18, v36
	v_mul_f32_e32 v43, v23, v36
	v_mul_f32_e32 v36, v19, v36
	v_max_f32_e32 v16, 0, v28
	v_max_f32_e32 v18, 0, v24
	v_max_f32_e32 v17, 0, v29
	v_max_f32_e32 v19, 0, v25
	v_max_f32_e32 v20, 0, v30
	v_max_f32_e32 v22, 0, v26
	v_max_f32_e32 v21, 0, v31
	v_max_f32_e32 v23, 0, v27
	v_max_f32_e32 v24, 0, v37
	v_max_f32_e32 v26, 0, v38
	v_max_f32_e32 v25, 0, v39
	v_max_f32_e32 v27, 0, v40
	v_max_f32_e32 v28, 0, v41
	v_max_f32_e32 v30, 0, v42
	v_max_f32_e32 v29, 0, v43
	v_max_f32_e32 v31, 0, v36
	v_pk_mul_f32 v[16:17], v[16:17], v[16:17]
	v_pk_mul_f32 v[18:19], v[18:19], v[18:19]
	v_pk_mul_f32 v[20:21], v[20:21], v[20:21]
	v_pk_mul_f32 v[22:23], v[22:23], v[22:23]
	v_addc_co_u32_e64 v35, s[6:7], 0, v147, s[6:7]
	v_pk_mul_f32 v[24:25], v[24:25], v[24:25]
	v_pk_mul_f32 v[26:27], v[26:27], v[26:27]
	v_pk_mul_f32 v[28:29], v[28:29], v[28:29]
	v_pk_mul_f32 v[30:31], v[30:31], v[30:31]
	v_cvt_pk_bf16_f32 v16, v16, v17
	v_cvt_pk_bf16_f32 v17, v20, v21
	v_cvt_pk_bf16_f32 v18, v18, v19
	v_cvt_pk_bf16_f32 v19, v22, v23
	v_cvt_pk_bf16_f32 v20, v24, v25
	v_cvt_pk_bf16_f32 v21, v28, v29
	v_cvt_pk_bf16_f32 v22, v26, v27
	v_cvt_pk_bf16_f32 v23, v30, v31
	global_store_dwordx4 v[34:35], v[16:19], off
	global_store_dwordx4 v[32:33], v[20:23], off offset:256
	global_load_dword v18, v[144:145], off offset:704
	s_and_b64 vcc, exec, s[4:5]
	v_lshl_add_u64 v[16:17], v[146:147], 0, s[24:25]
	s_waitcnt vmcnt(0)
	v_fmamk_f32 v18, v18, 0x3a800000, v160
	v_mul_f32_e32 v19, 0x4b800000, v18
	v_cmp_gt_f32_e64 s[4:5], s61, v18
	s_nop 1
	v_cndmask_b32_e64 v18, v18, v19, s[4:5]
	v_rsq_f32_e32 v20, v18
	v_add_co_u32_e64 v18, s[6:7], s65, v146
	v_mul_f32_e32 v21, 0x45800000, v20
	v_cndmask_b32_e64 v20, v20, v21, s[4:5]
	v_mul_f32_e32 v12, v12, v20
	v_mul_f32_e32 v8, v8, v20
	v_mul_f32_e32 v13, v13, v20
	v_mul_f32_e32 v9, v9, v20
	v_mul_f32_e32 v14, v14, v20
	v_mul_f32_e32 v10, v10, v20
	v_mul_f32_e32 v15, v15, v20
	v_mul_f32_e32 v11, v11, v20
	v_mul_f32_e32 v21, v4, v20
	v_mul_f32_e32 v22, v0, v20
	v_mul_f32_e32 v23, v5, v20
	v_mul_f32_e32 v24, v1, v20
	v_mul_f32_e32 v25, v6, v20
	v_mul_f32_e32 v26, v2, v20
	v_mul_f32_e32 v27, v7, v20
	v_mul_f32_e32 v20, v3, v20
	v_max_f32_e32 v0, 0, v12
	v_max_f32_e32 v2, 0, v8
	v_max_f32_e32 v1, 0, v13
	v_max_f32_e32 v3, 0, v9
	v_max_f32_e32 v4, 0, v14
	v_max_f32_e32 v6, 0, v10
	v_max_f32_e32 v5, 0, v15
	v_max_f32_e32 v7, 0, v11
	v_max_f32_e32 v8, 0, v21
	v_max_f32_e32 v10, 0, v22
	v_max_f32_e32 v9, 0, v23
	v_max_f32_e32 v11, 0, v24
	v_max_f32_e32 v12, 0, v25
	v_max_f32_e32 v14, 0, v26
	v_max_f32_e32 v13, 0, v27
	v_max_f32_e32 v15, 0, v20
	v_pk_mul_f32 v[0:1], v[0:1], v[0:1]
	v_pk_mul_f32 v[2:3], v[2:3], v[2:3]
	v_pk_mul_f32 v[4:5], v[4:5], v[4:5]
	v_pk_mul_f32 v[6:7], v[6:7], v[6:7]
	v_addc_co_u32_e64 v19, s[6:7], 0, v147, s[6:7]
	v_pk_mul_f32 v[8:9], v[8:9], v[8:9]
	v_pk_mul_f32 v[10:11], v[10:11], v[10:11]
	v_pk_mul_f32 v[12:13], v[12:13], v[12:13]
	v_pk_mul_f32 v[14:15], v[14:15], v[14:15]
	v_cvt_pk_bf16_f32 v0, v0, v1
	v_cvt_pk_bf16_f32 v1, v4, v5
	v_cvt_pk_bf16_f32 v2, v2, v3
	v_cvt_pk_bf16_f32 v3, v6, v7
	v_cvt_pk_bf16_f32 v4, v8, v9
	v_cvt_pk_bf16_f32 v5, v12, v13
	v_cvt_pk_bf16_f32 v6, v10, v11
	v_cvt_pk_bf16_f32 v7, v14, v15
	global_store_dwordx4 v[18:19], v[0:3], off
	global_store_dwordx4 v[16:17], v[4:7], off offset:256
	s_cbranch_vccz .LBB0_694
	s_waitcnt vmcnt(0)
	s_cmpk_gt_u32 s33, 0xff
	s_cbranch_scc1 .LBB0_701
	s_barrier

.LBB0_722:
	s_or_b32 s52, s37, 1
	s_sub_i32 s53, s52, s57
	s_min_u32 s53, s52, s53
	s_cmp_lt_u32 s52, s57
	s_cselect_b32 s52, s45, s58
	s_cselect_b32 s67, s44, s59
	s_lshl_b32 s53, s53, 7
	v_add_u32_e32 v149, s65, v145
	s_add_u32 s53, s67, s53
	ds_read_b128 v[140:143], v149
	ds_read_b128 v[150:153], v149 offset:1024
	ds_read_b128 v[156:159], v149 offset:2048
	ds_read_b128 v[160:163], v149 offset:3072
	s_addc_u32 s67, s52, 0
	s_lshl_b32 s52, s37, 7
	s_add_u32 s52, s40, s52
	s_addc_u32 s68, s41, 0
	s_add_u32 s52, s52, 0x100
	s_addc_u32 s68, s68, 0
	s_and_b64 s[50:51], exec, s[50:51]
	s_cselect_b32 s51, s19, s68
	s_cselect_b32 s50, s21, s52
	s_add_u32 s52, s53, 0x80000
	s_addc_u32 s53, s67, 0
	v_lshl_add_u64 v[196:197], s[52:53], 0, v[128:129]
	s_add_i32 m0, s35, 0xc000
	ds_read_b128 v[164:167], v147
	ds_read_b128 v[168:171], v147 offset:1024
	ds_read_b128 v[172:175], v147 offset:2048
	ds_read_b128 v[176:179], v147 offset:3072
	ds_read_b128 v[180:183], v147 offset:4096
	ds_read_b128 v[184:187], v147 offset:5120
	ds_read_b128 v[188:191], v147 offset:6144
	ds_read_b128 v[192:195], v147 offset:7168
	global_load_lds_dwordx4 v[196:197], off
	s_add_i32 m0, s35, 0xe000
	v_lshl_add_u64 v[196:197], s[52:53], 0, v[132:133]
	global_load_lds_dwordx4 v[196:197], off
	s_barrier
	s_waitcnt lgkmcnt(0)
	v_mfma_f32_16x16x32_bf16 v[124:127], v[140:143], v[164:167], v[124:127]
	v_mfma_f32_16x16x32_bf16 v[120:123], v[156:159], v[164:167], v[120:123]
	v_mfma_f32_16x16x32_bf16 v[108:111], v[140:143], v[172:175], v[108:111]
	v_mfma_f32_16x16x32_bf16 v[104:107], v[156:159], v[172:175], v[104:107]
	v_mfma_f32_16x16x32_bf16 v[92:95], v[140:143], v[180:183], v[92:95]
	v_mfma_f32_16x16x32_bf16 v[88:91], v[156:159], v[180:183], v[88:91]
	v_mfma_f32_16x16x32_bf16 v[76:79], v[140:143], v[188:191], v[76:79]
	v_mfma_f32_16x16x32_bf16 v[72:75], v[156:159], v[188:191], v[72:75]
	v_mfma_f32_16x16x32_bf16 v[124:127], v[150:153], v[168:171], v[124:127]
	v_mfma_f32_16x16x32_bf16 v[120:123], v[160:163], v[168:171], v[120:123]
	v_mfma_f32_16x16x32_bf16 v[108:111], v[150:153], v[176:179], v[108:111]
	v_mfma_f32_16x16x32_bf16 v[104:107], v[160:163], v[176:179], v[104:107]
	v_mfma_f32_16x16x32_bf16 v[92:95], v[150:153], v[184:187], v[92:95]
	v_mfma_f32_16x16x32_bf16 v[88:91], v[160:163], v[184:187], v[88:91]
	v_mfma_f32_16x16x32_bf16 v[76:79], v[150:153], v[192:195], v[76:79]
	v_mfma_f32_16x16x32_bf16 v[72:75], v[160:163], v[192:195], v[72:75]
	s_barrier
	s_add_i32 s52, s65, s34
	v_add_u32_e32 v149, s72, v145
	v_lshl_add_u64 v[212:213], s[50:51], 0, v[130:131]
	s_mov_b32 m0, s52
	ds_read_b128 v[196:199], v149
	ds_read_b128 v[200:203], v149 offset:1024
	ds_read_b128 v[204:207], v149 offset:2048
	ds_read_b128 v[208:211], v149 offset:3072
	global_load_lds_dwordx4 v[212:213], off
	s_add_i32 m0, s52, 0x2000
	v_lshl_add_u64 v[214:215], s[50:51], 0, v[134:135]
	global_load_lds_dwordx4 v[214:215], off
	s_barrier
	s_waitcnt lgkmcnt(0)
	v_mfma_f32_16x16x32_bf16 v[116:119], v[196:199], v[164:167], v[116:119]
	v_mfma_f32_16x16x32_bf16 v[112:115], v[204:207], v[164:167], v[112:115]
	v_mfma_f32_16x16x32_bf16 v[100:103], v[196:199], v[172:175], v[100:103]
	v_mfma_f32_16x16x32_bf16 v[96:99], v[204:207], v[172:175], v[96:99]
	v_mfma_f32_16x16x32_bf16 v[84:87], v[196:199], v[180:183], v[84:87]
	v_mfma_f32_16x16x32_bf16 v[80:83], v[204:207], v[180:183], v[80:83]
	v_mfma_f32_16x16x32_bf16 v[68:71], v[196:199], v[188:191], v[68:71]
	v_mfma_f32_16x16x32_bf16 v[64:67], v[204:207], v[188:191], v[64:67]
	v_mfma_f32_16x16x32_bf16 v[116:119], v[200:203], v[168:171], v[116:119]
	v_mfma_f32_16x16x32_bf16 v[112:115], v[208:211], v[168:171], v[112:115]
	v_mfma_f32_16x16x32_bf16 v[100:103], v[200:203], v[176:179], v[100:103]
	v_mfma_f32_16x16x32_bf16 v[96:99], v[208:211], v[176:179], v[96:99]
	v_mfma_f32_16x16x32_bf16 v[84:87], v[200:203], v[184:187], v[84:87]
	v_mfma_f32_16x16x32_bf16 v[80:83], v[208:211], v[184:187], v[80:83]
	v_mfma_f32_16x16x32_bf16 v[68:71], v[200:203], v[192:195], v[68:71]
	v_mfma_f32_16x16x32_bf16 v[64:67], v[208:211], v[192:195], v[64:67]
	s_mov_b32 m0, s35
	v_lshl_add_u64 v[216:217], s[48:49], 0, v[128:129]
	s_barrier
	ds_read_b128 v[164:167], v147 offset:16384
	ds_read_b128 v[168:171], v147 offset:17408
	ds_read_b128 v[172:175], v147 offset:18432
	ds_read_b128 v[176:179], v147 offset:19456
	ds_read_b128 v[180:183], v147 offset:20480
	ds_read_b128 v[184:187], v147 offset:21504
	ds_read_b128 v[188:191], v147 offset:22528
	ds_read_b128 v[192:195], v147 offset:23552
	global_load_lds_dwordx4 v[216:217], off
	s_mov_b32 m0, s39
	v_lshl_add_u64 v[218:219], s[48:49], 0, v[132:133]
	global_load_lds_dwordx4 v[218:219], off
	s_barrier
	s_waitcnt lgkmcnt(0)
	v_mfma_f32_16x16x32_bf16 v[60:63], v[140:143], v[164:167], v[60:63]
	v_mfma_f32_16x16x32_bf16 v[56:59], v[156:159], v[164:167], v[56:59]
	v_mfma_f32_16x16x32_bf16 v[44:47], v[140:143], v[172:175], v[44:47]
	v_mfma_f32_16x16x32_bf16 v[40:43], v[156:159], v[172:175], v[40:43]
	v_mfma_f32_16x16x32_bf16 v[28:31], v[140:143], v[180:183], v[28:31]
	v_mfma_f32_16x16x32_bf16 v[24:27], v[156:159], v[180:183], v[24:27]
	v_mfma_f32_16x16x32_bf16 v[12:15], v[140:143], v[188:191], v[12:15]
	v_mfma_f32_16x16x32_bf16 v[8:11], v[156:159], v[188:191], v[8:11]
	v_mfma_f32_16x16x32_bf16 v[60:63], v[150:153], v[168:171], v[60:63]
	v_mfma_f32_16x16x32_bf16 v[56:59], v[160:163], v[168:171], v[56:59]
	v_mfma_f32_16x16x32_bf16 v[44:47], v[150:153], v[176:179], v[44:47]
	v_mfma_f32_16x16x32_bf16 v[40:43], v[160:163], v[176:179], v[40:43]
	v_mfma_f32_16x16x32_bf16 v[28:31], v[150:153], v[184:187], v[28:31]
	v_mfma_f32_16x16x32_bf16 v[24:27], v[160:163], v[184:187], v[24:27]
	v_mfma_f32_16x16x32_bf16 v[12:15], v[150:153], v[192:195], v[12:15]
	v_mfma_f32_16x16x32_bf16 v[8:11], v[160:163], v[192:195], v[8:11]
	s_barrier
	s_add_u32 s52, s50, 0x100000
	s_addc_u32 s53, s51, 0
	s_add_i32 s67, s72, s34
	s_mov_b32 m0, s67
	v_lshl_add_u64 v[140:141], s[52:53], 0, v[130:131]
	global_load_lds_dwordx4 v[140:141], off
	s_add_i32 m0, s67, 0x2000
	v_lshl_add_u64 v[140:141], s[52:53], 0, v[134:135]
	global_load_lds_dwordx4 v[140:141], off
	s_waitcnt vmcnt(6)
	s_barrier
	v_mfma_f32_16x16x32_bf16 v[52:55], v[196:199], v[164:167], v[52:55]
	v_mfma_f32_16x16x32_bf16 v[48:51], v[204:207], v[164:167], v[48:51]
	v_mfma_f32_16x16x32_bf16 v[36:39], v[196:199], v[172:175], v[36:39]
	v_mfma_f32_16x16x32_bf16 v[32:35], v[204:207], v[172:175], v[32:35]
	v_mfma_f32_16x16x32_bf16 v[20:23], v[196:199], v[180:183], v[20:23]
	v_mfma_f32_16x16x32_bf16 v[16:19], v[204:207], v[180:183], v[16:19]
	v_mfma_f32_16x16x32_bf16 v[4:7], v[196:199], v[188:191], v[4:7]
	v_mfma_f32_16x16x32_bf16 v[0:3], v[204:207], v[188:191], v[0:3]
	v_mfma_f32_16x16x32_bf16 v[52:55], v[200:203], v[168:171], v[52:55]
	v_mfma_f32_16x16x32_bf16 v[48:51], v[208:211], v[168:171], v[48:51]
	v_mfma_f32_16x16x32_bf16 v[36:39], v[200:203], v[176:179], v[36:39]
	v_mfma_f32_16x16x32_bf16 v[32:35], v[208:211], v[176:179], v[32:35]
	v_mfma_f32_16x16x32_bf16 v[20:23], v[200:203], v[184:187], v[20:23]
	v_mfma_f32_16x16x32_bf16 v[16:19], v[208:211], v[184:187], v[16:19]
	v_mfma_f32_16x16x32_bf16 v[4:7], v[200:203], v[192:195], v[4:7]
	v_mfma_f32_16x16x32_bf16 v[0:3], v[208:211], v[192:195], v[0:3]
	s_add_i32 s52, 0, 0x18000
	v_add_u32_e32 v149, s52, v145
	s_barrier
	ds_read_b128 v[140:143], v149
	ds_read_b128 v[150:153], v149 offset:1024
	ds_read_b128 v[156:159], v149 offset:2048
	ds_read_b128 v[160:163], v149 offset:3072
	s_add_u32 s48, s48, 0x80000
	s_addc_u32 s49, s49, 0
	s_mov_b32 m0, s54
	v_lshl_add_u64 v[196:197], s[48:49], 0, v[128:129]
	ds_read_b128 v[164:167], v147 offset:32768
	ds_read_b128 v[168:171], v147 offset:33792
	ds_read_b128 v[172:175], v147 offset:34816
	ds_read_b128 v[176:179], v147 offset:35840
	ds_read_b128 v[180:183], v147 offset:36864
	ds_read_b128 v[184:187], v147 offset:37888
	ds_read_b128 v[188:191], v147 offset:38912
	ds_read_b128 v[192:195], v147 offset:39936
	global_load_lds_dwordx4 v[196:197], off
	s_mov_b32 m0, s55
	v_lshl_add_u64 v[196:197], s[48:49], 0, v[132:133]
	global_load_lds_dwordx4 v[196:197], off
	s_barrier
	s_waitcnt lgkmcnt(0)
	v_mfma_f32_16x16x32_bf16 v[124:127], v[140:143], v[164:167], v[124:127]
	v_mfma_f32_16x16x32_bf16 v[120:123], v[156:159], v[164:167], v[120:123]
	v_mfma_f32_16x16x32_bf16 v[108:111], v[140:143], v[172:175], v[108:111]
	v_mfma_f32_16x16x32_bf16 v[104:107], v[156:159], v[172:175], v[104:107]
	v_mfma_f32_16x16x32_bf16 v[92:95], v[140:143], v[180:183], v[92:95]
	v_mfma_f32_16x16x32_bf16 v[88:91], v[156:159], v[180:183], v[88:91]
	v_mfma_f32_16x16x32_bf16 v[76:79], v[140:143], v[188:191], v[76:79]
	v_mfma_f32_16x16x32_bf16 v[72:75], v[156:159], v[188:191], v[72:75]
	v_mfma_f32_16x16x32_bf16 v[124:127], v[150:153], v[168:171], v[124:127]
	v_mfma_f32_16x16x32_bf16 v[120:123], v[160:163], v[168:171], v[120:123]
	v_mfma_f32_16x16x32_bf16 v[108:111], v[150:153], v[176:179], v[108:111]
	v_mfma_f32_16x16x32_bf16 v[104:107], v[160:163], v[176:179], v[104:107]
	v_mfma_f32_16x16x32_bf16 v[92:95], v[150:153], v[184:187], v[92:95]
	v_mfma_f32_16x16x32_bf16 v[88:91], v[160:163], v[184:187], v[88:91]
	v_mfma_f32_16x16x32_bf16 v[76:79], v[150:153], v[192:195], v[76:79]
	v_mfma_f32_16x16x32_bf16 v[72:75], v[160:163], v[192:195], v[72:75]
	s_barrier
	s_add_i32 s48, s52, s34
	v_add_u32_e32 v149, s97, v145
	v_lshl_add_u64 v[212:213], v[212:213], 0, s[16:17]
	s_mov_b32 m0, s48
	ds_read_b128 v[196:199], v149
	ds_read_b128 v[200:203], v149 offset:1024
	ds_read_b128 v[204:207], v149 offset:2048
	ds_read_b128 v[208:211], v149 offset:3072
	global_load_lds_dwordx4 v[212:213], off
	s_add_i32 m0, s48, 0x2000
	v_lshl_add_u64 v[212:213], v[214:215], 0, s[16:17]
	global_load_lds_dwordx4 v[212:213], off
	s_barrier
	s_waitcnt lgkmcnt(0)
	v_mfma_f32_16x16x32_bf16 v[116:119], v[196:199], v[164:167], v[116:119]
	v_mfma_f32_16x16x32_bf16 v[112:115], v[204:207], v[164:167], v[112:115]
	v_mfma_f32_16x16x32_bf16 v[100:103], v[196:199], v[172:175], v[100:103]
	v_mfma_f32_16x16x32_bf16 v[96:99], v[204:207], v[172:175], v[96:99]
	v_mfma_f32_16x16x32_bf16 v[84:87], v[196:199], v[180:183], v[84:87]
	v_mfma_f32_16x16x32_bf16 v[80:83], v[204:207], v[180:183], v[80:83]
	v_mfma_f32_16x16x32_bf16 v[68:71], v[196:199], v[188:191], v[68:71]
	v_mfma_f32_16x16x32_bf16 v[64:67], v[204:207], v[188:191], v[64:67]
	v_mfma_f32_16x16x32_bf16 v[116:119], v[200:203], v[168:171], v[116:119]
	v_mfma_f32_16x16x32_bf16 v[112:115], v[208:211], v[168:171], v[112:115]
	v_mfma_f32_16x16x32_bf16 v[100:103], v[200:203], v[176:179], v[100:103]
	v_mfma_f32_16x16x32_bf16 v[96:99], v[208:211], v[176:179], v[96:99]
	v_mfma_f32_16x16x32_bf16 v[84:87], v[200:203], v[184:187], v[84:87]
	v_mfma_f32_16x16x32_bf16 v[80:83], v[208:211], v[184:187], v[80:83]
	v_mfma_f32_16x16x32_bf16 v[68:71], v[200:203], v[192:195], v[68:71]
	v_mfma_f32_16x16x32_bf16 v[64:67], v[208:211], v[192:195], v[64:67]
	s_mov_b32 m0, s60
	v_lshl_add_u64 v[212:213], v[216:217], 0, s[16:17]
	s_barrier
	ds_read_b128 v[164:167], v147 offset:49152
	ds_read_b128 v[168:171], v147 offset:50176
	ds_read_b128 v[172:175], v147 offset:51200
	ds_read_b128 v[176:179], v147 offset:52224
	ds_read_b128 v[180:183], v147 offset:53248
	ds_read_b128 v[184:187], v147 offset:54272
	ds_read_b128 v[188:191], v147 offset:55296
	ds_read_b128 v[192:195], v147 offset:56320
	global_load_lds_dwordx4 v[212:213], off
	s_mov_b32 m0, s61
	v_lshl_add_u64 v[212:213], v[218:219], 0, s[16:17]
	global_load_lds_dwordx4 v[212:213], off
	s_barrier
	s_waitcnt lgkmcnt(0)
	v_mfma_f32_16x16x32_bf16 v[60:63], v[140:143], v[164:167], v[60:63]
	v_mfma_f32_16x16x32_bf16 v[56:59], v[156:159], v[164:167], v[56:59]
	v_mfma_f32_16x16x32_bf16 v[44:47], v[140:143], v[172:175], v[44:47]
	v_mfma_f32_16x16x32_bf16 v[40:43], v[156:159], v[172:175], v[40:43]
	v_mfma_f32_16x16x32_bf16 v[28:31], v[140:143], v[180:183], v[28:31]
	v_mfma_f32_16x16x32_bf16 v[24:27], v[156:159], v[180:183], v[24:27]
	v_mfma_f32_16x16x32_bf16 v[12:15], v[140:143], v[188:191], v[12:15]
	v_mfma_f32_16x16x32_bf16 v[8:11], v[156:159], v[188:191], v[8:11]
	v_mfma_f32_16x16x32_bf16 v[60:63], v[150:153], v[168:171], v[60:63]
	v_mfma_f32_16x16x32_bf16 v[56:59], v[160:163], v[168:171], v[56:59]
	v_mfma_f32_16x16x32_bf16 v[44:47], v[150:153], v[176:179], v[44:47]
	v_mfma_f32_16x16x32_bf16 v[40:43], v[160:163], v[176:179], v[40:43]
	v_mfma_f32_16x16x32_bf16 v[28:31], v[150:153], v[184:187], v[28:31]
	v_mfma_f32_16x16x32_bf16 v[24:27], v[160:163], v[184:187], v[24:27]
	v_mfma_f32_16x16x32_bf16 v[12:15], v[150:153], v[192:195], v[12:15]
	v_mfma_f32_16x16x32_bf16 v[8:11], v[160:163], v[192:195], v[8:11]
	s_barrier
	s_add_u32 s48, s50, 0x100080
	s_addc_u32 s49, s51, 0
	s_add_i32 s50, s97, s34
	s_mov_b32 m0, s50
	v_lshl_add_u64 v[140:141], s[48:49], 0, v[130:131]
	global_load_lds_dwordx4 v[140:141], off
	s_add_i32 m0, s50, 0x2000
	v_lshl_add_u64 v[140:141], s[48:49], 0, v[134:135]
	global_load_lds_dwordx4 v[140:141], off
	s_waitcnt vmcnt(6)
	s_barrier
	v_mfma_f32_16x16x32_bf16 v[52:55], v[196:199], v[164:167], v[52:55]
	v_mfma_f32_16x16x32_bf16 v[48:51], v[204:207], v[164:167], v[48:51]
	v_mfma_f32_16x16x32_bf16 v[36:39], v[196:199], v[172:175], v[36:39]
	v_mfma_f32_16x16x32_bf16 v[32:35], v[204:207], v[172:175], v[32:35]
	v_mfma_f32_16x16x32_bf16 v[20:23], v[196:199], v[180:183], v[20:23]
	v_mfma_f32_16x16x32_bf16 v[16:19], v[204:207], v[180:183], v[16:19]
	v_mfma_f32_16x16x32_bf16 v[4:7], v[196:199], v[188:191], v[4:7]
	v_mfma_f32_16x16x32_bf16 v[0:3], v[204:207], v[188:191], v[0:3]
	v_mfma_f32_16x16x32_bf16 v[52:55], v[200:203], v[168:171], v[52:55]
	v_mfma_f32_16x16x32_bf16 v[48:51], v[208:211], v[168:171], v[48:51]
	v_mfma_f32_16x16x32_bf16 v[36:39], v[200:203], v[176:179], v[36:39]
	v_mfma_f32_16x16x32_bf16 v[32:35], v[208:211], v[176:179], v[32:35]
	v_mfma_f32_16x16x32_bf16 v[20:23], v[200:203], v[184:187], v[20:23]
	v_mfma_f32_16x16x32_bf16 v[16:19], v[208:211], v[184:187], v[16:19]
	v_mfma_f32_16x16x32_bf16 v[4:7], v[200:203], v[192:195], v[4:7]
	v_mfma_f32_16x16x32_bf16 v[0:3], v[208:211], v[192:195], v[0:3]
	s_cmp_gt_u32 s37, 61
	s_mov_b32 s37, s66
	s_barrier
	s_cbranch_scc1 .LBB0_728
